# baseline (speedup 1.0000x reference)
; #define PG8_STAGE(bufoff, gbase, voff) do { _Pragma("unroll") for (int _i = 0; _i < 2; ++_i) \
;         __builtin_amdgcn_global_load_lds((const unsigned*)((const char*)(gbase) + (voff)[_i]), (PG8_LAS unsigned*)(lds + (bufoff) + ldsw + _i * 8192), 16, 0, 0); } while (0)
; #define PG8_LDA(dst, b, h) do { _Pragma("unroll") for (int m = 0; m < 4; ++m) _Pragma("unroll") for (int k = 0; k < 2; ++k) dst[m][k] = *(const PG8_LAS bf16x8*)(lds + PG8_SA(b, h) + aoff + m * 2048 + k * 1024); } while (0)
; #define PG8_LDB(dst, b, h) do { _Pragma("unroll") for (int n = 0; n < 2; ++n) _Pragma("unroll") for (int k = 0; k < 2; ++k) dst[n][k] = *(const PG8_LAS bf16x8*)(lds + PG8_SB(b, h) + boff + n * 2048 + k * 1024); } while (0)
; #define PG8_MMA(ai, bj, At, Bt) do { __builtin_amdgcn_s_setprio(1); _Pragma("unroll") for (int m = 0; m < 4; ++m) _Pragma("unroll") for (int n = 0; n < 2; ++n) _Pragma("unroll") for (int k = 0; k < 2; ++k) \
;         acc[ai][bj][m][n] = __builtin_amdgcn_mfma_f32_16x16x32_bf16(Bt[n][k], At[m][k], acc[ai][bj][m][n], 0, 0, 0); __builtin_amdgcn_s_setprio(0); } while (0)
; #define PG8_WAIT_V(n) asm volatile("s_waitcnt vmcnt(" #n ")" ::: "memory")
; #define PG8_WAIT_L(n) asm volatile("s_waitcnt lgkmcnt(" #n ")" ::: "memory")
; template <class Epi, class Sched, bool ALIGN_EPI = false, bool SP2 = false>
; __device__ __forceinline__ void gemm_phase(PG8_LAS unsigned char* lds, const Gemm g, const Sched& S, const Epi& E, int wave_s) {
;     ...
;     for (;;) {
;         const bool has_next = S.next(ui + 1, nxt);
;         const char* nA = has_next ? (const char*)g.A + (size_t)nxt.pm * tstep : cA; const char* nB = has_next ? (const char*)g.Bt + (size_t)nxt.pn * tstep : cB;
;         for (int t = 0; t < nt; t += 2) {
;             const bool last = (t == nt - 2);
;             const char* a1 = cA + (size_t)(t + 1) * kstep;
;             const char* a2 = last ? nA : cA + (size_t)(t + 2) * kstep; const char* b2 = last ? nB : cB + (size_t)(t + 2) * kstep;
;             const char* a3 = a2 + kstep; const char* b3 = b2 + kstep;
;             if (last && has_next) S.a_ready(nxt);
;             if constexpr (SP2) {
;             PG8_LDB(B0, 0, 0); PG8_LDB(B1, 0, 1); PG8_SCHED; PG8_LDA(At, 0, 0); PG8_STAGE(PG8_SA(1, 1), a1 + hstep, voffA);
;             PG8_WAIT_V(8); PG8_WAIT_L(0); PG8_BAR; PG8_MMA(0, 0, At, B0); PG8_MMA(0, 1, At, B1); PG8_BAR; PG8_SCHED;
.LBB0_52:
	s_add_u32 s5, s62, 0x100
	v_mov_b64_e32 v[6:7], v[2:3]
	v_mov_b64_e32 v[18:19], v[2:3]
	v_mov_b64_e32 v[22:23], v[2:3]
	v_mov_b64_e32 v[34:35], v[2:3]
	v_mov_b64_e32 v[38:39], v[2:3]
	v_mov_b64_e32 v[50:51], v[2:3]
	v_mov_b64_e32 v[54:55], v[2:3]
	v_mov_b64_e32 v[10:11], v[2:3]
	v_mov_b64_e32 v[14:15], v[2:3]
	v_mov_b64_e32 v[26:27], v[2:3]
	v_mov_b64_e32 v[30:31], v[2:3]
	v_mov_b64_e32 v[42:43], v[2:3]
	v_mov_b64_e32 v[46:47], v[2:3]
	v_mov_b64_e32 v[58:59], v[2:3]
	v_mov_b64_e32 v[62:63], v[2:3]
	v_mov_b64_e32 v[66:67], v[2:3]
	v_mov_b64_e32 v[70:71], v[2:3]
	v_mov_b64_e32 v[82:83], v[2:3]
	v_mov_b64_e32 v[86:87], v[2:3]
	v_mov_b64_e32 v[98:99], v[2:3]
	v_mov_b64_e32 v[102:103], v[2:3]
	v_mov_b64_e32 v[114:115], v[2:3]
	v_mov_b64_e32 v[118:119], v[2:3]
	v_mov_b64_e32 v[74:75], v[2:3]
	v_mov_b64_e32 v[78:79], v[2:3]
	v_mov_b64_e32 v[90:91], v[2:3]
	v_mov_b64_e32 v[94:95], v[2:3]
	v_mov_b64_e32 v[106:107], v[2:3]
	v_mov_b64_e32 v[110:111], v[2:3]
	v_mov_b64_e32 v[122:123], v[2:3]
	v_mov_b64_e32 v[126:127], v[2:3]
	s_addc_u32 s22, s63, 0
	s_mov_b32 s23, -2
	v_mov_b64_e32 v[4:5], v[0:1]
	v_mov_b64_e32 v[16:17], v[0:1]
	v_mov_b64_e32 v[20:21], v[0:1]
	v_mov_b64_e32 v[32:33], v[0:1]
	v_mov_b64_e32 v[36:37], v[0:1]
	v_mov_b64_e32 v[48:49], v[0:1]
	v_mov_b64_e32 v[52:53], v[0:1]
	v_mov_b64_e32 v[8:9], v[0:1]
	v_mov_b64_e32 v[12:13], v[0:1]
	v_mov_b64_e32 v[24:25], v[0:1]
	v_mov_b64_e32 v[28:29], v[0:1]
	v_mov_b64_e32 v[40:41], v[0:1]
	v_mov_b64_e32 v[44:45], v[0:1]
	v_mov_b64_e32 v[56:57], v[0:1]
	v_mov_b64_e32 v[60:61], v[0:1]
	v_mov_b64_e32 v[64:65], v[0:1]
	v_mov_b64_e32 v[68:69], v[0:1]
	v_mov_b64_e32 v[80:81], v[0:1]
	v_mov_b64_e32 v[84:85], v[0:1]
	v_mov_b64_e32 v[96:97], v[0:1]
	v_mov_b64_e32 v[100:101], v[0:1]
	v_mov_b64_e32 v[112:113], v[0:1]
	v_mov_b64_e32 v[116:117], v[0:1]
	v_mov_b64_e32 v[72:73], v[0:1]
	v_mov_b64_e32 v[76:77], v[0:1]
	v_mov_b64_e32 v[88:89], v[0:1]
	v_mov_b64_e32 v[92:93], v[0:1]
	v_mov_b64_e32 v[104:105], v[0:1]
	v_mov_b64_e32 v[108:109], v[0:1]
	v_mov_b64_e32 v[120:121], v[0:1]
	v_mov_b64_e32 v[124:125], v[0:1]
	s_add_u32 s62, s60, 0x100
	s_addc_u32 s63, s61, 0
	s_add_i32 s3, 0, 0x10000
	s_cmpk_eq_i32 s23, 0x54
	s_cselect_b32 s67, s45, s63
	s_cselect_b32 s66, s44, s62
	s_cselect_b32 s65, s59, s22
	s_cselect_b32 s64, s58, s5
	s_add_i32 s26, 0, 0x14000
.LBB0_53:
	v_add_u32_e32 v146, s3, v143
	ds_read_b128 v[134:137], v146
	ds_read_b128 v[138:141], v146 offset:1024
	ds_read_b128 v[150:153], v146 offset:2048
	ds_read_b128 v[156:159], v146 offset:3072
	v_add_u32_e32 v146, s26, v143
	ds_read_b128 v[160:163], v146
	ds_read_b128 v[164:167], v146 offset:1024
	ds_read_b128 v[168:171], v146 offset:2048
	ds_read_b128 v[172:175], v146 offset:3072
	v_lshl_add_u64 v[146:147], s[60:61], 0, v[130:131]
	s_add_i32 m0, s25, 0xc000
	ds_read_b128 v[176:179], v145
	ds_read_b128 v[180:183], v145 offset:1024
	ds_read_b128 v[184:187], v145 offset:2048
	ds_read_b128 v[188:191], v145 offset:3072
	ds_read_b128 v[206:209], v145 offset:4096
	ds_read_b128 v[210:213], v145 offset:5120
	ds_read_b128 v[214:217], v145 offset:6144
	ds_read_b128 v[218:221], v145 offset:7168
	global_load_lds_dwordx4 v[146:147], off
	v_lshl_add_u64 v[146:147], s[60:61], 0, v[132:133]
	s_add_i32 m0, s25, 0xe000
	s_nop 0
	global_load_lds_dwordx4 v[146:147], off
	s_waitcnt vmcnt(8)
	s_waitcnt lgkmcnt(0)
	s_barrier
	s_setprio 1
	s_waitcnt lgkmcnt(0)
	v_mfma_f32_16x16x32_bf16 v[124:127], v[134:137], v[176:179], v[124:127]
	v_mfma_f32_16x16x32_bf16 v[120:123], v[150:153], v[176:179], v[120:123]
	v_mfma_f32_16x16x32_bf16 v[108:111], v[134:137], v[184:187], v[108:111]
	v_mfma_f32_16x16x32_bf16 v[104:107], v[150:153], v[184:187], v[104:107]
	v_mfma_f32_16x16x32_bf16 v[92:95], v[134:137], v[206:209], v[92:95]
	v_mfma_f32_16x16x32_bf16 v[88:91], v[150:153], v[206:209], v[88:91]
	v_mfma_f32_16x16x32_bf16 v[76:79], v[134:137], v[214:217], v[76:79]
	v_mfma_f32_16x16x32_bf16 v[72:75], v[150:153], v[214:217], v[72:75]
	v_mfma_f32_16x16x32_bf16 v[124:127], v[138:141], v[180:183], v[124:127]
	v_mfma_f32_16x16x32_bf16 v[120:123], v[156:159], v[180:183], v[120:123]
	v_mfma_f32_16x16x32_bf16 v[108:111], v[138:141], v[188:191], v[108:111]
	v_mfma_f32_16x16x32_bf16 v[104:107], v[156:159], v[188:191], v[104:107]
	v_mfma_f32_16x16x32_bf16 v[92:95], v[138:141], v[210:213], v[92:95]
	v_mfma_f32_16x16x32_bf16 v[88:91], v[156:159], v[210:213], v[88:91]
	v_mfma_f32_16x16x32_bf16 v[76:79], v[138:141], v[218:221], v[76:79]
	v_mfma_f32_16x16x32_bf16 v[72:75], v[156:159], v[218:221], v[72:75]
	s_setprio 0
	s_setprio 1
	v_mfma_f32_16x16x32_bf16 v[116:119], v[160:163], v[176:179], v[116:119]
	v_mfma_f32_16x16x32_bf16 v[112:115], v[168:171], v[176:179], v[112:115]
	v_mfma_f32_16x16x32_bf16 v[100:103], v[160:163], v[184:187], v[100:103]
	v_mfma_f32_16x16x32_bf16 v[96:99], v[168:171], v[184:187], v[96:99]
	v_mfma_f32_16x16x32_bf16 v[84:87], v[160:163], v[206:209], v[84:87]
	v_mfma_f32_16x16x32_bf16 v[80:83], v[168:171], v[206:209], v[80:83]
	v_mfma_f32_16x16x32_bf16 v[68:71], v[160:163], v[214:217], v[68:71]
	v_mfma_f32_16x16x32_bf16 v[64:67], v[168:171], v[214:217], v[64:67]
	v_mfma_f32_16x16x32_bf16 v[116:119], v[164:167], v[180:183], v[116:119]
	v_mfma_f32_16x16x32_bf16 v[112:115], v[172:175], v[180:183], v[112:115]
	v_mfma_f32_16x16x32_bf16 v[100:103], v[164:167], v[188:191], v[100:103]
	v_mfma_f32_16x16x32_bf16 v[96:99], v[172:175], v[188:191], v[96:99]
	v_mfma_f32_16x16x32_bf16 v[84:87], v[164:167], v[210:213], v[84:87]
	v_mfma_f32_16x16x32_bf16 v[80:83], v[172:175], v[210:213], v[80:83]
	v_mfma_f32_16x16x32_bf16 v[68:71], v[164:167], v[218:221], v[68:71]
	v_mfma_f32_16x16x32_bf16 v[64:67], v[172:175], v[218:221], v[64:67]
	s_setprio 0
	s_barrier
; #define PG8_STAGE(bufoff, gbase, voff) do { _Pragma("unroll") for (int _i = 0; _i < 2; ++_i) \
;         __builtin_amdgcn_global_load_lds((const unsigned*)((const char*)(gbase) + (voff)[_i]), (PG8_LAS unsigned*)(lds + (bufoff) + ldsw + _i * 8192), 16, 0, 0); } while (0)
; #define PG8_LDA(dst, b, h) do { _Pragma("unroll") for (int m = 0; m < 4; ++m) _Pragma("unroll") for (int k = 0; k < 2; ++k) dst[m][k] = *(const PG8_LAS bf16x8*)(lds + PG8_SA(b, h) + aoff + m * 2048 + k * 1024); } while (0)
; #define PG8_LDB(dst, b, h) do { _Pragma("unroll") for (int n = 0; n < 2; ++n) _Pragma("unroll") for (int k = 0; k < 2; ++k) dst[n][k] = *(const PG8_LAS bf16x8*)(lds + PG8_SB(b, h) + boff + n * 2048 + k * 1024); } while (0)
; #define PG8_MMA(ai, bj, At, Bt) do { __builtin_amdgcn_s_setprio(1); _Pragma("unroll") for (int m = 0; m < 4; ++m) _Pragma("unroll") for (int n = 0; n < 2; ++n) _Pragma("unroll") for (int k = 0; k < 2; ++k) \
;         acc[ai][bj][m][n] = __builtin_amdgcn_mfma_f32_16x16x32_bf16(Bt[n][k], At[m][k], acc[ai][bj][m][n], 0, 0, 0); __builtin_amdgcn_s_setprio(0); } while (0)
; #define PG8_WAIT_V(n) asm volatile("s_waitcnt vmcnt(" #n ")" ::: "memory")
; #define PG8_WAIT_L(n) asm volatile("s_waitcnt lgkmcnt(" #n ")" ::: "memory")
; #define PG8_BAR __builtin_amdgcn_s_barrier()
; #define PG8_SCHED __builtin_amdgcn_sched_barrier(0)
; template <class Epi, class Sched, bool ALIGN_EPI = false, bool SP2 = false>
; __device__ __forceinline__ void gemm_phase(PG8_LAS unsigned char* lds, const Gemm g, const Sched& S, const Epi& E, int wave_s) {
;     ...
;             PG8_LDB(B0, 0, 0); PG8_LDB(B1, 0, 1); PG8_SCHED; PG8_LDA(At, 0, 0); PG8_STAGE(PG8_SA(1, 1), a1 + hstep, voffA);
;             PG8_WAIT_V(8); PG8_WAIT_L(0); PG8_BAR; PG8_MMA(0, 0, At, B0); PG8_MMA(0, 1, At, B1); PG8_BAR; PG8_SCHED;
;             PG8_LDA(At, 0, 1); PG8_STAGE(PG8_SB(0, 0), b2, voffB); PG8_STAGE(PG8_SB(0, 1), b2 + hstep, voffB); PG8_STAGE(PG8_SA(0, 0), a2, voffA);
;             PG8_WAIT_V(8); PG8_WAIT_L(0); PG8_BAR; PG8_MMA(1, 0, At, B0); PG8_MMA(1, 1, At, B1); PG8_BAR; PG8_SCHED;
;             PG8_LDB(B0, 1, 0); PG8_LDB(B1, 1, 1); PG8_SCHED; PG8_LDA(At, 1, 0); PG8_STAGE(PG8_SA(0, 1), a2 + hstep, voffA);
;             PG8_WAIT_V(8); PG8_WAIT_L(0); PG8_BAR; PG8_MMA(0, 0, At, B0); PG8_MMA(0, 1, At, B1); PG8_BAR; PG8_SCHED;
	s_add_i32 s3, s3, s9
	v_lshl_add_u64 v[146:147], s[64:65], 0, v[148:149]
	s_mov_b32 m0, s3
	ds_read_b128 v[176:179], v145 offset:16384
	ds_read_b128 v[180:183], v145 offset:17408
	ds_read_b128 v[184:187], v145 offset:18432
	ds_read_b128 v[188:191], v145 offset:19456
	ds_read_b128 v[206:209], v145 offset:20480
	ds_read_b128 v[210:213], v145 offset:21504
	ds_read_b128 v[214:217], v145 offset:22528
	ds_read_b128 v[218:221], v145 offset:23552
	global_load_lds_dwordx4 v[146:147], off
	s_add_i32 m0, s3, 0x2000
	s_add_u32 s28, s64, 0x160000
	v_lshl_add_u64 v[222:223], s[64:65], 0, v[128:129]
	s_addc_u32 s29, s65, 0
	s_add_i32 s3, s26, s9
	global_load_lds_dwordx4 v[222:223], off
	v_lshl_add_u64 v[224:225], s[28:29], 0, v[148:149]
	s_mov_b32 m0, s3
	v_lshl_add_u64 v[226:227], s[66:67], 0, v[128:129]
	global_load_lds_dwordx4 v[224:225], off
	v_lshl_add_u64 v[224:225], s[28:29], 0, v[128:129]
	s_add_i32 m0, s3, 0x2000
	s_nop 0
	global_load_lds_dwordx4 v[224:225], off
	v_lshl_add_u64 v[224:225], s[66:67], 0, v[148:149]
	s_mov_b32 m0, s25
	s_nop 0
	global_load_lds_dwordx4 v[224:225], off
	s_mov_b32 m0, s73
	s_nop 0
	global_load_lds_dwordx4 v[226:227], off
	s_waitcnt vmcnt(8)
	s_waitcnt lgkmcnt(0)
	s_barrier
	s_setprio 1
	s_waitcnt lgkmcnt(0)
	v_mfma_f32_16x16x32_bf16 v[60:63], v[134:137], v[176:179], v[60:63]
	v_mfma_f32_16x16x32_bf16 v[56:59], v[150:153], v[176:179], v[56:59]
	v_mfma_f32_16x16x32_bf16 v[44:47], v[134:137], v[184:187], v[44:47]
	v_mfma_f32_16x16x32_bf16 v[40:43], v[150:153], v[184:187], v[40:43]
	v_mfma_f32_16x16x32_bf16 v[28:31], v[134:137], v[206:209], v[28:31]
	v_mfma_f32_16x16x32_bf16 v[24:27], v[150:153], v[206:209], v[24:27]
	v_mfma_f32_16x16x32_bf16 v[12:15], v[134:137], v[214:217], v[12:15]
	v_mfma_f32_16x16x32_bf16 v[8:11], v[150:153], v[214:217], v[8:11]
	v_mfma_f32_16x16x32_bf16 v[60:63], v[138:141], v[180:183], v[60:63]
	v_mfma_f32_16x16x32_bf16 v[56:59], v[156:159], v[180:183], v[56:59]
	v_mfma_f32_16x16x32_bf16 v[44:47], v[138:141], v[188:191], v[44:47]
	v_mfma_f32_16x16x32_bf16 v[40:43], v[156:159], v[188:191], v[40:43]
	v_mfma_f32_16x16x32_bf16 v[28:31], v[138:141], v[210:213], v[28:31]
	v_mfma_f32_16x16x32_bf16 v[24:27], v[156:159], v[210:213], v[24:27]
	v_mfma_f32_16x16x32_bf16 v[12:15], v[138:141], v[218:221], v[12:15]
	v_mfma_f32_16x16x32_bf16 v[8:11], v[156:159], v[218:221], v[8:11]
	s_setprio 0
	s_setprio 1
	v_mfma_f32_16x16x32_bf16 v[52:55], v[160:163], v[176:179], v[52:55]
	v_mfma_f32_16x16x32_bf16 v[48:51], v[168:171], v[176:179], v[48:51]
	v_mfma_f32_16x16x32_bf16 v[36:39], v[160:163], v[184:187], v[36:39]
	v_mfma_f32_16x16x32_bf16 v[32:35], v[168:171], v[184:187], v[32:35]
	v_mfma_f32_16x16x32_bf16 v[20:23], v[160:163], v[206:209], v[20:23]
	v_mfma_f32_16x16x32_bf16 v[16:19], v[168:171], v[206:209], v[16:19]
	v_mfma_f32_16x16x32_bf16 v[4:7], v[160:163], v[214:217], v[4:7]
	v_mfma_f32_16x16x32_bf16 v[0:3], v[168:171], v[214:217], v[0:3]
	v_mfma_f32_16x16x32_bf16 v[52:55], v[164:167], v[180:183], v[52:55]
	v_mfma_f32_16x16x32_bf16 v[48:51], v[172:175], v[180:183], v[48:51]
	v_mfma_f32_16x16x32_bf16 v[36:39], v[164:167], v[188:191], v[36:39]
	v_mfma_f32_16x16x32_bf16 v[32:35], v[172:175], v[188:191], v[32:35]
	v_mfma_f32_16x16x32_bf16 v[20:23], v[164:167], v[210:213], v[20:23]
	v_mfma_f32_16x16x32_bf16 v[16:19], v[172:175], v[210:213], v[16:19]
	v_mfma_f32_16x16x32_bf16 v[4:7], v[164:167], v[218:221], v[4:7]
	v_mfma_f32_16x16x32_bf16 v[0:3], v[172:175], v[218:221], v[0:3]
	s_setprio 0
	s_barrier
	s_add_i32 s3, 0, 0x18000
	s_add_i32 s26, 0, 0x1c000
	v_add_u32_e32 v156, s3, v143
	v_add_u32_e32 v172, s26, v143
	ds_read_b128 v[134:137], v156
	ds_read_b128 v[138:141], v156 offset:1024
	ds_read_b128 v[150:153], v156 offset:2048
	ds_read_b128 v[156:159], v156 offset:3072
	ds_read_b128 v[160:163], v172
	ds_read_b128 v[164:167], v172 offset:1024
	ds_read_b128 v[168:171], v172 offset:2048
	ds_read_b128 v[172:175], v172 offset:3072
	s_add_u32 s28, s66, 0x160000
	s_addc_u32 s29, s67, 0
	s_mov_b32 m0, s74
	v_lshl_add_u64 v[228:229], s[28:29], 0, v[148:149]
	ds_read_b128 v[176:179], v145 offset:32768
	ds_read_b128 v[180:183], v145 offset:33792
	ds_read_b128 v[184:187], v145 offset:34816
	ds_read_b128 v[188:191], v145 offset:35840
	ds_read_b128 v[206:209], v145 offset:36864
	ds_read_b128 v[210:213], v145 offset:37888
	ds_read_b128 v[214:217], v145 offset:38912
	ds_read_b128 v[218:221], v145 offset:39936
	global_load_lds_dwordx4 v[228:229], off
	v_lshl_add_u64 v[228:229], s[28:29], 0, v[128:129]
	s_mov_b32 m0, s75
	s_nop 0
	global_load_lds_dwordx4 v[228:229], off
	s_waitcnt vmcnt(8)
	s_waitcnt lgkmcnt(0)
	s_barrier
; #define PG8_STAGE(bufoff, gbase, voff) do { _Pragma("unroll") for (int _i = 0; _i < 2; ++_i) \
;         __builtin_amdgcn_global_load_lds((const unsigned*)((const char*)(gbase) + (voff)[_i]), (PG8_LAS unsigned*)(lds + (bufoff) + ldsw + _i * 8192), 16, 0, 0); } while (0)
; #define PG8_LDA(dst, b, h) do { _Pragma("unroll") for (int m = 0; m < 4; ++m) _Pragma("unroll") for (int k = 0; k < 2; ++k) dst[m][k] = *(const PG8_LAS bf16x8*)(lds + PG8_SA(b, h) + aoff + m * 2048 + k * 1024); } while (0)
; #define PG8_LDB(dst, b, h) do { _Pragma("unroll") for (int n = 0; n < 2; ++n) _Pragma("unroll") for (int k = 0; k < 2; ++k) dst[n][k] = *(const PG8_LAS bf16x8*)(lds + PG8_SB(b, h) + boff + n * 2048 + k * 1024); } while (0)
; #define PG8_MMA(ai, bj, At, Bt) do { __builtin_amdgcn_s_setprio(1); _Pragma("unroll") for (int m = 0; m < 4; ++m) _Pragma("unroll") for (int n = 0; n < 2; ++n) _Pragma("unroll") for (int k = 0; k < 2; ++k) \
;         acc[ai][bj][m][n] = __builtin_amdgcn_mfma_f32_16x16x32_bf16(Bt[n][k], At[m][k], acc[ai][bj][m][n], 0, 0, 0); __builtin_amdgcn_s_setprio(0); } while (0)
; #define PG8_WAIT_V(n) asm volatile("s_waitcnt vmcnt(" #n ")" ::: "memory")
; #define PG8_WAIT_L(n) asm volatile("s_waitcnt lgkmcnt(" #n ")" ::: "memory")
; #define PG8_BAR __builtin_amdgcn_s_barrier()
; #define PG8_SCHED __builtin_amdgcn_sched_barrier(0)
; template <class Epi, class Sched, bool ALIGN_EPI = false, bool SP2 = false>
; __device__ __forceinline__ void gemm_phase(PG8_LAS unsigned char* lds, const Gemm g, const Sched& S, const Epi& E, int wave_s) {
;     ...
;             PG8_LDB(B0, 1, 0); PG8_LDB(B1, 1, 1); PG8_SCHED; PG8_LDA(At, 1, 0); PG8_STAGE(PG8_SA(0, 1), a2 + hstep, voffA);
;             PG8_WAIT_V(8); PG8_WAIT_L(0); PG8_BAR; PG8_MMA(0, 0, At, B0); PG8_MMA(0, 1, At, B1); PG8_BAR; PG8_SCHED;
;             PG8_LDA(At, 1, 1); PG8_STAGE(PG8_SB(1, 0), b3, voffB); PG8_STAGE(PG8_SB(1, 1), b3 + hstep, voffB); PG8_STAGE(PG8_SA(1, 0), a3, voffA);
;             PG8_WAIT_V(8); PG8_WAIT_L(0); PG8_BAR; PG8_MMA(1, 0, At, B0); PG8_MMA(1, 1, At, B1); PG8_BAR; PG8_SCHED;
	s_setprio 1
	s_waitcnt lgkmcnt(0)
	v_mfma_f32_16x16x32_bf16 v[124:127], v[134:137], v[176:179], v[124:127]
	v_mfma_f32_16x16x32_bf16 v[120:123], v[150:153], v[176:179], v[120:123]
	v_mfma_f32_16x16x32_bf16 v[108:111], v[134:137], v[184:187], v[108:111]
	v_mfma_f32_16x16x32_bf16 v[104:107], v[150:153], v[184:187], v[104:107]
	v_mfma_f32_16x16x32_bf16 v[92:95], v[134:137], v[206:209], v[92:95]
	v_mfma_f32_16x16x32_bf16 v[88:91], v[150:153], v[206:209], v[88:91]
	v_mfma_f32_16x16x32_bf16 v[76:79], v[134:137], v[214:217], v[76:79]
	v_mfma_f32_16x16x32_bf16 v[72:75], v[150:153], v[214:217], v[72:75]
	v_mfma_f32_16x16x32_bf16 v[124:127], v[138:141], v[180:183], v[124:127]
	v_mfma_f32_16x16x32_bf16 v[120:123], v[156:159], v[180:183], v[120:123]
	v_mfma_f32_16x16x32_bf16 v[108:111], v[138:141], v[188:191], v[108:111]
	v_mfma_f32_16x16x32_bf16 v[104:107], v[156:159], v[188:191], v[104:107]
	v_mfma_f32_16x16x32_bf16 v[92:95], v[138:141], v[210:213], v[92:95]
	v_mfma_f32_16x16x32_bf16 v[88:91], v[156:159], v[210:213], v[88:91]
	v_mfma_f32_16x16x32_bf16 v[76:79], v[138:141], v[218:221], v[76:79]
	v_mfma_f32_16x16x32_bf16 v[72:75], v[156:159], v[218:221], v[72:75]
	s_setprio 0
	s_setprio 1
	v_mfma_f32_16x16x32_bf16 v[116:119], v[160:163], v[176:179], v[116:119]
	v_mfma_f32_16x16x32_bf16 v[112:115], v[168:171], v[176:179], v[112:115]
	v_mfma_f32_16x16x32_bf16 v[100:103], v[160:163], v[184:187], v[100:103]
	v_mfma_f32_16x16x32_bf16 v[96:99], v[168:171], v[184:187], v[96:99]
	v_mfma_f32_16x16x32_bf16 v[84:87], v[160:163], v[206:209], v[84:87]
	v_mfma_f32_16x16x32_bf16 v[80:83], v[168:171], v[206:209], v[80:83]
	v_mfma_f32_16x16x32_bf16 v[68:71], v[160:163], v[214:217], v[68:71]
	v_mfma_f32_16x16x32_bf16 v[64:67], v[168:171], v[214:217], v[64:67]
	v_mfma_f32_16x16x32_bf16 v[116:119], v[164:167], v[180:183], v[116:119]
	v_mfma_f32_16x16x32_bf16 v[112:115], v[172:175], v[180:183], v[112:115]
	v_mfma_f32_16x16x32_bf16 v[100:103], v[164:167], v[188:191], v[100:103]
	v_mfma_f32_16x16x32_bf16 v[96:99], v[172:175], v[188:191], v[96:99]
	v_mfma_f32_16x16x32_bf16 v[84:87], v[164:167], v[210:213], v[84:87]
	v_mfma_f32_16x16x32_bf16 v[80:83], v[172:175], v[210:213], v[80:83]
	v_mfma_f32_16x16x32_bf16 v[68:71], v[164:167], v[218:221], v[68:71]
	v_mfma_f32_16x16x32_bf16 v[64:67], v[172:175], v[218:221], v[64:67]
	s_setprio 0
	s_barrier
	s_add_i32 s3, s3, s9
	v_lshl_add_u64 v[146:147], v[146:147], 0, s[34:35]
	s_mov_b32 m0, s3
	ds_read_b128 v[176:179], v145 offset:49152
	ds_read_b128 v[180:183], v145 offset:50176
	ds_read_b128 v[184:187], v145 offset:51200
	ds_read_b128 v[188:191], v145 offset:52224
	ds_read_b128 v[206:209], v145 offset:53248
	ds_read_b128 v[210:213], v145 offset:54272
	ds_read_b128 v[214:217], v145 offset:55296
	ds_read_b128 v[218:221], v145 offset:56320
	global_load_lds_dwordx4 v[146:147], off
	s_add_i32 m0, s3, 0x2000
	s_add_u32 s28, s64, 0x160080
	v_lshl_add_u64 v[146:147], v[222:223], 0, s[34:35]
	s_addc_u32 s29, s65, 0
	s_add_i32 s3, s26, s9
	global_load_lds_dwordx4 v[146:147], off
	v_lshl_add_u64 v[146:147], s[28:29], 0, v[148:149]
	s_mov_b32 m0, s3
	s_nop 0
	global_load_lds_dwordx4 v[146:147], off
	v_lshl_add_u64 v[146:147], s[28:29], 0, v[128:129]
	s_add_i32 m0, s3, 0x2000
	s_nop 0
	global_load_lds_dwordx4 v[146:147], off
	v_lshl_add_u64 v[146:147], v[224:225], 0, s[34:35]
	s_mov_b32 m0, s79
	s_nop 0
	global_load_lds_dwordx4 v[146:147], off
	v_lshl_add_u64 v[146:147], v[226:227], 0, s[34:35]
	s_mov_b32 m0, s20
	s_nop 0
	global_load_lds_dwordx4 v[146:147], off
	s_waitcnt vmcnt(8)
	s_waitcnt lgkmcnt(0)
	s_barrier
	s_setprio 1
	s_waitcnt lgkmcnt(0)
	v_mfma_f32_16x16x32_bf16 v[60:63], v[134:137], v[176:179], v[60:63]
	s_add_i32 s23, s23, 2
	v_mfma_f32_16x16x32_bf16 v[56:59], v[150:153], v[176:179], v[56:59]
	s_add_u32 s5, s5, 0x100
	v_mfma_f32_16x16x32_bf16 v[44:47], v[134:137], v[184:187], v[44:47]
	s_addc_u32 s22, s22, 0
	v_mfma_f32_16x16x32_bf16 v[40:43], v[150:153], v[184:187], v[40:43]
	s_mov_b64 s[60:61], s[62:63]
	v_mfma_f32_16x16x32_bf16 v[28:31], v[134:137], v[206:209], v[28:31]
	s_add_u32 s62, s60, 0x100
	v_mfma_f32_16x16x32_bf16 v[24:27], v[150:153], v[206:209], v[24:27]
	s_addc_u32 s63, s61, 0
	v_mfma_f32_16x16x32_bf16 v[12:15], v[134:137], v[214:217], v[12:15]
	s_add_i32 s3, 0, 0x10000
	v_mfma_f32_16x16x32_bf16 v[8:11], v[150:153], v[214:217], v[8:11]
	s_cmpk_eq_i32 s23, 0x54
	v_mfma_f32_16x16x32_bf16 v[60:63], v[138:141], v[180:183], v[60:63]
	s_cselect_b32 s67, s45, s63
	v_mfma_f32_16x16x32_bf16 v[56:59], v[156:159], v[180:183], v[56:59]
	s_cselect_b32 s66, s44, s62
	v_mfma_f32_16x16x32_bf16 v[44:47], v[138:141], v[188:191], v[44:47]
	s_cselect_b32 s65, s59, s22
	v_mfma_f32_16x16x32_bf16 v[40:43], v[156:159], v[188:191], v[40:43]
	s_cselect_b32 s64, s58, s5
	v_mfma_f32_16x16x32_bf16 v[28:31], v[138:141], v[210:213], v[28:31]
	s_add_i32 s26, 0, 0x14000
	v_mfma_f32_16x16x32_bf16 v[24:27], v[156:159], v[210:213], v[24:27]
	v_mfma_f32_16x16x32_bf16 v[12:15], v[138:141], v[218:221], v[12:15]
	v_mfma_f32_16x16x32_bf16 v[8:11], v[156:159], v[218:221], v[8:11]
	s_setprio 0
	s_setprio 1
	v_mfma_f32_16x16x32_bf16 v[52:55], v[160:163], v[176:179], v[52:55]
	v_mfma_f32_16x16x32_bf16 v[48:51], v[168:171], v[176:179], v[48:51]
	v_mfma_f32_16x16x32_bf16 v[36:39], v[160:163], v[184:187], v[36:39]
	v_mfma_f32_16x16x32_bf16 v[32:35], v[168:171], v[184:187], v[32:35]
	v_mfma_f32_16x16x32_bf16 v[20:23], v[160:163], v[206:209], v[20:23]
	v_mfma_f32_16x16x32_bf16 v[16:19], v[168:171], v[206:209], v[16:19]
	v_mfma_f32_16x16x32_bf16 v[4:7], v[160:163], v[214:217], v[4:7]
	v_mfma_f32_16x16x32_bf16 v[0:3], v[168:171], v[214:217], v[0:3]
	v_mfma_f32_16x16x32_bf16 v[52:55], v[164:167], v[180:183], v[52:55]
	v_mfma_f32_16x16x32_bf16 v[48:51], v[172:175], v[180:183], v[48:51]
	v_mfma_f32_16x16x32_bf16 v[36:39], v[164:167], v[188:191], v[36:39]
	v_mfma_f32_16x16x32_bf16 v[32:35], v[172:175], v[188:191], v[32:35]
	v_mfma_f32_16x16x32_bf16 v[20:23], v[164:167], v[210:213], v[20:23]
	v_mfma_f32_16x16x32_bf16 v[16:19], v[172:175], v[210:213], v[16:19]
	v_mfma_f32_16x16x32_bf16 v[4:7], v[164:167], v[218:221], v[4:7]
	v_mfma_f32_16x16x32_bf16 v[0:3], v[172:175], v[218:221], v[0:3]
	s_setprio 0
	s_barrier
	s_cmpk_gt_u32 s23, 0x55
	s_cbranch_scc0 .LBB0_53
	s_and_b64 vcc, exec, s[56:57]
	s_cbranch_vccz .LBB0_56
	s_barrier

; #define PG8_STAGE(bufoff, gbase, voff) do { _Pragma("unroll") for (int _i = 0; _i < 2; ++_i) \
;         __builtin_amdgcn_global_load_lds((const unsigned*)((const char*)(gbase) + (voff)[_i]), (PG8_LAS unsigned*)(lds + (bufoff) + ldsw + _i * 8192), 16, 0, 0); } while (0)
; #define PG8_LDA(dst, b, h) do { _Pragma("unroll") for (int m = 0; m < 4; ++m) _Pragma("unroll") for (int k = 0; k < 2; ++k) dst[m][k] = *(const PG8_LAS bf16x8*)(lds + PG8_SA(b, h) + aoff + m * 2048 + k * 1024); } while (0)
; #define PG8_LDB(dst, b, h) do { _Pragma("unroll") for (int n = 0; n < 2; ++n) _Pragma("unroll") for (int k = 0; k < 2; ++k) dst[n][k] = *(const PG8_LAS bf16x8*)(lds + PG8_SB(b, h) + boff + n * 2048 + k * 1024); } while (0)
; #define PG8_MMA(ai, bj, At, Bt) do { __builtin_amdgcn_s_setprio(1); _Pragma("unroll") for (int m = 0; m < 4; ++m) _Pragma("unroll") for (int n = 0; n < 2; ++n) _Pragma("unroll") for (int k = 0; k < 2; ++k) \
;         acc[ai][bj][m][n] = __builtin_amdgcn_mfma_f32_16x16x32_bf16(Bt[n][k], At[m][k], acc[ai][bj][m][n], 0, 0, 0); __builtin_amdgcn_s_setprio(0); } while (0)
; #define PG8_WAIT_V(n) asm volatile("s_waitcnt vmcnt(" #n ")" ::: "memory")
; #define PG8_WAIT_L(n) asm volatile("s_waitcnt lgkmcnt(" #n ")" ::: "memory")
; template <class Epi, class Sched, bool ALIGN_EPI = false, bool SP2 = false>
; __device__ __forceinline__ void gemm_phase(PG8_LAS unsigned char* lds, const Gemm g, const Sched& S, const Epi& E, int wave_s) {
;     ...
;     for (;;) {
;         const bool has_next = S.next(ui + 1, nxt);
;         const char* nA = has_next ? (const char*)g.A + (size_t)nxt.pm * tstep : cA; const char* nB = has_next ? (const char*)g.Bt + (size_t)nxt.pn * tstep : cB;
;         for (int t = 0; t < nt; t += 2) {
;             const bool last = (t == nt - 2);
;             const char* a1 = cA + (size_t)(t + 1) * kstep;
;             const char* a2 = last ? nA : cA + (size_t)(t + 2) * kstep; const char* b2 = last ? nB : cB + (size_t)(t + 2) * kstep;
;             const char* a3 = a2 + kstep; const char* b3 = b2 + kstep;
;             if (last && has_next) S.a_ready(nxt);
;             if constexpr (SP2) {
;             PG8_LDB(B0, 0, 0); PG8_LDB(B1, 0, 1); PG8_SCHED; PG8_LDA(At, 0, 0); PG8_STAGE(PG8_SA(1, 1), a1 + hstep, voffA);
;             PG8_WAIT_V(8); PG8_WAIT_L(0); PG8_BAR; PG8_MMA(0, 0, At, B0); PG8_MMA(0, 1, At, B1); PG8_BAR; PG8_SCHED;
.LBB0_81:
	s_ashr_i32 s55, s54, 31
	s_lshl_b64 s[22:23], s[54:55], 20
	s_add_u32 s56, s9, s22
	s_addc_u32 s57, s11, s23
	s_and_b64 s[22:23], s[40:41], exec
	s_cselect_b32 s19, s57, s63
	s_cselect_b32 s22, s56, s62
	s_ashr_i32 s53, s52, 31
	s_lshl_b64 s[28:29], s[52:53], 20
	s_add_u32 s58, s20, s28
	s_addc_u32 s59, s21, s29
	s_and_b64 s[28:29], s[40:41], exec
	s_cselect_b32 s5, s59, s65
	s_cselect_b32 s23, s58, s64
	s_add_u32 s62, s62, 0x80080
	s_addc_u32 s63, s63, 0
	s_add_u32 s28, s64, 0x100
	v_mov_b64_e32 v[10:11], v[2:3]
	v_mov_b64_e32 v[18:19], v[2:3]
	v_mov_b64_e32 v[26:27], v[2:3]
	v_mov_b64_e32 v[34:35], v[2:3]
	v_mov_b64_e32 v[42:43], v[2:3]
	v_mov_b64_e32 v[50:51], v[2:3]
	v_mov_b64_e32 v[58:59], v[2:3]
	v_mov_b64_e32 v[6:7], v[2:3]
	v_mov_b64_e32 v[14:15], v[2:3]
	v_mov_b64_e32 v[22:23], v[2:3]
	v_mov_b64_e32 v[30:31], v[2:3]
	v_mov_b64_e32 v[38:39], v[2:3]
	v_mov_b64_e32 v[46:47], v[2:3]
	v_mov_b64_e32 v[54:55], v[2:3]
	v_mov_b64_e32 v[62:63], v[2:3]
	v_mov_b64_e32 v[66:67], v[2:3]
	v_mov_b64_e32 v[74:75], v[2:3]
	v_mov_b64_e32 v[82:83], v[2:3]
	v_mov_b64_e32 v[90:91], v[2:3]
	v_mov_b64_e32 v[98:99], v[2:3]
	v_mov_b64_e32 v[106:107], v[2:3]
	v_mov_b64_e32 v[114:115], v[2:3]
	v_mov_b64_e32 v[122:123], v[2:3]
	v_mov_b64_e32 v[70:71], v[2:3]
	v_mov_b64_e32 v[78:79], v[2:3]
	v_mov_b64_e32 v[86:87], v[2:3]
	v_mov_b64_e32 v[94:95], v[2:3]
	v_mov_b64_e32 v[102:103], v[2:3]
	v_mov_b64_e32 v[110:111], v[2:3]
	v_mov_b64_e32 v[118:119], v[2:3]
	v_mov_b64_e32 v[126:127], v[2:3]
	s_addc_u32 s29, s65, 0
	s_mov_b32 s38, -2
	v_mov_b64_e32 v[8:9], v[0:1]
	v_mov_b64_e32 v[16:17], v[0:1]
	v_mov_b64_e32 v[24:25], v[0:1]
	v_mov_b64_e32 v[32:33], v[0:1]
	v_mov_b64_e32 v[40:41], v[0:1]
	v_mov_b64_e32 v[48:49], v[0:1]
	v_mov_b64_e32 v[56:57], v[0:1]
	v_mov_b64_e32 v[4:5], v[0:1]
	v_mov_b64_e32 v[12:13], v[0:1]
	v_mov_b64_e32 v[20:21], v[0:1]
	v_mov_b64_e32 v[28:29], v[0:1]
	v_mov_b64_e32 v[36:37], v[0:1]
	v_mov_b64_e32 v[44:45], v[0:1]
	v_mov_b64_e32 v[52:53], v[0:1]
	v_mov_b64_e32 v[60:61], v[0:1]
	v_mov_b64_e32 v[64:65], v[0:1]
	v_mov_b64_e32 v[72:73], v[0:1]
	v_mov_b64_e32 v[80:81], v[0:1]
	v_mov_b64_e32 v[88:89], v[0:1]
	v_mov_b64_e32 v[96:97], v[0:1]
	v_mov_b64_e32 v[104:105], v[0:1]
	v_mov_b64_e32 v[112:113], v[0:1]
	v_mov_b64_e32 v[120:121], v[0:1]
	v_mov_b64_e32 v[68:69], v[0:1]
	v_mov_b64_e32 v[76:77], v[0:1]
	v_mov_b64_e32 v[84:85], v[0:1]
	v_mov_b64_e32 v[92:93], v[0:1]
	v_mov_b64_e32 v[100:101], v[0:1]
	v_mov_b64_e32 v[108:109], v[0:1]
	v_mov_b64_e32 v[116:117], v[0:1]
	v_mov_b64_e32 v[124:125], v[0:1]
	s_add_u32 s3, s62, 0xfff80080
	s_addc_u32 s26, s63, -1
	s_add_i32 s36, 0, 0x10000
	s_cmp_eq_u32 s38, 28
	s_cselect_b32 s67, s19, s26
	s_cselect_b32 s66, s22, s3
	s_cselect_b32 s65, s5, s29
	s_cselect_b32 s64, s23, s28
	s_add_i32 s3, 0, 0x14000
.LBB0_82:
	v_add_u32_e32 v146, s36, v139
	ds_read_b128 v[142:145], v146
	ds_read_b128 v[150:153], v146 offset:1024
	ds_read_b128 v[156:159], v146 offset:2048
	ds_read_b128 v[160:163], v146 offset:3072
	v_add_u32_e32 v146, s3, v139
	ds_read_b128 v[164:167], v146
	ds_read_b128 v[168:171], v146 offset:1024
	ds_read_b128 v[172:175], v146 offset:2048
	ds_read_b128 v[176:179], v146 offset:3072
	v_lshl_add_u64 v[146:147], s[62:63], 0, v[134:135]
	s_add_i32 m0, s61, 0xc000
	ds_read_b128 v[180:183], v141
	ds_read_b128 v[184:187], v141 offset:1024
	ds_read_b128 v[188:191], v141 offset:2048
	ds_read_b128 v[206:209], v141 offset:3072
	ds_read_b128 v[210:213], v141 offset:4096
	ds_read_b128 v[214:217], v141 offset:5120
	ds_read_b128 v[218:221], v141 offset:6144
	ds_read_b128 v[222:225], v141 offset:7168
	global_load_lds_dwordx4 v[146:147], off
	v_lshl_add_u64 v[146:147], s[62:63], 0, v[136:137]
	s_add_i32 m0, s61, 0xe000
	s_nop 0
	global_load_lds_dwordx4 v[146:147], off
	s_waitcnt vmcnt(8)
	s_waitcnt lgkmcnt(0)
	s_barrier
	s_setprio 1
	s_waitcnt lgkmcnt(0)
	v_mfma_f32_16x16x32_bf16 v[124:127], v[142:145], v[180:183], v[124:127]
	v_mfma_f32_16x16x32_bf16 v[116:119], v[156:159], v[180:183], v[116:119]
	v_mfma_f32_16x16x32_bf16 v[108:111], v[142:145], v[188:191], v[108:111]
	v_mfma_f32_16x16x32_bf16 v[100:103], v[156:159], v[188:191], v[100:103]
	v_mfma_f32_16x16x32_bf16 v[92:95], v[142:145], v[210:213], v[92:95]
	v_mfma_f32_16x16x32_bf16 v[84:87], v[156:159], v[210:213], v[84:87]
	v_mfma_f32_16x16x32_bf16 v[76:79], v[142:145], v[218:221], v[76:79]
	v_mfma_f32_16x16x32_bf16 v[68:71], v[156:159], v[218:221], v[68:71]
	v_mfma_f32_16x16x32_bf16 v[124:127], v[150:153], v[184:187], v[124:127]
	v_mfma_f32_16x16x32_bf16 v[116:119], v[160:163], v[184:187], v[116:119]
	v_mfma_f32_16x16x32_bf16 v[108:111], v[150:153], v[206:209], v[108:111]
	v_mfma_f32_16x16x32_bf16 v[100:103], v[160:163], v[206:209], v[100:103]
	v_mfma_f32_16x16x32_bf16 v[92:95], v[150:153], v[214:217], v[92:95]
	v_mfma_f32_16x16x32_bf16 v[84:87], v[160:163], v[214:217], v[84:87]
	v_mfma_f32_16x16x32_bf16 v[76:79], v[150:153], v[222:225], v[76:79]
	v_mfma_f32_16x16x32_bf16 v[68:71], v[160:163], v[222:225], v[68:71]
	s_setprio 0
	s_setprio 1
	v_mfma_f32_16x16x32_bf16 v[120:123], v[164:167], v[180:183], v[120:123]
	v_mfma_f32_16x16x32_bf16 v[112:115], v[172:175], v[180:183], v[112:115]
	v_mfma_f32_16x16x32_bf16 v[104:107], v[164:167], v[188:191], v[104:107]
	v_mfma_f32_16x16x32_bf16 v[96:99], v[172:175], v[188:191], v[96:99]
	v_mfma_f32_16x16x32_bf16 v[88:91], v[164:167], v[210:213], v[88:91]
	v_mfma_f32_16x16x32_bf16 v[80:83], v[172:175], v[210:213], v[80:83]
	v_mfma_f32_16x16x32_bf16 v[72:75], v[164:167], v[218:221], v[72:75]
	v_mfma_f32_16x16x32_bf16 v[64:67], v[172:175], v[218:221], v[64:67]
	v_mfma_f32_16x16x32_bf16 v[120:123], v[168:171], v[184:187], v[120:123]
	v_mfma_f32_16x16x32_bf16 v[112:115], v[176:179], v[184:187], v[112:115]
	v_mfma_f32_16x16x32_bf16 v[104:107], v[168:171], v[206:209], v[104:107]
	v_mfma_f32_16x16x32_bf16 v[96:99], v[176:179], v[206:209], v[96:99]
	v_mfma_f32_16x16x32_bf16 v[88:91], v[168:171], v[214:217], v[88:91]
	v_mfma_f32_16x16x32_bf16 v[80:83], v[176:179], v[214:217], v[80:83]
	v_mfma_f32_16x16x32_bf16 v[72:75], v[168:171], v[222:225], v[72:75]
	v_mfma_f32_16x16x32_bf16 v[64:67], v[176:179], v[222:225], v[64:67]
	s_setprio 0
	s_barrier
; #define PG8_STAGE(bufoff, gbase, voff) do { _Pragma("unroll") for (int _i = 0; _i < 2; ++_i) \
;         __builtin_amdgcn_global_load_lds((const unsigned*)((const char*)(gbase) + (voff)[_i]), (PG8_LAS unsigned*)(lds + (bufoff) + ldsw + _i * 8192), 16, 0, 0); } while (0)
; #define PG8_LDA(dst, b, h) do { _Pragma("unroll") for (int m = 0; m < 4; ++m) _Pragma("unroll") for (int k = 0; k < 2; ++k) dst[m][k] = *(const PG8_LAS bf16x8*)(lds + PG8_SA(b, h) + aoff + m * 2048 + k * 1024); } while (0)
; #define PG8_LDB(dst, b, h) do { _Pragma("unroll") for (int n = 0; n < 2; ++n) _Pragma("unroll") for (int k = 0; k < 2; ++k) dst[n][k] = *(const PG8_LAS bf16x8*)(lds + PG8_SB(b, h) + boff + n * 2048 + k * 1024); } while (0)
; #define PG8_MMA(ai, bj, At, Bt) do { __builtin_amdgcn_s_setprio(1); _Pragma("unroll") for (int m = 0; m < 4; ++m) _Pragma("unroll") for (int n = 0; n < 2; ++n) _Pragma("unroll") for (int k = 0; k < 2; ++k) \
;         acc[ai][bj][m][n] = __builtin_amdgcn_mfma_f32_16x16x32_bf16(Bt[n][k], At[m][k], acc[ai][bj][m][n], 0, 0, 0); __builtin_amdgcn_s_setprio(0); } while (0)
; #define PG8_WAIT_V(n) asm volatile("s_waitcnt vmcnt(" #n ")" ::: "memory")
; #define PG8_WAIT_L(n) asm volatile("s_waitcnt lgkmcnt(" #n ")" ::: "memory")
; #define PG8_BAR __builtin_amdgcn_s_barrier()
; #define PG8_SCHED __builtin_amdgcn_sched_barrier(0)
; template <class Epi, class Sched, bool ALIGN_EPI = false, bool SP2 = false>
; __device__ __forceinline__ void gemm_phase(PG8_LAS unsigned char* lds, const Gemm g, const Sched& S, const Epi& E, int wave_s) {
;     ...
;             PG8_LDA(At, 0, 1); PG8_STAGE(PG8_SB(0, 0), b2, voffB); PG8_STAGE(PG8_SB(0, 1), b2 + hstep, voffB); PG8_STAGE(PG8_SA(0, 0), a2, voffA);
;             PG8_WAIT_V(8); PG8_WAIT_L(0); PG8_BAR; PG8_MMA(1, 0, At, B0); PG8_MMA(1, 1, At, B1); PG8_BAR; PG8_SCHED;
;             PG8_LDB(B0, 1, 0); PG8_LDB(B1, 1, 1); PG8_SCHED; PG8_LDA(At, 1, 0); PG8_STAGE(PG8_SA(0, 1), a2 + hstep, voffA);
;             PG8_WAIT_V(8); PG8_WAIT_L(0); PG8_BAR; PG8_MMA(0, 0, At, B0); PG8_MMA(0, 1, At, B1); PG8_BAR; PG8_SCHED;
	s_add_i32 s26, s36, s25
	v_lshl_add_u64 v[146:147], s[64:65], 0, v[148:149]
	s_mov_b32 m0, s26
	ds_read_b128 v[180:183], v141 offset:16384
	ds_read_b128 v[184:187], v141 offset:17408
	ds_read_b128 v[188:191], v141 offset:18432
	ds_read_b128 v[206:209], v141 offset:19456
	ds_read_b128 v[210:213], v141 offset:20480
	ds_read_b128 v[214:217], v141 offset:21504
	ds_read_b128 v[218:221], v141 offset:22528
	ds_read_b128 v[222:225], v141 offset:23552
	global_load_lds_dwordx4 v[146:147], off
	s_add_i32 m0, s26, 0x2000
	s_add_u32 s36, s64, 0x80000
	v_lshl_add_u64 v[226:227], s[64:65], 0, v[128:129]
	s_addc_u32 s37, s65, 0
	s_add_i32 s3, s3, s25
	global_load_lds_dwordx4 v[226:227], off
	v_lshl_add_u64 v[228:229], s[36:37], 0, v[148:149]
	s_mov_b32 m0, s3
	v_lshl_add_u64 v[230:231], s[66:67], 0, v[130:131]
	global_load_lds_dwordx4 v[228:229], off
	v_lshl_add_u64 v[228:229], s[36:37], 0, v[128:129]
	s_add_i32 m0, s3, 0x2000
	s_nop 0
	global_load_lds_dwordx4 v[228:229], off
	v_lshl_add_u64 v[228:229], s[66:67], 0, v[132:133]
	s_mov_b32 m0, s61
	s_nop 0
	global_load_lds_dwordx4 v[228:229], off
	s_mov_b32 m0, s73
	s_nop 0
	global_load_lds_dwordx4 v[230:231], off
	s_waitcnt vmcnt(8)
	s_waitcnt lgkmcnt(0)
	s_barrier
	s_setprio 1
	s_waitcnt lgkmcnt(0)
	v_mfma_f32_16x16x32_bf16 v[60:63], v[142:145], v[180:183], v[60:63]
	v_mfma_f32_16x16x32_bf16 v[52:55], v[156:159], v[180:183], v[52:55]
	v_mfma_f32_16x16x32_bf16 v[44:47], v[142:145], v[188:191], v[44:47]
	v_mfma_f32_16x16x32_bf16 v[36:39], v[156:159], v[188:191], v[36:39]
	v_mfma_f32_16x16x32_bf16 v[28:31], v[142:145], v[210:213], v[28:31]
	v_mfma_f32_16x16x32_bf16 v[20:23], v[156:159], v[210:213], v[20:23]
	v_mfma_f32_16x16x32_bf16 v[12:15], v[142:145], v[218:221], v[12:15]
	v_mfma_f32_16x16x32_bf16 v[4:7], v[156:159], v[218:221], v[4:7]
	v_mfma_f32_16x16x32_bf16 v[60:63], v[150:153], v[184:187], v[60:63]
	v_mfma_f32_16x16x32_bf16 v[52:55], v[160:163], v[184:187], v[52:55]
	v_mfma_f32_16x16x32_bf16 v[44:47], v[150:153], v[206:209], v[44:47]
	v_mfma_f32_16x16x32_bf16 v[36:39], v[160:163], v[206:209], v[36:39]
	v_mfma_f32_16x16x32_bf16 v[28:31], v[150:153], v[214:217], v[28:31]
	v_mfma_f32_16x16x32_bf16 v[20:23], v[160:163], v[214:217], v[20:23]
	v_mfma_f32_16x16x32_bf16 v[12:15], v[150:153], v[222:225], v[12:15]
	v_mfma_f32_16x16x32_bf16 v[4:7], v[160:163], v[222:225], v[4:7]
	s_setprio 0
	s_setprio 1
	v_mfma_f32_16x16x32_bf16 v[56:59], v[164:167], v[180:183], v[56:59]
	v_mfma_f32_16x16x32_bf16 v[48:51], v[172:175], v[180:183], v[48:51]
	v_mfma_f32_16x16x32_bf16 v[40:43], v[164:167], v[188:191], v[40:43]
	v_mfma_f32_16x16x32_bf16 v[32:35], v[172:175], v[188:191], v[32:35]
	v_mfma_f32_16x16x32_bf16 v[24:27], v[164:167], v[210:213], v[24:27]
	v_mfma_f32_16x16x32_bf16 v[16:19], v[172:175], v[210:213], v[16:19]
	v_mfma_f32_16x16x32_bf16 v[8:11], v[164:167], v[218:221], v[8:11]
	v_mfma_f32_16x16x32_bf16 v[0:3], v[172:175], v[218:221], v[0:3]
	v_mfma_f32_16x16x32_bf16 v[56:59], v[168:171], v[184:187], v[56:59]
	v_mfma_f32_16x16x32_bf16 v[48:51], v[176:179], v[184:187], v[48:51]
	v_mfma_f32_16x16x32_bf16 v[40:43], v[168:171], v[206:209], v[40:43]
	v_mfma_f32_16x16x32_bf16 v[32:35], v[176:179], v[206:209], v[32:35]
	v_mfma_f32_16x16x32_bf16 v[24:27], v[168:171], v[214:217], v[24:27]
	v_mfma_f32_16x16x32_bf16 v[16:19], v[176:179], v[214:217], v[16:19]
	v_mfma_f32_16x16x32_bf16 v[8:11], v[168:171], v[222:225], v[8:11]
	v_mfma_f32_16x16x32_bf16 v[0:3], v[176:179], v[222:225], v[0:3]
	s_setprio 0
	s_barrier
	s_add_i32 s3, 0, 0x18000
	s_add_i32 s26, 0, 0x1c000
	v_add_u32_e32 v160, s3, v139
	v_add_u32_e32 v176, s26, v139
	ds_read_b128 v[142:145], v160
	ds_read_b128 v[150:153], v160 offset:1024
	ds_read_b128 v[156:159], v160 offset:2048
	ds_read_b128 v[160:163], v160 offset:3072
	ds_read_b128 v[164:167], v176
	ds_read_b128 v[168:171], v176 offset:1024
	ds_read_b128 v[172:175], v176 offset:2048
	ds_read_b128 v[176:179], v176 offset:3072
	s_add_u32 s36, s66, 0x80000
	s_addc_u32 s37, s67, 0
	s_mov_b32 m0, s74
	v_lshl_add_u64 v[232:233], s[36:37], 0, v[132:133]
	ds_read_b128 v[180:183], v141 offset:32768
	ds_read_b128 v[184:187], v141 offset:33792
	ds_read_b128 v[188:191], v141 offset:34816
	ds_read_b128 v[206:209], v141 offset:35840
	ds_read_b128 v[210:213], v141 offset:36864
	ds_read_b128 v[214:217], v141 offset:37888
	ds_read_b128 v[218:221], v141 offset:38912
	ds_read_b128 v[222:225], v141 offset:39936
	global_load_lds_dwordx4 v[232:233], off
	v_lshl_add_u64 v[232:233], s[36:37], 0, v[130:131]
	s_mov_b32 m0, s75
	s_nop 0
	global_load_lds_dwordx4 v[232:233], off
	s_waitcnt vmcnt(8)
	s_waitcnt lgkmcnt(0)
	s_barrier
; #define PG8_STAGE(bufoff, gbase, voff) do { _Pragma("unroll") for (int _i = 0; _i < 2; ++_i) \
;         __builtin_amdgcn_global_load_lds((const unsigned*)((const char*)(gbase) + (voff)[_i]), (PG8_LAS unsigned*)(lds + (bufoff) + ldsw + _i * 8192), 16, 0, 0); } while (0)
; #define PG8_LDA(dst, b, h) do { _Pragma("unroll") for (int m = 0; m < 4; ++m) _Pragma("unroll") for (int k = 0; k < 2; ++k) dst[m][k] = *(const PG8_LAS bf16x8*)(lds + PG8_SA(b, h) + aoff + m * 2048 + k * 1024); } while (0)
; #define PG8_MMA(ai, bj, At, Bt) do { __builtin_amdgcn_s_setprio(1); _Pragma("unroll") for (int m = 0; m < 4; ++m) _Pragma("unroll") for (int n = 0; n < 2; ++n) _Pragma("unroll") for (int k = 0; k < 2; ++k) \
;         acc[ai][bj][m][n] = __builtin_amdgcn_mfma_f32_16x16x32_bf16(Bt[n][k], At[m][k], acc[ai][bj][m][n], 0, 0, 0); __builtin_amdgcn_s_setprio(0); } while (0)
; #define PG8_WAIT_V(n) asm volatile("s_waitcnt vmcnt(" #n ")" ::: "memory")
; #define PG8_WAIT_L(n) asm volatile("s_waitcnt lgkmcnt(" #n ")" ::: "memory")
; #define PG8_BAR __builtin_amdgcn_s_barrier()
; #define PG8_SCHED __builtin_amdgcn_sched_barrier(0)
; template <class Epi, class Sched, bool ALIGN_EPI = false, bool SP2 = false>
; __device__ __forceinline__ void gemm_phase(PG8_LAS unsigned char* lds, const Gemm g, const Sched& S, const Epi& E, int wave_s) {
;     ...
;         for (int t = 0; t < nt; t += 2) {
;             const bool last = (t == nt - 2);
;             const char* a1 = cA + (size_t)(t + 1) * kstep;
;             const char* a2 = last ? nA : cA + (size_t)(t + 2) * kstep; const char* b2 = last ? nB : cB + (size_t)(t + 2) * kstep;
;             const char* a3 = a2 + kstep; const char* b3 = b2 + kstep;
;             if (last && has_next) S.a_ready(nxt);
;     ...
;             PG8_WAIT_V(8); PG8_WAIT_L(0); PG8_BAR; PG8_MMA(0, 0, At, B0); PG8_MMA(0, 1, At, B1); PG8_BAR; PG8_SCHED;
;             PG8_LDA(At, 1, 1); PG8_STAGE(PG8_SB(1, 0), b3, voffB); PG8_STAGE(PG8_SB(1, 1), b3 + hstep, voffB); PG8_STAGE(PG8_SA(1, 0), a3, voffA);
;             PG8_WAIT_V(8); PG8_WAIT_L(0); PG8_BAR; PG8_MMA(1, 0, At, B0); PG8_MMA(1, 1, At, B1); PG8_BAR; PG8_SCHED;
	s_setprio 1
	s_waitcnt lgkmcnt(0)
	v_mfma_f32_16x16x32_bf16 v[124:127], v[142:145], v[180:183], v[124:127]
	v_mfma_f32_16x16x32_bf16 v[116:119], v[156:159], v[180:183], v[116:119]
	v_mfma_f32_16x16x32_bf16 v[108:111], v[142:145], v[188:191], v[108:111]
	v_mfma_f32_16x16x32_bf16 v[100:103], v[156:159], v[188:191], v[100:103]
	v_mfma_f32_16x16x32_bf16 v[92:95], v[142:145], v[210:213], v[92:95]
	v_mfma_f32_16x16x32_bf16 v[84:87], v[156:159], v[210:213], v[84:87]
	v_mfma_f32_16x16x32_bf16 v[76:79], v[142:145], v[218:221], v[76:79]
	v_mfma_f32_16x16x32_bf16 v[68:71], v[156:159], v[218:221], v[68:71]
	v_mfma_f32_16x16x32_bf16 v[124:127], v[150:153], v[184:187], v[124:127]
	v_mfma_f32_16x16x32_bf16 v[116:119], v[160:163], v[184:187], v[116:119]
	v_mfma_f32_16x16x32_bf16 v[108:111], v[150:153], v[206:209], v[108:111]
	v_mfma_f32_16x16x32_bf16 v[100:103], v[160:163], v[206:209], v[100:103]
	v_mfma_f32_16x16x32_bf16 v[92:95], v[150:153], v[214:217], v[92:95]
	v_mfma_f32_16x16x32_bf16 v[84:87], v[160:163], v[214:217], v[84:87]
	v_mfma_f32_16x16x32_bf16 v[76:79], v[150:153], v[222:225], v[76:79]
	v_mfma_f32_16x16x32_bf16 v[68:71], v[160:163], v[222:225], v[68:71]
	s_setprio 0
	s_setprio 1
	v_mfma_f32_16x16x32_bf16 v[120:123], v[164:167], v[180:183], v[120:123]
	v_mfma_f32_16x16x32_bf16 v[112:115], v[172:175], v[180:183], v[112:115]
	v_mfma_f32_16x16x32_bf16 v[104:107], v[164:167], v[188:191], v[104:107]
	v_mfma_f32_16x16x32_bf16 v[96:99], v[172:175], v[188:191], v[96:99]
	v_mfma_f32_16x16x32_bf16 v[88:91], v[164:167], v[210:213], v[88:91]
	v_mfma_f32_16x16x32_bf16 v[80:83], v[172:175], v[210:213], v[80:83]
	v_mfma_f32_16x16x32_bf16 v[72:75], v[164:167], v[218:221], v[72:75]
	v_mfma_f32_16x16x32_bf16 v[64:67], v[172:175], v[218:221], v[64:67]
	v_mfma_f32_16x16x32_bf16 v[120:123], v[168:171], v[184:187], v[120:123]
	v_mfma_f32_16x16x32_bf16 v[112:115], v[176:179], v[184:187], v[112:115]
	v_mfma_f32_16x16x32_bf16 v[104:107], v[168:171], v[206:209], v[104:107]
	v_mfma_f32_16x16x32_bf16 v[96:99], v[176:179], v[206:209], v[96:99]
	v_mfma_f32_16x16x32_bf16 v[88:91], v[168:171], v[214:217], v[88:91]
	v_mfma_f32_16x16x32_bf16 v[80:83], v[176:179], v[214:217], v[80:83]
	v_mfma_f32_16x16x32_bf16 v[72:75], v[168:171], v[222:225], v[72:75]
	v_mfma_f32_16x16x32_bf16 v[64:67], v[176:179], v[222:225], v[64:67]
	s_setprio 0
	s_barrier
	s_add_i32 s3, s3, s25
	v_lshl_add_u64 v[146:147], v[146:147], 0, s[34:35]
	s_mov_b32 m0, s3
	ds_read_b128 v[180:183], v141 offset:49152
	ds_read_b128 v[184:187], v141 offset:50176
	ds_read_b128 v[188:191], v141 offset:51200
	ds_read_b128 v[206:209], v141 offset:52224
	ds_read_b128 v[210:213], v141 offset:53248
	ds_read_b128 v[214:217], v141 offset:54272
	ds_read_b128 v[218:221], v141 offset:55296
	ds_read_b128 v[222:225], v141 offset:56320
	global_load_lds_dwordx4 v[146:147], off
	s_add_i32 m0, s3, 0x2000
	s_add_u32 s36, s64, 0x80080
	v_lshl_add_u64 v[146:147], v[226:227], 0, s[34:35]
	s_addc_u32 s37, s65, 0
	s_add_i32 s3, s26, s25
	global_load_lds_dwordx4 v[146:147], off
	v_lshl_add_u64 v[146:147], s[36:37], 0, v[148:149]
	s_mov_b32 m0, s3
	s_nop 0
	global_load_lds_dwordx4 v[146:147], off
	v_lshl_add_u64 v[146:147], s[36:37], 0, v[128:129]
	s_add_i32 m0, s3, 0x2000
	s_nop 0
	global_load_lds_dwordx4 v[146:147], off
	v_lshl_add_u64 v[146:147], v[228:229], 0, s[34:35]
	s_mov_b32 m0, s77
	s_nop 0
	global_load_lds_dwordx4 v[146:147], off
	v_lshl_add_u64 v[146:147], v[230:231], 0, s[34:35]
	s_mov_b32 m0, s78
	s_nop 0
	global_load_lds_dwordx4 v[146:147], off
	s_waitcnt vmcnt(8)
	s_waitcnt lgkmcnt(0)
	s_barrier
	s_setprio 1
	s_waitcnt lgkmcnt(0)
	v_mfma_f32_16x16x32_bf16 v[60:63], v[142:145], v[180:183], v[60:63]
	s_add_i32 s38, s38, 2
	v_mfma_f32_16x16x32_bf16 v[52:55], v[156:159], v[180:183], v[52:55]
	s_add_u32 s62, s62, 0x100
	v_mfma_f32_16x16x32_bf16 v[44:47], v[142:145], v[188:191], v[44:47]
	s_addc_u32 s63, s63, 0
	v_mfma_f32_16x16x32_bf16 v[36:39], v[156:159], v[188:191], v[36:39]
	s_add_u32 s28, s28, 0x100
	v_mfma_f32_16x16x32_bf16 v[28:31], v[142:145], v[210:213], v[28:31]
	s_addc_u32 s29, s29, 0
	v_mfma_f32_16x16x32_bf16 v[20:23], v[156:159], v[210:213], v[20:23]
	s_add_u32 s3, s62, 0xfff80080
	v_mfma_f32_16x16x32_bf16 v[12:15], v[142:145], v[218:221], v[12:15]
	s_addc_u32 s26, s63, -1
	v_mfma_f32_16x16x32_bf16 v[4:7], v[156:159], v[218:221], v[4:7]
	s_add_i32 s36, 0, 0x10000
	v_mfma_f32_16x16x32_bf16 v[60:63], v[150:153], v[184:187], v[60:63]
	s_cmp_eq_u32 s38, 28
	v_mfma_f32_16x16x32_bf16 v[52:55], v[160:163], v[184:187], v[52:55]
	s_cselect_b32 s67, s19, s26
	v_mfma_f32_16x16x32_bf16 v[44:47], v[150:153], v[206:209], v[44:47]
	s_cselect_b32 s66, s22, s3
	v_mfma_f32_16x16x32_bf16 v[36:39], v[160:163], v[206:209], v[36:39]
	s_cselect_b32 s65, s5, s29
	v_mfma_f32_16x16x32_bf16 v[28:31], v[150:153], v[214:217], v[28:31]
	s_cselect_b32 s64, s23, s28
	v_mfma_f32_16x16x32_bf16 v[20:23], v[160:163], v[214:217], v[20:23]
	s_add_i32 s3, 0, 0x14000
	v_mfma_f32_16x16x32_bf16 v[12:15], v[150:153], v[222:225], v[12:15]
	v_mfma_f32_16x16x32_bf16 v[4:7], v[160:163], v[222:225], v[4:7]
	s_setprio 0
	s_setprio 1
	v_mfma_f32_16x16x32_bf16 v[56:59], v[164:167], v[180:183], v[56:59]
	v_mfma_f32_16x16x32_bf16 v[48:51], v[172:175], v[180:183], v[48:51]
	v_mfma_f32_16x16x32_bf16 v[40:43], v[164:167], v[188:191], v[40:43]
	v_mfma_f32_16x16x32_bf16 v[32:35], v[172:175], v[188:191], v[32:35]
	v_mfma_f32_16x16x32_bf16 v[24:27], v[164:167], v[210:213], v[24:27]
	v_mfma_f32_16x16x32_bf16 v[16:19], v[172:175], v[210:213], v[16:19]
	v_mfma_f32_16x16x32_bf16 v[8:11], v[164:167], v[218:221], v[8:11]
	v_mfma_f32_16x16x32_bf16 v[0:3], v[172:175], v[218:221], v[0:3]
	v_mfma_f32_16x16x32_bf16 v[56:59], v[168:171], v[184:187], v[56:59]
	v_mfma_f32_16x16x32_bf16 v[48:51], v[176:179], v[184:187], v[48:51]
	v_mfma_f32_16x16x32_bf16 v[40:43], v[168:171], v[206:209], v[40:43]
	v_mfma_f32_16x16x32_bf16 v[32:35], v[176:179], v[206:209], v[32:35]
	v_mfma_f32_16x16x32_bf16 v[24:27], v[168:171], v[214:217], v[24:27]
	v_mfma_f32_16x16x32_bf16 v[16:19], v[176:179], v[214:217], v[16:19]
	v_mfma_f32_16x16x32_bf16 v[8:11], v[168:171], v[222:225], v[8:11]
	v_mfma_f32_16x16x32_bf16 v[0:3], v[176:179], v[222:225], v[0:3]
	s_setprio 0
	s_barrier
	s_cmp_gt_u32 s38, 29
	s_cbranch_scc0 .LBB0_82
	s_and_b64 vcc, exec, s[48:49]
	s_cbranch_vccz .LBB0_85
	s_barrier

; #define PG8_STAGE(bufoff, gbase, voff) do { _Pragma("unroll") for (int _i = 0; _i < 2; ++_i) \
;         __builtin_amdgcn_global_load_lds((const unsigned*)((const char*)(gbase) + (voff)[_i]), (PG8_LAS unsigned*)(lds + (bufoff) + ldsw + _i * 8192), 16, 0, 0); } while (0)
; #define PG8_LDA(dst, b, h) do { _Pragma("unroll") for (int m = 0; m < 4; ++m) _Pragma("unroll") for (int k = 0; k < 2; ++k) dst[m][k] = *(const PG8_LAS bf16x8*)(lds + PG8_SA(b, h) + aoff + m * 2048 + k * 1024); } while (0)
; #define PG8_LDB(dst, b, h) do { _Pragma("unroll") for (int n = 0; n < 2; ++n) _Pragma("unroll") for (int k = 0; k < 2; ++k) dst[n][k] = *(const PG8_LAS bf16x8*)(lds + PG8_SB(b, h) + boff + n * 2048 + k * 1024); } while (0)
; #define PG8_WAIT_V(n) asm volatile("s_waitcnt vmcnt(" #n ")" ::: "memory")
; #define PG8_WAIT_L(n) asm volatile("s_waitcnt lgkmcnt(" #n ")" ::: "memory")
; template <class Epi, class Sched, bool ALIGN_EPI = false, bool SP2 = false>
; __device__ __forceinline__ void gemm_phase(PG8_LAS unsigned char* lds, const Gemm g, const Sched& S, const Epi& E, int wave_s) {
;     ...
;         const bool has_next = S.next(ui + 1, nxt);
;         const char* nA = has_next ? (const char*)g.A + (size_t)nxt.pm * tstep : cA; const char* nB = has_next ? (const char*)g.Bt + (size_t)nxt.pn * tstep : cB;
;         for (int t = 0; t < nt; t += 2) {
;             const bool last = (t == nt - 2);
;             const char* a1 = cA + (size_t)(t + 1) * kstep;
;             const char* a2 = last ? nA : cA + (size_t)(t + 2) * kstep; const char* b2 = last ? nB : cB + (size_t)(t + 2) * kstep;
;             const char* a3 = a2 + kstep; const char* b3 = b2 + kstep;
;             if (last && has_next) S.a_ready(nxt);
;             if constexpr (SP2) {
;             PG8_LDB(B0, 0, 0); PG8_LDB(B1, 0, 1); PG8_SCHED; PG8_LDA(At, 0, 0); PG8_STAGE(PG8_SA(1, 1), a1 + hstep, voffA);
;             PG8_WAIT_V(8); PG8_WAIT_L(0); PG8_BAR; PG8_MMA(0, 0, At, B0); PG8_MMA(0, 1, At, B1); PG8_BAR; PG8_SCHED;
;     ...
;         { float zf_ = 0.f; asm volatile("" : "+v"(zf_)); const f32x4 zero4_ = {zf_, zf_, zf_, zf_};
; #pragma unroll
;         for (int a = 0; a < 2; ++a)
; #pragma unroll
;             for (int b = 0; b < 2; ++b)
; #pragma unroll
;                 for (int m = 0; m < 4; ++m)
; #pragma unroll
;                     for (int n = 0; n < 2; ++n) acc[a][b][m][n] = zero4_; }
.LBB0_114:
	s_ashr_i32 s55, s54, 31
	s_lshl_b64 s[22:23], s[54:55], 20
	s_add_u32 s56, s9, s22
	s_addc_u32 s57, s11, s23
	s_and_b64 s[22:23], s[40:41], exec
	s_cselect_b32 s22, s57, s63
	s_cselect_b32 s23, s56, s62
	s_ashr_i32 s53, s52, 31
	s_lshl_b64 s[28:29], s[52:53], 20
	s_add_u32 s58, s20, s28
	s_addc_u32 s59, s21, s29
	s_and_b64 s[28:29], s[40:41], exec
	s_cselect_b32 s5, s59, s65
	s_cselect_b32 s28, s58, s64
	s_add_u32 s29, s64, 0x100
	v_mov_b64_e32 v[6:7], v[2:3]
	v_mov_b64_e32 v[18:19], v[2:3]
	v_mov_b64_e32 v[22:23], v[2:3]
	v_mov_b64_e32 v[34:35], v[2:3]
	v_mov_b64_e32 v[38:39], v[2:3]
	v_mov_b64_e32 v[50:51], v[2:3]
	v_mov_b64_e32 v[54:55], v[2:3]
	v_mov_b64_e32 v[10:11], v[2:3]
	v_mov_b64_e32 v[14:15], v[2:3]
	v_mov_b64_e32 v[26:27], v[2:3]
	v_mov_b64_e32 v[30:31], v[2:3]
	v_mov_b64_e32 v[42:43], v[2:3]
	v_mov_b64_e32 v[46:47], v[2:3]
	v_mov_b64_e32 v[58:59], v[2:3]
	v_mov_b64_e32 v[62:63], v[2:3]
	v_mov_b64_e32 v[66:67], v[2:3]
	v_mov_b64_e32 v[70:71], v[2:3]
	v_mov_b64_e32 v[82:83], v[2:3]
	v_mov_b64_e32 v[86:87], v[2:3]
	v_mov_b64_e32 v[98:99], v[2:3]
	v_mov_b64_e32 v[102:103], v[2:3]
	v_mov_b64_e32 v[114:115], v[2:3]
	v_mov_b64_e32 v[118:119], v[2:3]
	v_mov_b64_e32 v[74:75], v[2:3]
	v_mov_b64_e32 v[78:79], v[2:3]
	v_mov_b64_e32 v[90:91], v[2:3]
	v_mov_b64_e32 v[94:95], v[2:3]
	v_mov_b64_e32 v[106:107], v[2:3]
	v_mov_b64_e32 v[110:111], v[2:3]
	v_mov_b64_e32 v[122:123], v[2:3]
	v_mov_b64_e32 v[126:127], v[2:3]
	s_addc_u32 s39, s65, 0
	s_mov_b32 s53, -2
	v_mov_b64_e32 v[4:5], v[0:1]
	v_mov_b64_e32 v[16:17], v[0:1]
	v_mov_b64_e32 v[20:21], v[0:1]
	v_mov_b64_e32 v[32:33], v[0:1]
	v_mov_b64_e32 v[36:37], v[0:1]
	v_mov_b64_e32 v[48:49], v[0:1]
	v_mov_b64_e32 v[52:53], v[0:1]
	v_mov_b64_e32 v[8:9], v[0:1]
	v_mov_b64_e32 v[12:13], v[0:1]
	v_mov_b64_e32 v[24:25], v[0:1]
	v_mov_b64_e32 v[28:29], v[0:1]
	v_mov_b64_e32 v[40:41], v[0:1]
	v_mov_b64_e32 v[44:45], v[0:1]
	v_mov_b64_e32 v[56:57], v[0:1]
	v_mov_b64_e32 v[60:61], v[0:1]
	v_mov_b64_e32 v[64:65], v[0:1]
	v_mov_b64_e32 v[68:69], v[0:1]
	v_mov_b64_e32 v[80:81], v[0:1]
	v_mov_b64_e32 v[84:85], v[0:1]
	v_mov_b64_e32 v[96:97], v[0:1]
	v_mov_b64_e32 v[100:101], v[0:1]
	v_mov_b64_e32 v[112:113], v[0:1]
	v_mov_b64_e32 v[116:117], v[0:1]
	v_mov_b64_e32 v[72:73], v[0:1]
	v_mov_b64_e32 v[76:77], v[0:1]
	v_mov_b64_e32 v[88:89], v[0:1]
	v_mov_b64_e32 v[92:93], v[0:1]
	v_mov_b64_e32 v[104:105], v[0:1]
	v_mov_b64_e32 v[108:109], v[0:1]
	v_mov_b64_e32 v[120:121], v[0:1]
	v_mov_b64_e32 v[124:125], v[0:1]
	s_add_u32 s64, s62, 0x100
	s_addc_u32 s65, s63, 0
	s_add_i32 s3, 0, 0x10000
	s_cmp_eq_u32 s53, 28
	s_cselect_b32 s75, s22, s65
	s_cselect_b32 s74, s23, s64
	s_cselect_b32 s67, s5, s39
	s_cselect_b32 s66, s28, s29
	s_add_i32 s26, 0, 0x14000
.LBB0_115:
	v_add_u32_e32 v134, s3, v137
	ds_read_b128 v[140:143], v134
	ds_read_b128 v[144:147], v134 offset:1024
	ds_read_b128 v[150:153], v134 offset:2048
	ds_read_b128 v[156:159], v134 offset:3072
	v_add_u32_e32 v134, s26, v137
	ds_read_b128 v[160:163], v134
	ds_read_b128 v[164:167], v134 offset:1024
	ds_read_b128 v[168:171], v134 offset:2048
	ds_read_b128 v[172:175], v134 offset:3072
	v_lshl_add_u64 v[134:135], s[62:63], 0, v[130:131]
	s_add_i32 m0, s61, 0xc000
	ds_read_b128 v[176:179], v139
	ds_read_b128 v[180:183], v139 offset:1024
	ds_read_b128 v[184:187], v139 offset:2048
	ds_read_b128 v[188:191], v139 offset:3072
	ds_read_b128 v[206:209], v139 offset:4096
	ds_read_b128 v[210:213], v139 offset:5120
	ds_read_b128 v[214:217], v139 offset:6144
	ds_read_b128 v[218:221], v139 offset:7168
	global_load_lds_dwordx4 v[134:135], off
	v_lshl_add_u64 v[134:135], s[62:63], 0, v[132:133]
	s_add_i32 m0, s61, 0xe000
	s_nop 0
	global_load_lds_dwordx4 v[134:135], off
	s_waitcnt vmcnt(8)
	s_waitcnt lgkmcnt(0)
	s_barrier
	s_setprio 1
	s_waitcnt lgkmcnt(0)
	v_mfma_f32_16x16x32_bf16 v[124:127], v[140:143], v[176:179], v[124:127]
	v_mfma_f32_16x16x32_bf16 v[120:123], v[150:153], v[176:179], v[120:123]
	v_mfma_f32_16x16x32_bf16 v[108:111], v[140:143], v[184:187], v[108:111]
	v_mfma_f32_16x16x32_bf16 v[104:107], v[150:153], v[184:187], v[104:107]
	v_mfma_f32_16x16x32_bf16 v[92:95], v[140:143], v[206:209], v[92:95]
	v_mfma_f32_16x16x32_bf16 v[88:91], v[150:153], v[206:209], v[88:91]
	v_mfma_f32_16x16x32_bf16 v[76:79], v[140:143], v[214:217], v[76:79]
	v_mfma_f32_16x16x32_bf16 v[72:75], v[150:153], v[214:217], v[72:75]
	v_mfma_f32_16x16x32_bf16 v[124:127], v[144:147], v[180:183], v[124:127]
	v_mfma_f32_16x16x32_bf16 v[120:123], v[156:159], v[180:183], v[120:123]
	v_mfma_f32_16x16x32_bf16 v[108:111], v[144:147], v[188:191], v[108:111]
	v_mfma_f32_16x16x32_bf16 v[104:107], v[156:159], v[188:191], v[104:107]
	v_mfma_f32_16x16x32_bf16 v[92:95], v[144:147], v[210:213], v[92:95]
	v_mfma_f32_16x16x32_bf16 v[88:91], v[156:159], v[210:213], v[88:91]
	v_mfma_f32_16x16x32_bf16 v[76:79], v[144:147], v[218:221], v[76:79]
	v_mfma_f32_16x16x32_bf16 v[72:75], v[156:159], v[218:221], v[72:75]
	s_setprio 0
	s_setprio 1
	v_mfma_f32_16x16x32_bf16 v[116:119], v[160:163], v[176:179], v[116:119]
	v_mfma_f32_16x16x32_bf16 v[112:115], v[168:171], v[176:179], v[112:115]
	v_mfma_f32_16x16x32_bf16 v[100:103], v[160:163], v[184:187], v[100:103]
	v_mfma_f32_16x16x32_bf16 v[96:99], v[168:171], v[184:187], v[96:99]
	v_mfma_f32_16x16x32_bf16 v[84:87], v[160:163], v[206:209], v[84:87]
	v_mfma_f32_16x16x32_bf16 v[80:83], v[168:171], v[206:209], v[80:83]
	v_mfma_f32_16x16x32_bf16 v[68:71], v[160:163], v[214:217], v[68:71]
	v_mfma_f32_16x16x32_bf16 v[64:67], v[168:171], v[214:217], v[64:67]
	v_mfma_f32_16x16x32_bf16 v[116:119], v[164:167], v[180:183], v[116:119]
	v_mfma_f32_16x16x32_bf16 v[112:115], v[172:175], v[180:183], v[112:115]
	v_mfma_f32_16x16x32_bf16 v[100:103], v[164:167], v[188:191], v[100:103]
	v_mfma_f32_16x16x32_bf16 v[96:99], v[172:175], v[188:191], v[96:99]
	v_mfma_f32_16x16x32_bf16 v[84:87], v[164:167], v[210:213], v[84:87]
	v_mfma_f32_16x16x32_bf16 v[80:83], v[172:175], v[210:213], v[80:83]
	v_mfma_f32_16x16x32_bf16 v[68:71], v[164:167], v[218:221], v[68:71]
	v_mfma_f32_16x16x32_bf16 v[64:67], v[172:175], v[218:221], v[64:67]
	s_setprio 0
	s_barrier
; #define PG8_STAGE(bufoff, gbase, voff) do { _Pragma("unroll") for (int _i = 0; _i < 2; ++_i) \
;         __builtin_amdgcn_global_load_lds((const unsigned*)((const char*)(gbase) + (voff)[_i]), (PG8_LAS unsigned*)(lds + (bufoff) + ldsw + _i * 8192), 16, 0, 0); } while (0)
; #define PG8_LDA(dst, b, h) do { _Pragma("unroll") for (int m = 0; m < 4; ++m) _Pragma("unroll") for (int k = 0; k < 2; ++k) dst[m][k] = *(const PG8_LAS bf16x8*)(lds + PG8_SA(b, h) + aoff + m * 2048 + k * 1024); } while (0)
; #define PG8_LDB(dst, b, h) do { _Pragma("unroll") for (int n = 0; n < 2; ++n) _Pragma("unroll") for (int k = 0; k < 2; ++k) dst[n][k] = *(const PG8_LAS bf16x8*)(lds + PG8_SB(b, h) + boff + n * 2048 + k * 1024); } while (0)
; #define PG8_MMA(ai, bj, At, Bt) do { __builtin_amdgcn_s_setprio(1); _Pragma("unroll") for (int m = 0; m < 4; ++m) _Pragma("unroll") for (int n = 0; n < 2; ++n) _Pragma("unroll") for (int k = 0; k < 2; ++k) \
;         acc[ai][bj][m][n] = __builtin_amdgcn_mfma_f32_16x16x32_bf16(Bt[n][k], At[m][k], acc[ai][bj][m][n], 0, 0, 0); __builtin_amdgcn_s_setprio(0); } while (0)
; #define PG8_WAIT_V(n) asm volatile("s_waitcnt vmcnt(" #n ")" ::: "memory")
; #define PG8_WAIT_L(n) asm volatile("s_waitcnt lgkmcnt(" #n ")" ::: "memory")
; #define PG8_BAR __builtin_amdgcn_s_barrier()
; #define PG8_SCHED __builtin_amdgcn_sched_barrier(0)
; template <class Epi, class Sched, bool ALIGN_EPI = false, bool SP2 = false>
; __device__ __forceinline__ void gemm_phase(PG8_LAS unsigned char* lds, const Gemm g, const Sched& S, const Epi& E, int wave_s) {
;     ...
;             PG8_LDA(At, 0, 1); PG8_STAGE(PG8_SB(0, 0), b2, voffB); PG8_STAGE(PG8_SB(0, 1), b2 + hstep, voffB); PG8_STAGE(PG8_SA(0, 0), a2, voffA);
;             PG8_WAIT_V(8); PG8_WAIT_L(0); PG8_BAR; PG8_MMA(1, 0, At, B0); PG8_MMA(1, 1, At, B1); PG8_BAR; PG8_SCHED;
;             PG8_LDB(B0, 1, 0); PG8_LDB(B1, 1, 1); PG8_SCHED; PG8_LDA(At, 1, 0); PG8_STAGE(PG8_SA(0, 1), a2 + hstep, voffA);
;             PG8_WAIT_V(8); PG8_WAIT_L(0); PG8_BAR; PG8_MMA(0, 0, At, B0); PG8_MMA(0, 1, At, B1); PG8_BAR; PG8_SCHED;
	s_add_i32 s3, s3, s25
	v_lshl_add_u64 v[134:135], s[66:67], 0, v[148:149]
	s_mov_b32 m0, s3
	ds_read_b128 v[176:179], v139 offset:16384
	ds_read_b128 v[180:183], v139 offset:17408
	ds_read_b128 v[184:187], v139 offset:18432
	ds_read_b128 v[188:191], v139 offset:19456
	ds_read_b128 v[206:209], v139 offset:20480
	ds_read_b128 v[210:213], v139 offset:21504
	ds_read_b128 v[214:217], v139 offset:22528
	ds_read_b128 v[218:221], v139 offset:23552
	global_load_lds_dwordx4 v[134:135], off
	s_add_i32 m0, s3, 0x2000
	s_add_u32 s36, s66, 0x80000
	v_lshl_add_u64 v[222:223], s[66:67], 0, v[128:129]
	s_addc_u32 s37, s67, 0
	s_add_i32 s3, s26, s25
	global_load_lds_dwordx4 v[222:223], off
	v_lshl_add_u64 v[224:225], s[36:37], 0, v[148:149]
	s_mov_b32 m0, s3
	v_lshl_add_u64 v[226:227], s[74:75], 0, v[128:129]
	global_load_lds_dwordx4 v[224:225], off
	v_lshl_add_u64 v[224:225], s[36:37], 0, v[128:129]
	s_add_i32 m0, s3, 0x2000
	s_nop 0
	global_load_lds_dwordx4 v[224:225], off
	v_lshl_add_u64 v[224:225], s[74:75], 0, v[148:149]
	s_mov_b32 m0, s61
	s_nop 0
	global_load_lds_dwordx4 v[224:225], off
	s_mov_b32 m0, s73
	s_nop 0
	global_load_lds_dwordx4 v[226:227], off
	s_waitcnt vmcnt(8)
	s_waitcnt lgkmcnt(0)
	s_barrier
	s_setprio 1
	s_waitcnt lgkmcnt(0)
	v_mfma_f32_16x16x32_bf16 v[60:63], v[140:143], v[176:179], v[60:63]
	v_mfma_f32_16x16x32_bf16 v[56:59], v[150:153], v[176:179], v[56:59]
	v_mfma_f32_16x16x32_bf16 v[44:47], v[140:143], v[184:187], v[44:47]
	v_mfma_f32_16x16x32_bf16 v[40:43], v[150:153], v[184:187], v[40:43]
	v_mfma_f32_16x16x32_bf16 v[28:31], v[140:143], v[206:209], v[28:31]
	v_mfma_f32_16x16x32_bf16 v[24:27], v[150:153], v[206:209], v[24:27]
	v_mfma_f32_16x16x32_bf16 v[12:15], v[140:143], v[214:217], v[12:15]
	v_mfma_f32_16x16x32_bf16 v[8:11], v[150:153], v[214:217], v[8:11]
	v_mfma_f32_16x16x32_bf16 v[60:63], v[144:147], v[180:183], v[60:63]
	v_mfma_f32_16x16x32_bf16 v[56:59], v[156:159], v[180:183], v[56:59]
	v_mfma_f32_16x16x32_bf16 v[44:47], v[144:147], v[188:191], v[44:47]
	v_mfma_f32_16x16x32_bf16 v[40:43], v[156:159], v[188:191], v[40:43]
	v_mfma_f32_16x16x32_bf16 v[28:31], v[144:147], v[210:213], v[28:31]
	v_mfma_f32_16x16x32_bf16 v[24:27], v[156:159], v[210:213], v[24:27]
	v_mfma_f32_16x16x32_bf16 v[12:15], v[144:147], v[218:221], v[12:15]
	v_mfma_f32_16x16x32_bf16 v[8:11], v[156:159], v[218:221], v[8:11]
	s_setprio 0
	s_setprio 1
	v_mfma_f32_16x16x32_bf16 v[52:55], v[160:163], v[176:179], v[52:55]
	v_mfma_f32_16x16x32_bf16 v[48:51], v[168:171], v[176:179], v[48:51]
	v_mfma_f32_16x16x32_bf16 v[36:39], v[160:163], v[184:187], v[36:39]
	v_mfma_f32_16x16x32_bf16 v[32:35], v[168:171], v[184:187], v[32:35]
	v_mfma_f32_16x16x32_bf16 v[20:23], v[160:163], v[206:209], v[20:23]
	v_mfma_f32_16x16x32_bf16 v[16:19], v[168:171], v[206:209], v[16:19]
	v_mfma_f32_16x16x32_bf16 v[4:7], v[160:163], v[214:217], v[4:7]
	v_mfma_f32_16x16x32_bf16 v[0:3], v[168:171], v[214:217], v[0:3]
	v_mfma_f32_16x16x32_bf16 v[52:55], v[164:167], v[180:183], v[52:55]
	v_mfma_f32_16x16x32_bf16 v[48:51], v[172:175], v[180:183], v[48:51]
	v_mfma_f32_16x16x32_bf16 v[36:39], v[164:167], v[188:191], v[36:39]
	v_mfma_f32_16x16x32_bf16 v[32:35], v[172:175], v[188:191], v[32:35]
	v_mfma_f32_16x16x32_bf16 v[20:23], v[164:167], v[210:213], v[20:23]
	v_mfma_f32_16x16x32_bf16 v[16:19], v[172:175], v[210:213], v[16:19]
	v_mfma_f32_16x16x32_bf16 v[4:7], v[164:167], v[218:221], v[4:7]
	v_mfma_f32_16x16x32_bf16 v[0:3], v[172:175], v[218:221], v[0:3]
	s_setprio 0
	s_barrier
	s_add_i32 s3, 0, 0x18000
	s_add_i32 s26, 0, 0x1c000
	v_add_u32_e32 v156, s3, v137
	v_add_u32_e32 v172, s26, v137
	ds_read_b128 v[140:143], v156
	ds_read_b128 v[144:147], v156 offset:1024
	ds_read_b128 v[150:153], v156 offset:2048
	ds_read_b128 v[156:159], v156 offset:3072
	ds_read_b128 v[160:163], v172
	ds_read_b128 v[164:167], v172 offset:1024
	ds_read_b128 v[168:171], v172 offset:2048
	ds_read_b128 v[172:175], v172 offset:3072
	s_add_u32 s36, s74, 0x80000
	s_addc_u32 s37, s75, 0
	s_mov_b32 m0, s76
	v_lshl_add_u64 v[228:229], s[36:37], 0, v[148:149]
	ds_read_b128 v[176:179], v139 offset:32768
	ds_read_b128 v[180:183], v139 offset:33792
	ds_read_b128 v[184:187], v139 offset:34816
	ds_read_b128 v[188:191], v139 offset:35840
	ds_read_b128 v[206:209], v139 offset:36864
	ds_read_b128 v[210:213], v139 offset:37888
	ds_read_b128 v[214:217], v139 offset:38912
	ds_read_b128 v[218:221], v139 offset:39936
	global_load_lds_dwordx4 v[228:229], off
	v_lshl_add_u64 v[228:229], s[36:37], 0, v[128:129]
	s_mov_b32 m0, s77
	s_nop 0
	global_load_lds_dwordx4 v[228:229], off
	s_waitcnt vmcnt(8)
	s_waitcnt lgkmcnt(0)
	s_barrier
; #define PG8_STAGE(bufoff, gbase, voff) do { _Pragma("unroll") for (int _i = 0; _i < 2; ++_i) \
;         __builtin_amdgcn_global_load_lds((const unsigned*)((const char*)(gbase) + (voff)[_i]), (PG8_LAS unsigned*)(lds + (bufoff) + ldsw + _i * 8192), 16, 0, 0); } while (0)
; #define PG8_LDA(dst, b, h) do { _Pragma("unroll") for (int m = 0; m < 4; ++m) _Pragma("unroll") for (int k = 0; k < 2; ++k) dst[m][k] = *(const PG8_LAS bf16x8*)(lds + PG8_SA(b, h) + aoff + m * 2048 + k * 1024); } while (0)
; #define PG8_MMA(ai, bj, At, Bt) do { __builtin_amdgcn_s_setprio(1); _Pragma("unroll") for (int m = 0; m < 4; ++m) _Pragma("unroll") for (int n = 0; n < 2; ++n) _Pragma("unroll") for (int k = 0; k < 2; ++k) \
;         acc[ai][bj][m][n] = __builtin_amdgcn_mfma_f32_16x16x32_bf16(Bt[n][k], At[m][k], acc[ai][bj][m][n], 0, 0, 0); __builtin_amdgcn_s_setprio(0); } while (0)
; #define PG8_WAIT_V(n) asm volatile("s_waitcnt vmcnt(" #n ")" ::: "memory")
; #define PG8_WAIT_L(n) asm volatile("s_waitcnt lgkmcnt(" #n ")" ::: "memory")
; #define PG8_BAR __builtin_amdgcn_s_barrier()
; #define PG8_SCHED __builtin_amdgcn_sched_barrier(0)
; template <class Epi, class Sched, bool ALIGN_EPI = false, bool SP2 = false>
; __device__ __forceinline__ void gemm_phase(PG8_LAS unsigned char* lds, const Gemm g, const Sched& S, const Epi& E, int wave_s) {
;     ...
;         for (int t = 0; t < nt; t += 2) {
;             const bool last = (t == nt - 2);
;             const char* a1 = cA + (size_t)(t + 1) * kstep;
;             const char* a2 = last ? nA : cA + (size_t)(t + 2) * kstep; const char* b2 = last ? nB : cB + (size_t)(t + 2) * kstep;
;             const char* a3 = a2 + kstep; const char* b3 = b2 + kstep;
;             if (last && has_next) S.a_ready(nxt);
;     ...
;             PG8_WAIT_V(8); PG8_WAIT_L(0); PG8_BAR; PG8_MMA(0, 0, At, B0); PG8_MMA(0, 1, At, B1); PG8_BAR; PG8_SCHED;
;             PG8_LDA(At, 1, 1); PG8_STAGE(PG8_SB(1, 0), b3, voffB); PG8_STAGE(PG8_SB(1, 1), b3 + hstep, voffB); PG8_STAGE(PG8_SA(1, 0), a3, voffA);
;             PG8_WAIT_V(8); PG8_WAIT_L(0); PG8_BAR; PG8_MMA(1, 0, At, B0); PG8_MMA(1, 1, At, B1); PG8_BAR; PG8_SCHED;
	s_setprio 1
	s_waitcnt lgkmcnt(0)
	v_mfma_f32_16x16x32_bf16 v[124:127], v[140:143], v[176:179], v[124:127]
	v_mfma_f32_16x16x32_bf16 v[120:123], v[150:153], v[176:179], v[120:123]
	v_mfma_f32_16x16x32_bf16 v[108:111], v[140:143], v[184:187], v[108:111]
	v_mfma_f32_16x16x32_bf16 v[104:107], v[150:153], v[184:187], v[104:107]
	v_mfma_f32_16x16x32_bf16 v[92:95], v[140:143], v[206:209], v[92:95]
	v_mfma_f32_16x16x32_bf16 v[88:91], v[150:153], v[206:209], v[88:91]
	v_mfma_f32_16x16x32_bf16 v[76:79], v[140:143], v[214:217], v[76:79]
	v_mfma_f32_16x16x32_bf16 v[72:75], v[150:153], v[214:217], v[72:75]
	v_mfma_f32_16x16x32_bf16 v[124:127], v[144:147], v[180:183], v[124:127]
	v_mfma_f32_16x16x32_bf16 v[120:123], v[156:159], v[180:183], v[120:123]
	v_mfma_f32_16x16x32_bf16 v[108:111], v[144:147], v[188:191], v[108:111]
	v_mfma_f32_16x16x32_bf16 v[104:107], v[156:159], v[188:191], v[104:107]
	v_mfma_f32_16x16x32_bf16 v[92:95], v[144:147], v[210:213], v[92:95]
	v_mfma_f32_16x16x32_bf16 v[88:91], v[156:159], v[210:213], v[88:91]
	v_mfma_f32_16x16x32_bf16 v[76:79], v[144:147], v[218:221], v[76:79]
	v_mfma_f32_16x16x32_bf16 v[72:75], v[156:159], v[218:221], v[72:75]
	s_setprio 0
	s_setprio 1
	v_mfma_f32_16x16x32_bf16 v[116:119], v[160:163], v[176:179], v[116:119]
	v_mfma_f32_16x16x32_bf16 v[112:115], v[168:171], v[176:179], v[112:115]
	v_mfma_f32_16x16x32_bf16 v[100:103], v[160:163], v[184:187], v[100:103]
	v_mfma_f32_16x16x32_bf16 v[96:99], v[168:171], v[184:187], v[96:99]
	v_mfma_f32_16x16x32_bf16 v[84:87], v[160:163], v[206:209], v[84:87]
	v_mfma_f32_16x16x32_bf16 v[80:83], v[168:171], v[206:209], v[80:83]
	v_mfma_f32_16x16x32_bf16 v[68:71], v[160:163], v[214:217], v[68:71]
	v_mfma_f32_16x16x32_bf16 v[64:67], v[168:171], v[214:217], v[64:67]
	v_mfma_f32_16x16x32_bf16 v[116:119], v[164:167], v[180:183], v[116:119]
	v_mfma_f32_16x16x32_bf16 v[112:115], v[172:175], v[180:183], v[112:115]
	v_mfma_f32_16x16x32_bf16 v[100:103], v[164:167], v[188:191], v[100:103]
	v_mfma_f32_16x16x32_bf16 v[96:99], v[172:175], v[188:191], v[96:99]
	v_mfma_f32_16x16x32_bf16 v[84:87], v[164:167], v[210:213], v[84:87]
	v_mfma_f32_16x16x32_bf16 v[80:83], v[172:175], v[210:213], v[80:83]
	v_mfma_f32_16x16x32_bf16 v[68:71], v[164:167], v[218:221], v[68:71]
	v_mfma_f32_16x16x32_bf16 v[64:67], v[172:175], v[218:221], v[64:67]
	s_setprio 0
	s_barrier
	s_add_i32 s3, s3, s25
	v_lshl_add_u64 v[134:135], v[134:135], 0, s[34:35]
	s_mov_b32 m0, s3
	ds_read_b128 v[176:179], v139 offset:49152
	ds_read_b128 v[180:183], v139 offset:50176
	ds_read_b128 v[184:187], v139 offset:51200
	ds_read_b128 v[188:191], v139 offset:52224
	ds_read_b128 v[206:209], v139 offset:53248
	ds_read_b128 v[210:213], v139 offset:54272
	ds_read_b128 v[214:217], v139 offset:55296
	ds_read_b128 v[218:221], v139 offset:56320
	global_load_lds_dwordx4 v[134:135], off
	s_add_i32 m0, s3, 0x2000
	s_add_u32 s36, s66, 0x80080
	v_lshl_add_u64 v[134:135], v[222:223], 0, s[34:35]
	s_addc_u32 s37, s67, 0
	s_add_i32 s3, s26, s25
	global_load_lds_dwordx4 v[134:135], off
	v_lshl_add_u64 v[134:135], s[36:37], 0, v[148:149]
	s_mov_b32 m0, s3
	s_nop 0
	global_load_lds_dwordx4 v[134:135], off
	v_lshl_add_u64 v[134:135], s[36:37], 0, v[128:129]
	s_add_i32 m0, s3, 0x2000
	s_nop 0
	global_load_lds_dwordx4 v[134:135], off
	v_lshl_add_u64 v[134:135], v[224:225], 0, s[34:35]
	s_mov_b32 m0, s79
	s_nop 0
	global_load_lds_dwordx4 v[134:135], off
	v_lshl_add_u64 v[134:135], v[226:227], 0, s[34:35]
	s_mov_b32 m0, s18
	s_nop 0
	global_load_lds_dwordx4 v[134:135], off
	s_waitcnt vmcnt(8)
	s_waitcnt lgkmcnt(0)
	s_barrier
	s_setprio 1
	s_waitcnt lgkmcnt(0)
	v_mfma_f32_16x16x32_bf16 v[60:63], v[140:143], v[176:179], v[60:63]
	s_add_i32 s53, s53, 2
	v_mfma_f32_16x16x32_bf16 v[56:59], v[150:153], v[176:179], v[56:59]
	s_add_u32 s29, s29, 0x100
	v_mfma_f32_16x16x32_bf16 v[44:47], v[140:143], v[184:187], v[44:47]
	s_addc_u32 s39, s39, 0
	v_mfma_f32_16x16x32_bf16 v[40:43], v[150:153], v[184:187], v[40:43]
	s_mov_b64 s[62:63], s[64:65]
	v_mfma_f32_16x16x32_bf16 v[28:31], v[140:143], v[206:209], v[28:31]
	s_add_u32 s64, s62, 0x100
	v_mfma_f32_16x16x32_bf16 v[24:27], v[150:153], v[206:209], v[24:27]
	s_addc_u32 s65, s63, 0
	v_mfma_f32_16x16x32_bf16 v[12:15], v[140:143], v[214:217], v[12:15]
	s_add_i32 s3, 0, 0x10000
	v_mfma_f32_16x16x32_bf16 v[8:11], v[150:153], v[214:217], v[8:11]
	s_cmp_eq_u32 s53, 28
	v_mfma_f32_16x16x32_bf16 v[60:63], v[144:147], v[180:183], v[60:63]
	s_cselect_b32 s75, s22, s65
	v_mfma_f32_16x16x32_bf16 v[56:59], v[156:159], v[180:183], v[56:59]
	s_cselect_b32 s74, s23, s64
	v_mfma_f32_16x16x32_bf16 v[44:47], v[144:147], v[188:191], v[44:47]
	s_cselect_b32 s67, s5, s39
	v_mfma_f32_16x16x32_bf16 v[40:43], v[156:159], v[188:191], v[40:43]
	s_cselect_b32 s66, s28, s29
	v_mfma_f32_16x16x32_bf16 v[28:31], v[144:147], v[210:213], v[28:31]
	s_add_i32 s26, 0, 0x14000
	v_mfma_f32_16x16x32_bf16 v[24:27], v[156:159], v[210:213], v[24:27]
	v_mfma_f32_16x16x32_bf16 v[12:15], v[144:147], v[218:221], v[12:15]
	v_mfma_f32_16x16x32_bf16 v[8:11], v[156:159], v[218:221], v[8:11]
	s_setprio 0
	s_setprio 1
	v_mfma_f32_16x16x32_bf16 v[52:55], v[160:163], v[176:179], v[52:55]
	v_mfma_f32_16x16x32_bf16 v[48:51], v[168:171], v[176:179], v[48:51]
	v_mfma_f32_16x16x32_bf16 v[36:39], v[160:163], v[184:187], v[36:39]
	v_mfma_f32_16x16x32_bf16 v[32:35], v[168:171], v[184:187], v[32:35]
	v_mfma_f32_16x16x32_bf16 v[20:23], v[160:163], v[206:209], v[20:23]
	v_mfma_f32_16x16x32_bf16 v[16:19], v[168:171], v[206:209], v[16:19]
	v_mfma_f32_16x16x32_bf16 v[4:7], v[160:163], v[214:217], v[4:7]
	v_mfma_f32_16x16x32_bf16 v[0:3], v[168:171], v[214:217], v[0:3]
	v_mfma_f32_16x16x32_bf16 v[52:55], v[164:167], v[180:183], v[52:55]
	v_mfma_f32_16x16x32_bf16 v[48:51], v[172:175], v[180:183], v[48:51]
	v_mfma_f32_16x16x32_bf16 v[36:39], v[164:167], v[188:191], v[36:39]
	v_mfma_f32_16x16x32_bf16 v[32:35], v[172:175], v[188:191], v[32:35]
	v_mfma_f32_16x16x32_bf16 v[20:23], v[164:167], v[210:213], v[20:23]
	v_mfma_f32_16x16x32_bf16 v[16:19], v[172:175], v[210:213], v[16:19]
	v_mfma_f32_16x16x32_bf16 v[4:7], v[164:167], v[218:221], v[4:7]
	v_mfma_f32_16x16x32_bf16 v[0:3], v[172:175], v[218:221], v[0:3]
	s_setprio 0
	s_barrier
	s_cmp_gt_u32 s53, 29
	s_cbranch_scc0 .LBB0_115
	s_and_b64 vcc, exec, s[48:49]
	s_cbranch_vccz .LBB0_118
	s_barrier

; #define PG8_STAGE(bufoff, gbase, voff) do { _Pragma("unroll") for (int _i = 0; _i < 2; ++_i) \
;         __builtin_amdgcn_global_load_lds((const unsigned*)((const char*)(gbase) + (voff)[_i]), (PG8_LAS unsigned*)(lds + (bufoff) + ldsw + _i * 8192), 16, 0, 0); } while (0)
; #define PG8_LDA(dst, b, h) do { _Pragma("unroll") for (int m = 0; m < 4; ++m) _Pragma("unroll") for (int k = 0; k < 2; ++k) dst[m][k] = *(const PG8_LAS bf16x8*)(lds + PG8_SA(b, h) + aoff + m * 2048 + k * 1024); } while (0)
; #define PG8_LDB(dst, b, h) do { _Pragma("unroll") for (int n = 0; n < 2; ++n) _Pragma("unroll") for (int k = 0; k < 2; ++k) dst[n][k] = *(const PG8_LAS bf16x8*)(lds + PG8_SB(b, h) + boff + n * 2048 + k * 1024); } while (0)
; #define PG8_WAIT_V(n) asm volatile("s_waitcnt vmcnt(" #n ")" ::: "memory")
; #define PG8_WAIT_L(n) asm volatile("s_waitcnt lgkmcnt(" #n ")" ::: "memory")
; template <class Epi, class Sched, bool ALIGN_EPI = false, bool SP2 = false>
; __device__ __forceinline__ void gemm_phase(PG8_LAS unsigned char* lds, const Gemm g, const Sched& S, const Epi& E, int wave_s) {
;     ...
;         const bool has_next = S.next(ui + 1, nxt);
;         const char* nA = has_next ? (const char*)g.A + (size_t)nxt.pm * tstep : cA; const char* nB = has_next ? (const char*)g.Bt + (size_t)nxt.pn * tstep : cB;
;         for (int t = 0; t < nt; t += 2) {
;             const bool last = (t == nt - 2);
;             const char* a1 = cA + (size_t)(t + 1) * kstep;
;             const char* a2 = last ? nA : cA + (size_t)(t + 2) * kstep; const char* b2 = last ? nB : cB + (size_t)(t + 2) * kstep;
;             const char* a3 = a2 + kstep; const char* b3 = b2 + kstep;
;             if (last && has_next) S.a_ready(nxt);
;             if constexpr (SP2) {
;             PG8_LDB(B0, 0, 0); PG8_LDB(B1, 0, 1); PG8_SCHED; PG8_LDA(At, 0, 0); PG8_STAGE(PG8_SA(1, 1), a1 + hstep, voffA);
;             PG8_WAIT_V(8); PG8_WAIT_L(0); PG8_BAR; PG8_MMA(0, 0, At, B0); PG8_MMA(0, 1, At, B1); PG8_BAR; PG8_SCHED;
;     ...
;         { float zf_ = 0.f; asm volatile("" : "+v"(zf_)); const f32x4 zero4_ = {zf_, zf_, zf_, zf_};
; #pragma unroll
;         for (int a = 0; a < 2; ++a)
; #pragma unroll
;             for (int b = 0; b < 2; ++b)
; #pragma unroll
;                 for (int m = 0; m < 4; ++m)
; #pragma unroll
;                     for (int n = 0; n < 2; ++n) acc[a][b][m][n] = zero4_; }
.LBB0_386:
	s_ashr_i32 s53, s52, 31
	s_lshl_b64 s[22:23], s[52:53], 18
	s_add_u32 s54, s19, s22
	s_addc_u32 s55, s20, s23
	s_and_b64 s[22:23], s[40:41], exec
	s_cselect_b32 s22, s55, s61
	s_cselect_b32 s23, s54, s60
	s_ashr_i32 s49, s48, 31
	s_lshl_b64 s[56:57], s[48:49], 18
	s_add_u32 s56, s43, s56
	s_addc_u32 s57, s1, s57
	s_and_b64 s[64:65], s[40:41], exec
	s_cselect_b32 s5, s57, s63
	s_cselect_b32 s29, s56, s62
	s_add_u32 s60, s60, 0x20080
	s_addc_u32 s61, s61, 0
	s_add_u32 s49, s62, 0x100
	v_mov_b64_e32 v[6:7], v[2:3]
	v_mov_b64_e32 v[18:19], v[2:3]
	v_mov_b64_e32 v[22:23], v[2:3]
	v_mov_b64_e32 v[34:35], v[2:3]
	v_mov_b64_e32 v[38:39], v[2:3]
	v_mov_b64_e32 v[50:51], v[2:3]
	v_mov_b64_e32 v[54:55], v[2:3]
	v_mov_b64_e32 v[10:11], v[2:3]
	v_mov_b64_e32 v[14:15], v[2:3]
	v_mov_b64_e32 v[26:27], v[2:3]
	v_mov_b64_e32 v[30:31], v[2:3]
	v_mov_b64_e32 v[42:43], v[2:3]
	v_mov_b64_e32 v[46:47], v[2:3]
	v_mov_b64_e32 v[58:59], v[2:3]
	v_mov_b64_e32 v[62:63], v[2:3]
	v_mov_b64_e32 v[66:67], v[2:3]
	v_mov_b64_e32 v[70:71], v[2:3]
	v_mov_b64_e32 v[82:83], v[2:3]
	v_mov_b64_e32 v[86:87], v[2:3]
	v_mov_b64_e32 v[98:99], v[2:3]
	v_mov_b64_e32 v[102:103], v[2:3]
	v_mov_b64_e32 v[114:115], v[2:3]
	v_mov_b64_e32 v[118:119], v[2:3]
	v_mov_b64_e32 v[74:75], v[2:3]
	v_mov_b64_e32 v[78:79], v[2:3]
	v_mov_b64_e32 v[90:91], v[2:3]
	v_mov_b64_e32 v[94:95], v[2:3]
	v_mov_b64_e32 v[106:107], v[2:3]
	v_mov_b64_e32 v[110:111], v[2:3]
	v_mov_b64_e32 v[122:123], v[2:3]
	v_mov_b64_e32 v[126:127], v[2:3]
	s_addc_u32 s53, s63, 0
	s_mov_b32 s74, -2
	v_mov_b64_e32 v[4:5], v[0:1]
	v_mov_b64_e32 v[16:17], v[0:1]
	v_mov_b64_e32 v[20:21], v[0:1]
	v_mov_b64_e32 v[32:33], v[0:1]
	v_mov_b64_e32 v[36:37], v[0:1]
	v_mov_b64_e32 v[48:49], v[0:1]
	v_mov_b64_e32 v[52:53], v[0:1]
	v_mov_b64_e32 v[8:9], v[0:1]
	v_mov_b64_e32 v[12:13], v[0:1]
	v_mov_b64_e32 v[24:25], v[0:1]
	v_mov_b64_e32 v[28:29], v[0:1]
	v_mov_b64_e32 v[40:41], v[0:1]
	v_mov_b64_e32 v[44:45], v[0:1]
	v_mov_b64_e32 v[56:57], v[0:1]
	v_mov_b64_e32 v[60:61], v[0:1]
	v_mov_b64_e32 v[64:65], v[0:1]
	v_mov_b64_e32 v[68:69], v[0:1]
	v_mov_b64_e32 v[80:81], v[0:1]
	v_mov_b64_e32 v[84:85], v[0:1]
	v_mov_b64_e32 v[96:97], v[0:1]
	v_mov_b64_e32 v[100:101], v[0:1]
	v_mov_b64_e32 v[112:113], v[0:1]
	v_mov_b64_e32 v[116:117], v[0:1]
	v_mov_b64_e32 v[72:73], v[0:1]
	v_mov_b64_e32 v[76:77], v[0:1]
	v_mov_b64_e32 v[88:89], v[0:1]
	v_mov_b64_e32 v[92:93], v[0:1]
	v_mov_b64_e32 v[104:105], v[0:1]
	v_mov_b64_e32 v[108:109], v[0:1]
	v_mov_b64_e32 v[120:121], v[0:1]
	v_mov_b64_e32 v[124:125], v[0:1]
	s_add_u32 s36, s60, 0xfffe0080
	s_addc_u32 s37, s61, -1
	s_add_i32 s75, 0, 0x10000
	s_cmp_eq_u32 s74, 4
	s_cselect_b32 s65, s22, s37
	s_cselect_b32 s64, s23, s36
	s_cselect_b32 s63, s5, s53
	s_cselect_b32 s62, s29, s49
	s_add_i32 s36, 0, 0x14000
.LBB0_387:
	v_add_u32_e32 v138, s75, v141
	ds_read_b128 v[144:147], v138
	ds_read_b128 v[156:159], v138 offset:1024
	ds_read_b128 v[160:163], v138 offset:2048
	ds_read_b128 v[164:167], v138 offset:3072
	v_add_u32_e32 v138, s36, v141
	ds_read_b128 v[168:171], v138
	ds_read_b128 v[172:175], v138 offset:1024
	ds_read_b128 v[176:179], v138 offset:2048
	ds_read_b128 v[180:183], v138 offset:3072
	v_lshl_add_u64 v[138:139], s[60:61], 0, v[134:135]
	s_add_i32 m0, s25, 0xc000
	ds_read_b128 v[184:187], v143
	ds_read_b128 v[188:191], v143 offset:1024
	ds_read_b128 v[206:209], v143 offset:2048
	ds_read_b128 v[210:213], v143 offset:3072
	ds_read_b128 v[214:217], v143 offset:4096
	ds_read_b128 v[218:221], v143 offset:5120
	ds_read_b128 v[222:225], v143 offset:6144
	ds_read_b128 v[226:229], v143 offset:7168
	global_load_lds_dwordx4 v[138:139], off
	v_lshl_add_u64 v[138:139], s[60:61], 0, v[136:137]
	s_add_i32 m0, s25, 0xe000
	s_nop 0
	global_load_lds_dwordx4 v[138:139], off
	s_waitcnt vmcnt(8)
	s_waitcnt lgkmcnt(0)
	s_barrier
	s_setprio 1
	s_waitcnt lgkmcnt(0)
	v_mfma_f32_16x16x32_bf16 v[124:127], v[144:147], v[184:187], v[124:127]
	v_mfma_f32_16x16x32_bf16 v[120:123], v[160:163], v[184:187], v[120:123]
	v_mfma_f32_16x16x32_bf16 v[108:111], v[144:147], v[206:209], v[108:111]
	v_mfma_f32_16x16x32_bf16 v[104:107], v[160:163], v[206:209], v[104:107]
	v_mfma_f32_16x16x32_bf16 v[92:95], v[144:147], v[214:217], v[92:95]
	v_mfma_f32_16x16x32_bf16 v[88:91], v[160:163], v[214:217], v[88:91]
	v_mfma_f32_16x16x32_bf16 v[76:79], v[144:147], v[222:225], v[76:79]
	v_mfma_f32_16x16x32_bf16 v[72:75], v[160:163], v[222:225], v[72:75]
	v_mfma_f32_16x16x32_bf16 v[124:127], v[156:159], v[188:191], v[124:127]
	v_mfma_f32_16x16x32_bf16 v[120:123], v[164:167], v[188:191], v[120:123]
	v_mfma_f32_16x16x32_bf16 v[108:111], v[156:159], v[210:213], v[108:111]
	v_mfma_f32_16x16x32_bf16 v[104:107], v[164:167], v[210:213], v[104:107]
	v_mfma_f32_16x16x32_bf16 v[92:95], v[156:159], v[218:221], v[92:95]
	v_mfma_f32_16x16x32_bf16 v[88:91], v[164:167], v[218:221], v[88:91]
	v_mfma_f32_16x16x32_bf16 v[76:79], v[156:159], v[226:229], v[76:79]
	v_mfma_f32_16x16x32_bf16 v[72:75], v[164:167], v[226:229], v[72:75]
	s_setprio 0
	s_setprio 1
	v_mfma_f32_16x16x32_bf16 v[116:119], v[168:171], v[184:187], v[116:119]
	v_mfma_f32_16x16x32_bf16 v[112:115], v[176:179], v[184:187], v[112:115]
	v_mfma_f32_16x16x32_bf16 v[100:103], v[168:171], v[206:209], v[100:103]
	v_mfma_f32_16x16x32_bf16 v[96:99], v[176:179], v[206:209], v[96:99]
	v_mfma_f32_16x16x32_bf16 v[84:87], v[168:171], v[214:217], v[84:87]
	v_mfma_f32_16x16x32_bf16 v[80:83], v[176:179], v[214:217], v[80:83]
	v_mfma_f32_16x16x32_bf16 v[68:71], v[168:171], v[222:225], v[68:71]
	v_mfma_f32_16x16x32_bf16 v[64:67], v[176:179], v[222:225], v[64:67]
	v_mfma_f32_16x16x32_bf16 v[116:119], v[172:175], v[188:191], v[116:119]
	v_mfma_f32_16x16x32_bf16 v[112:115], v[180:183], v[188:191], v[112:115]
	v_mfma_f32_16x16x32_bf16 v[100:103], v[172:175], v[210:213], v[100:103]
	v_mfma_f32_16x16x32_bf16 v[96:99], v[180:183], v[210:213], v[96:99]
	v_mfma_f32_16x16x32_bf16 v[84:87], v[172:175], v[218:221], v[84:87]
	v_mfma_f32_16x16x32_bf16 v[80:83], v[180:183], v[218:221], v[80:83]
	v_mfma_f32_16x16x32_bf16 v[68:71], v[172:175], v[226:229], v[68:71]
	v_mfma_f32_16x16x32_bf16 v[64:67], v[180:183], v[226:229], v[64:67]
	s_setprio 0
	s_barrier
; #define PG8_STAGE(bufoff, gbase, voff) do { _Pragma("unroll") for (int _i = 0; _i < 2; ++_i) \
;         __builtin_amdgcn_global_load_lds((const unsigned*)((const char*)(gbase) + (voff)[_i]), (PG8_LAS unsigned*)(lds + (bufoff) + ldsw + _i * 8192), 16, 0, 0); } while (0)
; #define PG8_LDA(dst, b, h) do { _Pragma("unroll") for (int m = 0; m < 4; ++m) _Pragma("unroll") for (int k = 0; k < 2; ++k) dst[m][k] = *(const PG8_LAS bf16x8*)(lds + PG8_SA(b, h) + aoff + m * 2048 + k * 1024); } while (0)
; #define PG8_LDB(dst, b, h) do { _Pragma("unroll") for (int n = 0; n < 2; ++n) _Pragma("unroll") for (int k = 0; k < 2; ++k) dst[n][k] = *(const PG8_LAS bf16x8*)(lds + PG8_SB(b, h) + boff + n * 2048 + k * 1024); } while (0)
; #define PG8_MMA(ai, bj, At, Bt) do { __builtin_amdgcn_s_setprio(1); _Pragma("unroll") for (int m = 0; m < 4; ++m) _Pragma("unroll") for (int n = 0; n < 2; ++n) _Pragma("unroll") for (int k = 0; k < 2; ++k) \
;         acc[ai][bj][m][n] = __builtin_amdgcn_mfma_f32_16x16x32_bf16(Bt[n][k], At[m][k], acc[ai][bj][m][n], 0, 0, 0); __builtin_amdgcn_s_setprio(0); } while (0)
; #define PG8_WAIT_V(n) asm volatile("s_waitcnt vmcnt(" #n ")" ::: "memory")
; #define PG8_WAIT_L(n) asm volatile("s_waitcnt lgkmcnt(" #n ")" ::: "memory")
; #define PG8_BAR __builtin_amdgcn_s_barrier()
; #define PG8_SCHED __builtin_amdgcn_sched_barrier(0)
; template <class Epi, class Sched, bool ALIGN_EPI = false, bool SP2 = false>
; __device__ __forceinline__ void gemm_phase(PG8_LAS unsigned char* lds, const Gemm g, const Sched& S, const Epi& E, int wave_s) {
;     ...
;             PG8_LDA(At, 0, 1); PG8_STAGE(PG8_SB(0, 0), b2, voffB); PG8_STAGE(PG8_SB(0, 1), b2 + hstep, voffB); PG8_STAGE(PG8_SA(0, 0), a2, voffA);
;             PG8_WAIT_V(8); PG8_WAIT_L(0); PG8_BAR; PG8_MMA(1, 0, At, B0); PG8_MMA(1, 1, At, B1); PG8_BAR; PG8_SCHED;
;             PG8_LDB(B0, 1, 0); PG8_LDB(B1, 1, 1); PG8_SCHED; PG8_LDA(At, 1, 0); PG8_STAGE(PG8_SA(0, 1), a2 + hstep, voffA);
;             PG8_WAIT_V(8); PG8_WAIT_L(0); PG8_BAR; PG8_MMA(0, 0, At, B0); PG8_MMA(0, 1, At, B1); PG8_BAR; PG8_SCHED;
	s_add_i32 s37, s75, s21
	v_lshl_add_u64 v[138:139], s[62:63], 0, v[148:149]
	s_mov_b32 m0, s37
	ds_read_b128 v[184:187], v143 offset:16384
	ds_read_b128 v[188:191], v143 offset:17408
	ds_read_b128 v[206:209], v143 offset:18432
	ds_read_b128 v[210:213], v143 offset:19456
	ds_read_b128 v[214:217], v143 offset:20480
	ds_read_b128 v[218:221], v143 offset:21504
	ds_read_b128 v[222:225], v143 offset:22528
	ds_read_b128 v[226:229], v143 offset:23552
	global_load_lds_dwordx4 v[138:139], off
	s_add_i32 m0, s37, 0x2000
	s_add_u32 s76, s62, 0x20000
	v_lshl_add_u64 v[150:151], s[62:63], 0, v[128:129]
	s_addc_u32 s77, s63, 0
	s_add_i32 s36, s36, s21
	global_load_lds_dwordx4 v[150:151], off
	v_lshl_add_u64 v[152:153], s[76:77], 0, v[148:149]
	s_mov_b32 m0, s36
	v_lshl_add_u64 v[230:231], s[64:65], 0, v[130:131]
	global_load_lds_dwordx4 v[152:153], off
	v_lshl_add_u64 v[152:153], s[76:77], 0, v[128:129]
	s_add_i32 m0, s36, 0x2000
	s_nop 0
	global_load_lds_dwordx4 v[152:153], off
	v_lshl_add_u64 v[152:153], s[64:65], 0, v[132:133]
	s_mov_b32 m0, s25
	s_nop 0
	global_load_lds_dwordx4 v[152:153], off
	s_mov_b32 m0, s38
	s_nop 0
	global_load_lds_dwordx4 v[230:231], off
	s_waitcnt vmcnt(8)
	s_waitcnt lgkmcnt(0)
	s_barrier
	s_setprio 1
	s_waitcnt lgkmcnt(0)
	v_mfma_f32_16x16x32_bf16 v[60:63], v[144:147], v[184:187], v[60:63]
	v_mfma_f32_16x16x32_bf16 v[56:59], v[160:163], v[184:187], v[56:59]
	v_mfma_f32_16x16x32_bf16 v[44:47], v[144:147], v[206:209], v[44:47]
	v_mfma_f32_16x16x32_bf16 v[40:43], v[160:163], v[206:209], v[40:43]
	v_mfma_f32_16x16x32_bf16 v[28:31], v[144:147], v[214:217], v[28:31]
	v_mfma_f32_16x16x32_bf16 v[24:27], v[160:163], v[214:217], v[24:27]
	v_mfma_f32_16x16x32_bf16 v[12:15], v[144:147], v[222:225], v[12:15]
	v_mfma_f32_16x16x32_bf16 v[8:11], v[160:163], v[222:225], v[8:11]
	v_mfma_f32_16x16x32_bf16 v[60:63], v[156:159], v[188:191], v[60:63]
	v_mfma_f32_16x16x32_bf16 v[56:59], v[164:167], v[188:191], v[56:59]
	v_mfma_f32_16x16x32_bf16 v[44:47], v[156:159], v[210:213], v[44:47]
	v_mfma_f32_16x16x32_bf16 v[40:43], v[164:167], v[210:213], v[40:43]
	v_mfma_f32_16x16x32_bf16 v[28:31], v[156:159], v[218:221], v[28:31]
	v_mfma_f32_16x16x32_bf16 v[24:27], v[164:167], v[218:221], v[24:27]
	v_mfma_f32_16x16x32_bf16 v[12:15], v[156:159], v[226:229], v[12:15]
	v_mfma_f32_16x16x32_bf16 v[8:11], v[164:167], v[226:229], v[8:11]
	s_setprio 0
	s_setprio 1
	v_mfma_f32_16x16x32_bf16 v[52:55], v[168:171], v[184:187], v[52:55]
	v_mfma_f32_16x16x32_bf16 v[48:51], v[176:179], v[184:187], v[48:51]
	v_mfma_f32_16x16x32_bf16 v[36:39], v[168:171], v[206:209], v[36:39]
	v_mfma_f32_16x16x32_bf16 v[32:35], v[176:179], v[206:209], v[32:35]
	v_mfma_f32_16x16x32_bf16 v[20:23], v[168:171], v[214:217], v[20:23]
	v_mfma_f32_16x16x32_bf16 v[16:19], v[176:179], v[214:217], v[16:19]
	v_mfma_f32_16x16x32_bf16 v[4:7], v[168:171], v[222:225], v[4:7]
	v_mfma_f32_16x16x32_bf16 v[0:3], v[176:179], v[222:225], v[0:3]
	v_mfma_f32_16x16x32_bf16 v[52:55], v[172:175], v[188:191], v[52:55]
	v_mfma_f32_16x16x32_bf16 v[48:51], v[180:183], v[188:191], v[48:51]
	v_mfma_f32_16x16x32_bf16 v[36:39], v[172:175], v[210:213], v[36:39]
	v_mfma_f32_16x16x32_bf16 v[32:35], v[180:183], v[210:213], v[32:35]
	v_mfma_f32_16x16x32_bf16 v[20:23], v[172:175], v[218:221], v[20:23]
	v_mfma_f32_16x16x32_bf16 v[16:19], v[180:183], v[218:221], v[16:19]
	v_mfma_f32_16x16x32_bf16 v[4:7], v[172:175], v[226:229], v[4:7]
	v_mfma_f32_16x16x32_bf16 v[0:3], v[180:183], v[226:229], v[0:3]
	s_setprio 0
	s_barrier
	s_add_i32 s36, 0, 0x18000
	s_add_i32 s37, 0, 0x1c000
	v_add_u32_e32 v164, s36, v141
	v_add_u32_e32 v180, s37, v141
	ds_read_b128 v[144:147], v164
	ds_read_b128 v[156:159], v164 offset:1024
	ds_read_b128 v[160:163], v164 offset:2048
	ds_read_b128 v[164:167], v164 offset:3072
	ds_read_b128 v[168:171], v180
	ds_read_b128 v[172:175], v180 offset:1024
	ds_read_b128 v[176:179], v180 offset:2048
	ds_read_b128 v[180:183], v180 offset:3072
	s_add_u32 s64, s64, 0x20000
	s_addc_u32 s65, s65, 0
	s_mov_b32 m0, s39
	v_lshl_add_u64 v[232:233], s[64:65], 0, v[132:133]
	ds_read_b128 v[184:187], v143 offset:32768
	ds_read_b128 v[188:191], v143 offset:33792
	ds_read_b128 v[206:209], v143 offset:34816
	ds_read_b128 v[210:213], v143 offset:35840
	ds_read_b128 v[214:217], v143 offset:36864
	ds_read_b128 v[218:221], v143 offset:37888
	ds_read_b128 v[222:225], v143 offset:38912
	ds_read_b128 v[226:229], v143 offset:39936
	global_load_lds_dwordx4 v[232:233], off
	v_lshl_add_u64 v[232:233], s[64:65], 0, v[130:131]
	s_mov_b32 m0, s59
	s_nop 0
	global_load_lds_dwordx4 v[232:233], off
	s_waitcnt vmcnt(8)
	s_waitcnt lgkmcnt(0)
	s_barrier
; #define PG8_STAGE(bufoff, gbase, voff) do { _Pragma("unroll") for (int _i = 0; _i < 2; ++_i) \
;         __builtin_amdgcn_global_load_lds((const unsigned*)((const char*)(gbase) + (voff)[_i]), (PG8_LAS unsigned*)(lds + (bufoff) + ldsw + _i * 8192), 16, 0, 0); } while (0)
; #define PG8_LDA(dst, b, h) do { _Pragma("unroll") for (int m = 0; m < 4; ++m) _Pragma("unroll") for (int k = 0; k < 2; ++k) dst[m][k] = *(const PG8_LAS bf16x8*)(lds + PG8_SA(b, h) + aoff + m * 2048 + k * 1024); } while (0)
; #define PG8_MMA(ai, bj, At, Bt) do { __builtin_amdgcn_s_setprio(1); _Pragma("unroll") for (int m = 0; m < 4; ++m) _Pragma("unroll") for (int n = 0; n < 2; ++n) _Pragma("unroll") for (int k = 0; k < 2; ++k) \
;         acc[ai][bj][m][n] = __builtin_amdgcn_mfma_f32_16x16x32_bf16(Bt[n][k], At[m][k], acc[ai][bj][m][n], 0, 0, 0); __builtin_amdgcn_s_setprio(0); } while (0)
; #define PG8_WAIT_V(n) asm volatile("s_waitcnt vmcnt(" #n ")" ::: "memory")
; #define PG8_WAIT_L(n) asm volatile("s_waitcnt lgkmcnt(" #n ")" ::: "memory")
; #define PG8_BAR __builtin_amdgcn_s_barrier()
; #define PG8_SCHED __builtin_amdgcn_sched_barrier(0)
; template <class Epi, class Sched, bool ALIGN_EPI = false, bool SP2 = false>
; __device__ __forceinline__ void gemm_phase(PG8_LAS unsigned char* lds, const Gemm g, const Sched& S, const Epi& E, int wave_s) {
;     ...
;         for (int t = 0; t < nt; t += 2) {
;             const bool last = (t == nt - 2);
;             const char* a1 = cA + (size_t)(t + 1) * kstep;
;             const char* a2 = last ? nA : cA + (size_t)(t + 2) * kstep; const char* b2 = last ? nB : cB + (size_t)(t + 2) * kstep;
;             const char* a3 = a2 + kstep; const char* b3 = b2 + kstep;
;             if (last && has_next) S.a_ready(nxt);
;     ...
;             PG8_WAIT_V(8); PG8_WAIT_L(0); PG8_BAR; PG8_MMA(0, 0, At, B0); PG8_MMA(0, 1, At, B1); PG8_BAR; PG8_SCHED;
;             PG8_LDA(At, 1, 1); PG8_STAGE(PG8_SB(1, 0), b3, voffB); PG8_STAGE(PG8_SB(1, 1), b3 + hstep, voffB); PG8_STAGE(PG8_SA(1, 0), a3, voffA);
;             PG8_WAIT_V(8); PG8_WAIT_L(0); PG8_BAR; PG8_MMA(1, 0, At, B0); PG8_MMA(1, 1, At, B1); PG8_BAR; PG8_SCHED;
	s_setprio 1
	s_waitcnt lgkmcnt(0)
	v_mfma_f32_16x16x32_bf16 v[124:127], v[144:147], v[184:187], v[124:127]
	v_mfma_f32_16x16x32_bf16 v[120:123], v[160:163], v[184:187], v[120:123]
	v_mfma_f32_16x16x32_bf16 v[108:111], v[144:147], v[206:209], v[108:111]
	v_mfma_f32_16x16x32_bf16 v[104:107], v[160:163], v[206:209], v[104:107]
	v_mfma_f32_16x16x32_bf16 v[92:95], v[144:147], v[214:217], v[92:95]
	v_mfma_f32_16x16x32_bf16 v[88:91], v[160:163], v[214:217], v[88:91]
	v_mfma_f32_16x16x32_bf16 v[76:79], v[144:147], v[222:225], v[76:79]
	v_mfma_f32_16x16x32_bf16 v[72:75], v[160:163], v[222:225], v[72:75]
	v_mfma_f32_16x16x32_bf16 v[124:127], v[156:159], v[188:191], v[124:127]
	v_mfma_f32_16x16x32_bf16 v[120:123], v[164:167], v[188:191], v[120:123]
	v_mfma_f32_16x16x32_bf16 v[108:111], v[156:159], v[210:213], v[108:111]
	v_mfma_f32_16x16x32_bf16 v[104:107], v[164:167], v[210:213], v[104:107]
	v_mfma_f32_16x16x32_bf16 v[92:95], v[156:159], v[218:221], v[92:95]
	v_mfma_f32_16x16x32_bf16 v[88:91], v[164:167], v[218:221], v[88:91]
	v_mfma_f32_16x16x32_bf16 v[76:79], v[156:159], v[226:229], v[76:79]
	v_mfma_f32_16x16x32_bf16 v[72:75], v[164:167], v[226:229], v[72:75]
	s_setprio 0
	s_setprio 1
	v_mfma_f32_16x16x32_bf16 v[116:119], v[168:171], v[184:187], v[116:119]
	v_mfma_f32_16x16x32_bf16 v[112:115], v[176:179], v[184:187], v[112:115]
	v_mfma_f32_16x16x32_bf16 v[100:103], v[168:171], v[206:209], v[100:103]
	v_mfma_f32_16x16x32_bf16 v[96:99], v[176:179], v[206:209], v[96:99]
	v_mfma_f32_16x16x32_bf16 v[84:87], v[168:171], v[214:217], v[84:87]
	v_mfma_f32_16x16x32_bf16 v[80:83], v[176:179], v[214:217], v[80:83]
	v_mfma_f32_16x16x32_bf16 v[68:71], v[168:171], v[222:225], v[68:71]
	v_mfma_f32_16x16x32_bf16 v[64:67], v[176:179], v[222:225], v[64:67]
	v_mfma_f32_16x16x32_bf16 v[116:119], v[172:175], v[188:191], v[116:119]
	v_mfma_f32_16x16x32_bf16 v[112:115], v[180:183], v[188:191], v[112:115]
	v_mfma_f32_16x16x32_bf16 v[100:103], v[172:175], v[210:213], v[100:103]
	v_mfma_f32_16x16x32_bf16 v[96:99], v[180:183], v[210:213], v[96:99]
	v_mfma_f32_16x16x32_bf16 v[84:87], v[172:175], v[218:221], v[84:87]
	v_mfma_f32_16x16x32_bf16 v[80:83], v[180:183], v[218:221], v[80:83]
	v_mfma_f32_16x16x32_bf16 v[68:71], v[172:175], v[226:229], v[68:71]
	v_mfma_f32_16x16x32_bf16 v[64:67], v[180:183], v[226:229], v[64:67]
	s_setprio 0
	s_barrier
	s_add_i32 s36, s36, s21
	v_lshl_add_u64 v[138:139], v[138:139], 0, s[34:35]
	s_mov_b32 m0, s36
	ds_read_b128 v[184:187], v143 offset:49152
	ds_read_b128 v[188:191], v143 offset:50176
	ds_read_b128 v[206:209], v143 offset:51200
	ds_read_b128 v[210:213], v143 offset:52224
	ds_read_b128 v[214:217], v143 offset:53248
	ds_read_b128 v[218:221], v143 offset:54272
	ds_read_b128 v[222:225], v143 offset:55296
	ds_read_b128 v[226:229], v143 offset:56320
	global_load_lds_dwordx4 v[138:139], off
	s_add_i32 m0, s36, 0x2000
	s_add_u32 s62, s62, 0x20080
	v_lshl_add_u64 v[138:139], v[150:151], 0, s[34:35]
	s_addc_u32 s63, s63, 0
	s_add_i32 s36, s37, s21
	global_load_lds_dwordx4 v[138:139], off
	v_lshl_add_u64 v[138:139], s[62:63], 0, v[148:149]
	s_mov_b32 m0, s36
	s_nop 0
	global_load_lds_dwordx4 v[138:139], off
	v_lshl_add_u64 v[138:139], s[62:63], 0, v[128:129]
	s_add_i32 m0, s36, 0x2000
	s_nop 0
	global_load_lds_dwordx4 v[138:139], off
	v_lshl_add_u64 v[138:139], v[152:153], 0, s[34:35]
	s_mov_b32 m0, s66
	s_nop 0
	global_load_lds_dwordx4 v[138:139], off
	v_lshl_add_u64 v[138:139], v[230:231], 0, s[34:35]
	s_mov_b32 m0, s67
	s_nop 0
	global_load_lds_dwordx4 v[138:139], off
	s_waitcnt vmcnt(8)
	s_waitcnt lgkmcnt(0)
	s_barrier
	s_setprio 1
	s_waitcnt lgkmcnt(0)
	v_mfma_f32_16x16x32_bf16 v[60:63], v[144:147], v[184:187], v[60:63]
	s_add_i32 s74, s74, 2
	v_mfma_f32_16x16x32_bf16 v[56:59], v[160:163], v[184:187], v[56:59]
	s_add_u32 s60, s60, 0x100
	v_mfma_f32_16x16x32_bf16 v[44:47], v[144:147], v[206:209], v[44:47]
	s_addc_u32 s61, s61, 0
	v_mfma_f32_16x16x32_bf16 v[40:43], v[160:163], v[206:209], v[40:43]
	s_add_u32 s49, s49, 0x100
	v_mfma_f32_16x16x32_bf16 v[28:31], v[144:147], v[214:217], v[28:31]
	s_addc_u32 s53, s53, 0
	v_mfma_f32_16x16x32_bf16 v[24:27], v[160:163], v[214:217], v[24:27]
	s_add_u32 s36, s60, 0xfffe0080
	v_mfma_f32_16x16x32_bf16 v[12:15], v[144:147], v[222:225], v[12:15]
	s_addc_u32 s37, s61, -1
	v_mfma_f32_16x16x32_bf16 v[8:11], v[160:163], v[222:225], v[8:11]
	s_add_i32 s75, 0, 0x10000
	v_mfma_f32_16x16x32_bf16 v[60:63], v[156:159], v[188:191], v[60:63]
	s_cmp_eq_u32 s74, 4
	v_mfma_f32_16x16x32_bf16 v[56:59], v[164:167], v[188:191], v[56:59]
	s_cselect_b32 s65, s22, s37
	v_mfma_f32_16x16x32_bf16 v[44:47], v[156:159], v[210:213], v[44:47]
	s_cselect_b32 s64, s23, s36
	v_mfma_f32_16x16x32_bf16 v[40:43], v[164:167], v[210:213], v[40:43]
	s_cselect_b32 s63, s5, s53
	v_mfma_f32_16x16x32_bf16 v[28:31], v[156:159], v[218:221], v[28:31]
	s_cselect_b32 s62, s29, s49
	v_mfma_f32_16x16x32_bf16 v[24:27], v[164:167], v[218:221], v[24:27]
	s_add_i32 s36, 0, 0x14000
	v_mfma_f32_16x16x32_bf16 v[12:15], v[156:159], v[226:229], v[12:15]
	v_mfma_f32_16x16x32_bf16 v[8:11], v[164:167], v[226:229], v[8:11]
	s_setprio 0
	s_setprio 1
	v_mfma_f32_16x16x32_bf16 v[52:55], v[168:171], v[184:187], v[52:55]
	v_mfma_f32_16x16x32_bf16 v[48:51], v[176:179], v[184:187], v[48:51]
	v_mfma_f32_16x16x32_bf16 v[36:39], v[168:171], v[206:209], v[36:39]
	v_mfma_f32_16x16x32_bf16 v[32:35], v[176:179], v[206:209], v[32:35]
	v_mfma_f32_16x16x32_bf16 v[20:23], v[168:171], v[214:217], v[20:23]
	v_mfma_f32_16x16x32_bf16 v[16:19], v[176:179], v[214:217], v[16:19]
	v_mfma_f32_16x16x32_bf16 v[4:7], v[168:171], v[222:225], v[4:7]
	v_mfma_f32_16x16x32_bf16 v[0:3], v[176:179], v[222:225], v[0:3]
	v_mfma_f32_16x16x32_bf16 v[52:55], v[172:175], v[188:191], v[52:55]
	v_mfma_f32_16x16x32_bf16 v[48:51], v[180:183], v[188:191], v[48:51]
	v_mfma_f32_16x16x32_bf16 v[36:39], v[172:175], v[210:213], v[36:39]
	v_mfma_f32_16x16x32_bf16 v[32:35], v[180:183], v[210:213], v[32:35]
	v_mfma_f32_16x16x32_bf16 v[20:23], v[172:175], v[218:221], v[20:23]
	v_mfma_f32_16x16x32_bf16 v[16:19], v[180:183], v[218:221], v[16:19]
	v_mfma_f32_16x16x32_bf16 v[4:7], v[172:175], v[226:229], v[4:7]
	v_mfma_f32_16x16x32_bf16 v[0:3], v[180:183], v[226:229], v[0:3]
	s_setprio 0
	s_barrier
	s_cmp_gt_u32 s74, 5
	s_cbranch_scc0 .LBB0_387
	s_and_b64 vcc, exec, s[46:47]
	s_cbranch_vccz .LBB0_390
	s_barrier

; #define PG8_STAGE(bufoff, gbase, voff) do { _Pragma("unroll") for (int _i = 0; _i < 2; ++_i) \
;         __builtin_amdgcn_global_load_lds((const unsigned*)((const char*)(gbase) + (voff)[_i]), (PG8_LAS unsigned*)(lds + (bufoff) + ldsw + _i * 8192), 16, 0, 0); } while (0)
; #define PG8_LDA(dst, b, h) do { _Pragma("unroll") for (int m = 0; m < 4; ++m) _Pragma("unroll") for (int k = 0; k < 2; ++k) dst[m][k] = *(const PG8_LAS bf16x8*)(lds + PG8_SA(b, h) + aoff + m * 2048 + k * 1024); } while (0)
; #define PG8_LDB(dst, b, h) do { _Pragma("unroll") for (int n = 0; n < 2; ++n) _Pragma("unroll") for (int k = 0; k < 2; ++k) dst[n][k] = *(const PG8_LAS bf16x8*)(lds + PG8_SB(b, h) + boff + n * 2048 + k * 1024); } while (0)
; #define PG8_WAIT_V(n) asm volatile("s_waitcnt vmcnt(" #n ")" ::: "memory")
; #define PG8_WAIT_L(n) asm volatile("s_waitcnt lgkmcnt(" #n ")" ::: "memory")
; template <class Epi, class Sched, bool ALIGN_EPI = false, bool SP2 = false>
; __device__ __forceinline__ void gemm_phase(PG8_LAS unsigned char* lds, const Gemm g, const Sched& S, const Epi& E, int wave_s) {
;     ...
;         const bool has_next = S.next(ui + 1, nxt);
;         const char* nA = has_next ? (const char*)g.A + (size_t)nxt.pm * tstep : cA; const char* nB = has_next ? (const char*)g.Bt + (size_t)nxt.pn * tstep : cB;
;         for (int t = 0; t < nt; t += 2) {
;             const bool last = (t == nt - 2);
;             const char* a1 = cA + (size_t)(t + 1) * kstep;
;             const char* a2 = last ? nA : cA + (size_t)(t + 2) * kstep; const char* b2 = last ? nB : cB + (size_t)(t + 2) * kstep;
;             const char* a3 = a2 + kstep; const char* b3 = b2 + kstep;
;             if (last && has_next) S.a_ready(nxt);
;             if constexpr (SP2) {
;             PG8_LDB(B0, 0, 0); PG8_LDB(B1, 0, 1); PG8_SCHED; PG8_LDA(At, 0, 0); PG8_STAGE(PG8_SA(1, 1), a1 + hstep, voffA);
;             PG8_WAIT_V(8); PG8_WAIT_L(0); PG8_BAR; PG8_MMA(0, 0, At, B0); PG8_MMA(0, 1, At, B1); PG8_BAR; PG8_SCHED;
;     ...
;         { float zf_ = 0.f; asm volatile("" : "+v"(zf_)); const f32x4 zero4_ = {zf_, zf_, zf_, zf_};
; #pragma unroll
;         for (int a = 0; a < 2; ++a)
; #pragma unroll
;             for (int b = 0; b < 2; ++b)
; #pragma unroll
;                 for (int m = 0; m < 4; ++m)
; #pragma unroll
;                     for (int n = 0; n < 2; ++n) acc[a][b][m][n] = zero4_; }
.LBB0_452:
	s_ashr_i32 s49, s48, 31
	s_lshl_b64 s[22:23], s[48:49], 20
	s_add_u32 s52, s9, s22
	s_addc_u32 s53, s11, s23
	s_and_b64 s[22:23], s[40:41], exec
	s_cselect_b32 s22, s53, s59
	s_cselect_b32 s23, s52, s58
	s_ashr_i32 s47, s46, 31
	s_lshl_b64 s[28:29], s[46:47], 20
	v_readlane_b32 s0, v254, 63
	s_add_u32 s54, s0, s28
	v_readlane_b32 s0, v255, 2
	s_addc_u32 s55, s0, s29
	s_and_b64 s[28:29], s[40:41], exec
	s_cselect_b32 s5, s55, s61
	s_cselect_b32 s28, s54, s60
	s_add_u32 s58, s58, 0x80080
	s_addc_u32 s59, s59, 0
	s_add_u32 s29, s60, 0x100
	v_mov_b64_e32 v[6:7], v[2:3]
	v_mov_b64_e32 v[18:19], v[2:3]
	v_mov_b64_e32 v[22:23], v[2:3]
	v_mov_b64_e32 v[34:35], v[2:3]
	v_mov_b64_e32 v[38:39], v[2:3]
	v_mov_b64_e32 v[50:51], v[2:3]
	v_mov_b64_e32 v[54:55], v[2:3]
	v_mov_b64_e32 v[10:11], v[2:3]
	v_mov_b64_e32 v[14:15], v[2:3]
	v_mov_b64_e32 v[26:27], v[2:3]
	v_mov_b64_e32 v[30:31], v[2:3]
	v_mov_b64_e32 v[42:43], v[2:3]
	v_mov_b64_e32 v[46:47], v[2:3]
	v_mov_b64_e32 v[58:59], v[2:3]
	v_mov_b64_e32 v[62:63], v[2:3]
	v_mov_b64_e32 v[66:67], v[2:3]
	v_mov_b64_e32 v[70:71], v[2:3]
	v_mov_b64_e32 v[82:83], v[2:3]
	v_mov_b64_e32 v[86:87], v[2:3]
	v_mov_b64_e32 v[98:99], v[2:3]
	v_mov_b64_e32 v[102:103], v[2:3]
	v_mov_b64_e32 v[114:115], v[2:3]
	v_mov_b64_e32 v[118:119], v[2:3]
	v_mov_b64_e32 v[74:75], v[2:3]
	v_mov_b64_e32 v[78:79], v[2:3]
	v_mov_b64_e32 v[90:91], v[2:3]
	v_mov_b64_e32 v[94:95], v[2:3]
	v_mov_b64_e32 v[106:107], v[2:3]
	v_mov_b64_e32 v[110:111], v[2:3]
	v_mov_b64_e32 v[122:123], v[2:3]
	v_mov_b64_e32 v[126:127], v[2:3]
	s_addc_u32 s47, s61, 0
	s_mov_b32 s49, -2
	v_mov_b64_e32 v[4:5], v[0:1]
	v_mov_b64_e32 v[16:17], v[0:1]
	v_mov_b64_e32 v[20:21], v[0:1]
	v_mov_b64_e32 v[32:33], v[0:1]
	v_mov_b64_e32 v[36:37], v[0:1]
	v_mov_b64_e32 v[48:49], v[0:1]
	v_mov_b64_e32 v[52:53], v[0:1]
	v_mov_b64_e32 v[8:9], v[0:1]
	v_mov_b64_e32 v[12:13], v[0:1]
	v_mov_b64_e32 v[24:25], v[0:1]
	v_mov_b64_e32 v[28:29], v[0:1]
	v_mov_b64_e32 v[40:41], v[0:1]
	v_mov_b64_e32 v[44:45], v[0:1]
	v_mov_b64_e32 v[56:57], v[0:1]
	v_mov_b64_e32 v[60:61], v[0:1]
	v_mov_b64_e32 v[64:65], v[0:1]
	v_mov_b64_e32 v[68:69], v[0:1]
	v_mov_b64_e32 v[80:81], v[0:1]
	v_mov_b64_e32 v[84:85], v[0:1]
	v_mov_b64_e32 v[96:97], v[0:1]
	v_mov_b64_e32 v[100:101], v[0:1]
	v_mov_b64_e32 v[112:113], v[0:1]
	v_mov_b64_e32 v[116:117], v[0:1]
	v_mov_b64_e32 v[72:73], v[0:1]
	v_mov_b64_e32 v[76:77], v[0:1]
	v_mov_b64_e32 v[88:89], v[0:1]
	v_mov_b64_e32 v[92:93], v[0:1]
	v_mov_b64_e32 v[104:105], v[0:1]
	v_mov_b64_e32 v[108:109], v[0:1]
	v_mov_b64_e32 v[120:121], v[0:1]
	v_mov_b64_e32 v[124:125], v[0:1]
	s_add_u32 s36, s58, 0xfff80080
	s_addc_u32 s37, s59, -1
	s_add_i32 s66, 0, 0x10000
	s_cmp_eq_u32 s49, 28
	s_cselect_b32 s63, s22, s37
	s_cselect_b32 s62, s23, s36
	s_cselect_b32 s61, s5, s47
	s_cselect_b32 s60, s28, s29
	s_add_i32 s36, 0, 0x14000
.LBB0_453:
	v_add_u32_e32 v138, s66, v141
	ds_read_b128 v[144:147], v138
	ds_read_b128 v[156:159], v138 offset:1024
	ds_read_b128 v[160:163], v138 offset:2048
	ds_read_b128 v[164:167], v138 offset:3072
	v_add_u32_e32 v138, s36, v141
	ds_read_b128 v[168:171], v138
	ds_read_b128 v[172:175], v138 offset:1024
	ds_read_b128 v[176:179], v138 offset:2048
	ds_read_b128 v[180:183], v138 offset:3072
	v_lshl_add_u64 v[138:139], s[58:59], 0, v[134:135]
	s_add_i32 m0, s19, 0xc000
	ds_read_b128 v[184:187], v143
	ds_read_b128 v[188:191], v143 offset:1024
	ds_read_b128 v[206:209], v143 offset:2048
	ds_read_b128 v[210:213], v143 offset:3072
	ds_read_b128 v[214:217], v143 offset:4096
	ds_read_b128 v[218:221], v143 offset:5120
	ds_read_b128 v[222:225], v143 offset:6144
	ds_read_b128 v[226:229], v143 offset:7168
	global_load_lds_dwordx4 v[138:139], off
	v_lshl_add_u64 v[138:139], s[58:59], 0, v[136:137]
	s_add_i32 m0, s19, 0xe000
	s_nop 0
	global_load_lds_dwordx4 v[138:139], off
	s_waitcnt vmcnt(8)
	s_waitcnt lgkmcnt(0)
	s_barrier
	s_setprio 1
	s_waitcnt lgkmcnt(0)
	v_mfma_f32_16x16x32_bf16 v[124:127], v[144:147], v[184:187], v[124:127]
	v_mfma_f32_16x16x32_bf16 v[120:123], v[160:163], v[184:187], v[120:123]
	v_mfma_f32_16x16x32_bf16 v[108:111], v[144:147], v[206:209], v[108:111]
	v_mfma_f32_16x16x32_bf16 v[104:107], v[160:163], v[206:209], v[104:107]
	v_mfma_f32_16x16x32_bf16 v[92:95], v[144:147], v[214:217], v[92:95]
	v_mfma_f32_16x16x32_bf16 v[88:91], v[160:163], v[214:217], v[88:91]
	v_mfma_f32_16x16x32_bf16 v[76:79], v[144:147], v[222:225], v[76:79]
	v_mfma_f32_16x16x32_bf16 v[72:75], v[160:163], v[222:225], v[72:75]
	v_mfma_f32_16x16x32_bf16 v[124:127], v[156:159], v[188:191], v[124:127]
	v_mfma_f32_16x16x32_bf16 v[120:123], v[164:167], v[188:191], v[120:123]
	v_mfma_f32_16x16x32_bf16 v[108:111], v[156:159], v[210:213], v[108:111]
	v_mfma_f32_16x16x32_bf16 v[104:107], v[164:167], v[210:213], v[104:107]
	v_mfma_f32_16x16x32_bf16 v[92:95], v[156:159], v[218:221], v[92:95]
	v_mfma_f32_16x16x32_bf16 v[88:91], v[164:167], v[218:221], v[88:91]
	v_mfma_f32_16x16x32_bf16 v[76:79], v[156:159], v[226:229], v[76:79]
	v_mfma_f32_16x16x32_bf16 v[72:75], v[164:167], v[226:229], v[72:75]
	s_setprio 0
	s_setprio 1
	v_mfma_f32_16x16x32_bf16 v[116:119], v[168:171], v[184:187], v[116:119]
	v_mfma_f32_16x16x32_bf16 v[112:115], v[176:179], v[184:187], v[112:115]
	v_mfma_f32_16x16x32_bf16 v[100:103], v[168:171], v[206:209], v[100:103]
	v_mfma_f32_16x16x32_bf16 v[96:99], v[176:179], v[206:209], v[96:99]
	v_mfma_f32_16x16x32_bf16 v[84:87], v[168:171], v[214:217], v[84:87]
	v_mfma_f32_16x16x32_bf16 v[80:83], v[176:179], v[214:217], v[80:83]
	v_mfma_f32_16x16x32_bf16 v[68:71], v[168:171], v[222:225], v[68:71]
	v_mfma_f32_16x16x32_bf16 v[64:67], v[176:179], v[222:225], v[64:67]
	v_mfma_f32_16x16x32_bf16 v[116:119], v[172:175], v[188:191], v[116:119]
	v_mfma_f32_16x16x32_bf16 v[112:115], v[180:183], v[188:191], v[112:115]
	v_mfma_f32_16x16x32_bf16 v[100:103], v[172:175], v[210:213], v[100:103]
	v_mfma_f32_16x16x32_bf16 v[96:99], v[180:183], v[210:213], v[96:99]
	v_mfma_f32_16x16x32_bf16 v[84:87], v[172:175], v[218:221], v[84:87]
	v_mfma_f32_16x16x32_bf16 v[80:83], v[180:183], v[218:221], v[80:83]
	v_mfma_f32_16x16x32_bf16 v[68:71], v[172:175], v[226:229], v[68:71]
	v_mfma_f32_16x16x32_bf16 v[64:67], v[180:183], v[226:229], v[64:67]
	s_setprio 0
	s_barrier
; #define PG8_STAGE(bufoff, gbase, voff) do { _Pragma("unroll") for (int _i = 0; _i < 2; ++_i) \
;         __builtin_amdgcn_global_load_lds((const unsigned*)((const char*)(gbase) + (voff)[_i]), (PG8_LAS unsigned*)(lds + (bufoff) + ldsw + _i * 8192), 16, 0, 0); } while (0)
; #define PG8_LDA(dst, b, h) do { _Pragma("unroll") for (int m = 0; m < 4; ++m) _Pragma("unroll") for (int k = 0; k < 2; ++k) dst[m][k] = *(const PG8_LAS bf16x8*)(lds + PG8_SA(b, h) + aoff + m * 2048 + k * 1024); } while (0)
; #define PG8_LDB(dst, b, h) do { _Pragma("unroll") for (int n = 0; n < 2; ++n) _Pragma("unroll") for (int k = 0; k < 2; ++k) dst[n][k] = *(const PG8_LAS bf16x8*)(lds + PG8_SB(b, h) + boff + n * 2048 + k * 1024); } while (0)
; #define PG8_MMA(ai, bj, At, Bt) do { __builtin_amdgcn_s_setprio(1); _Pragma("unroll") for (int m = 0; m < 4; ++m) _Pragma("unroll") for (int n = 0; n < 2; ++n) _Pragma("unroll") for (int k = 0; k < 2; ++k) \
;         acc[ai][bj][m][n] = __builtin_amdgcn_mfma_f32_16x16x32_bf16(Bt[n][k], At[m][k], acc[ai][bj][m][n], 0, 0, 0); __builtin_amdgcn_s_setprio(0); } while (0)
; #define PG8_WAIT_V(n) asm volatile("s_waitcnt vmcnt(" #n ")" ::: "memory")
; #define PG8_WAIT_L(n) asm volatile("s_waitcnt lgkmcnt(" #n ")" ::: "memory")
; #define PG8_BAR __builtin_amdgcn_s_barrier()
; #define PG8_SCHED __builtin_amdgcn_sched_barrier(0)
; template <class Epi, class Sched, bool ALIGN_EPI = false, bool SP2 = false>
; __device__ __forceinline__ void gemm_phase(PG8_LAS unsigned char* lds, const Gemm g, const Sched& S, const Epi& E, int wave_s) {
;     ...
;             PG8_LDA(At, 0, 1); PG8_STAGE(PG8_SB(0, 0), b2, voffB); PG8_STAGE(PG8_SB(0, 1), b2 + hstep, voffB); PG8_STAGE(PG8_SA(0, 0), a2, voffA);
;             PG8_WAIT_V(8); PG8_WAIT_L(0); PG8_BAR; PG8_MMA(1, 0, At, B0); PG8_MMA(1, 1, At, B1); PG8_BAR; PG8_SCHED;
;             PG8_LDB(B0, 1, 0); PG8_LDB(B1, 1, 1); PG8_SCHED; PG8_LDA(At, 1, 0); PG8_STAGE(PG8_SA(0, 1), a2 + hstep, voffA);
;             PG8_WAIT_V(8); PG8_WAIT_L(0); PG8_BAR; PG8_MMA(0, 0, At, B0); PG8_MMA(0, 1, At, B1); PG8_BAR; PG8_SCHED;
	s_add_i32 s37, s66, s18
	v_lshl_add_u64 v[138:139], s[60:61], 0, v[148:149]
	s_mov_b32 m0, s37
	ds_read_b128 v[184:187], v143 offset:16384
	ds_read_b128 v[188:191], v143 offset:17408
	ds_read_b128 v[206:209], v143 offset:18432
	ds_read_b128 v[210:213], v143 offset:19456
	ds_read_b128 v[214:217], v143 offset:20480
	ds_read_b128 v[218:221], v143 offset:21504
	ds_read_b128 v[222:225], v143 offset:22528
	ds_read_b128 v[226:229], v143 offset:23552
	global_load_lds_dwordx4 v[138:139], off
	s_add_i32 m0, s37, 0x2000
	s_add_u32 s66, s60, 0x80000
	v_lshl_add_u64 v[150:151], s[60:61], 0, v[128:129]
	s_addc_u32 s67, s61, 0
	s_add_i32 s36, s36, s18
	global_load_lds_dwordx4 v[150:151], off
	v_lshl_add_u64 v[152:153], s[66:67], 0, v[148:149]
	s_mov_b32 m0, s36
	v_lshl_add_u64 v[230:231], s[62:63], 0, v[130:131]
	global_load_lds_dwordx4 v[152:153], off
	v_lshl_add_u64 v[152:153], s[66:67], 0, v[128:129]
	s_add_i32 m0, s36, 0x2000
	s_nop 0
	global_load_lds_dwordx4 v[152:153], off
	v_lshl_add_u64 v[152:153], s[62:63], 0, v[132:133]
	s_mov_b32 m0, s19
	s_nop 0
	global_load_lds_dwordx4 v[152:153], off
	s_mov_b32 m0, s24
	s_nop 0
	global_load_lds_dwordx4 v[230:231], off
	s_waitcnt vmcnt(8)
	s_waitcnt lgkmcnt(0)
	s_barrier
	s_setprio 1
	s_waitcnt lgkmcnt(0)
	v_mfma_f32_16x16x32_bf16 v[60:63], v[144:147], v[184:187], v[60:63]
	v_mfma_f32_16x16x32_bf16 v[56:59], v[160:163], v[184:187], v[56:59]
	v_mfma_f32_16x16x32_bf16 v[44:47], v[144:147], v[206:209], v[44:47]
	v_mfma_f32_16x16x32_bf16 v[40:43], v[160:163], v[206:209], v[40:43]
	v_mfma_f32_16x16x32_bf16 v[28:31], v[144:147], v[214:217], v[28:31]
	v_mfma_f32_16x16x32_bf16 v[24:27], v[160:163], v[214:217], v[24:27]
	v_mfma_f32_16x16x32_bf16 v[12:15], v[144:147], v[222:225], v[12:15]
	v_mfma_f32_16x16x32_bf16 v[8:11], v[160:163], v[222:225], v[8:11]
	v_mfma_f32_16x16x32_bf16 v[60:63], v[156:159], v[188:191], v[60:63]
	v_mfma_f32_16x16x32_bf16 v[56:59], v[164:167], v[188:191], v[56:59]
	v_mfma_f32_16x16x32_bf16 v[44:47], v[156:159], v[210:213], v[44:47]
	v_mfma_f32_16x16x32_bf16 v[40:43], v[164:167], v[210:213], v[40:43]
	v_mfma_f32_16x16x32_bf16 v[28:31], v[156:159], v[218:221], v[28:31]
	v_mfma_f32_16x16x32_bf16 v[24:27], v[164:167], v[218:221], v[24:27]
	v_mfma_f32_16x16x32_bf16 v[12:15], v[156:159], v[226:229], v[12:15]
	v_mfma_f32_16x16x32_bf16 v[8:11], v[164:167], v[226:229], v[8:11]
	s_setprio 0
	s_setprio 1
	v_mfma_f32_16x16x32_bf16 v[52:55], v[168:171], v[184:187], v[52:55]
	v_mfma_f32_16x16x32_bf16 v[48:51], v[176:179], v[184:187], v[48:51]
	v_mfma_f32_16x16x32_bf16 v[36:39], v[168:171], v[206:209], v[36:39]
	v_mfma_f32_16x16x32_bf16 v[32:35], v[176:179], v[206:209], v[32:35]
	v_mfma_f32_16x16x32_bf16 v[20:23], v[168:171], v[214:217], v[20:23]
	v_mfma_f32_16x16x32_bf16 v[16:19], v[176:179], v[214:217], v[16:19]
	v_mfma_f32_16x16x32_bf16 v[4:7], v[168:171], v[222:225], v[4:7]
	v_mfma_f32_16x16x32_bf16 v[0:3], v[176:179], v[222:225], v[0:3]
	v_mfma_f32_16x16x32_bf16 v[52:55], v[172:175], v[188:191], v[52:55]
	v_mfma_f32_16x16x32_bf16 v[48:51], v[180:183], v[188:191], v[48:51]
	v_mfma_f32_16x16x32_bf16 v[36:39], v[172:175], v[210:213], v[36:39]
	v_mfma_f32_16x16x32_bf16 v[32:35], v[180:183], v[210:213], v[32:35]
	v_mfma_f32_16x16x32_bf16 v[20:23], v[172:175], v[218:221], v[20:23]
	v_mfma_f32_16x16x32_bf16 v[16:19], v[180:183], v[218:221], v[16:19]
	v_mfma_f32_16x16x32_bf16 v[4:7], v[172:175], v[226:229], v[4:7]
	v_mfma_f32_16x16x32_bf16 v[0:3], v[180:183], v[226:229], v[0:3]
	s_setprio 0
	s_barrier
	s_add_i32 s36, 0, 0x18000
	s_add_i32 s37, 0, 0x1c000
	v_add_u32_e32 v164, s36, v141
	v_add_u32_e32 v180, s37, v141
	ds_read_b128 v[144:147], v164
	ds_read_b128 v[156:159], v164 offset:1024
	ds_read_b128 v[160:163], v164 offset:2048
	ds_read_b128 v[164:167], v164 offset:3072
	ds_read_b128 v[168:171], v180
	ds_read_b128 v[172:175], v180 offset:1024
	ds_read_b128 v[176:179], v180 offset:2048
	ds_read_b128 v[180:183], v180 offset:3072
	s_add_u32 s62, s62, 0x80000
	s_addc_u32 s63, s63, 0
	s_mov_b32 m0, s25
	v_lshl_add_u64 v[232:233], s[62:63], 0, v[132:133]
	ds_read_b128 v[184:187], v143 offset:32768
	ds_read_b128 v[188:191], v143 offset:33792
	ds_read_b128 v[206:209], v143 offset:34816
	ds_read_b128 v[210:213], v143 offset:35840
	ds_read_b128 v[214:217], v143 offset:36864
	ds_read_b128 v[218:221], v143 offset:37888
	ds_read_b128 v[222:225], v143 offset:38912
	ds_read_b128 v[226:229], v143 offset:39936
	global_load_lds_dwordx4 v[232:233], off
	v_lshl_add_u64 v[232:233], s[62:63], 0, v[130:131]
	s_mov_b32 m0, s57
	s_nop 0
	global_load_lds_dwordx4 v[232:233], off
	s_waitcnt vmcnt(8)
	s_waitcnt lgkmcnt(0)
	s_barrier
; #define PG8_STAGE(bufoff, gbase, voff) do { _Pragma("unroll") for (int _i = 0; _i < 2; ++_i) \
;         __builtin_amdgcn_global_load_lds((const unsigned*)((const char*)(gbase) + (voff)[_i]), (PG8_LAS unsigned*)(lds + (bufoff) + ldsw + _i * 8192), 16, 0, 0); } while (0)
; #define PG8_LDA(dst, b, h) do { _Pragma("unroll") for (int m = 0; m < 4; ++m) _Pragma("unroll") for (int k = 0; k < 2; ++k) dst[m][k] = *(const PG8_LAS bf16x8*)(lds + PG8_SA(b, h) + aoff + m * 2048 + k * 1024); } while (0)
; #define PG8_MMA(ai, bj, At, Bt) do { __builtin_amdgcn_s_setprio(1); _Pragma("unroll") for (int m = 0; m < 4; ++m) _Pragma("unroll") for (int n = 0; n < 2; ++n) _Pragma("unroll") for (int k = 0; k < 2; ++k) \
;         acc[ai][bj][m][n] = __builtin_amdgcn_mfma_f32_16x16x32_bf16(Bt[n][k], At[m][k], acc[ai][bj][m][n], 0, 0, 0); __builtin_amdgcn_s_setprio(0); } while (0)
; #define PG8_WAIT_V(n) asm volatile("s_waitcnt vmcnt(" #n ")" ::: "memory")
; #define PG8_WAIT_L(n) asm volatile("s_waitcnt lgkmcnt(" #n ")" ::: "memory")
; #define PG8_BAR __builtin_amdgcn_s_barrier()
; #define PG8_SCHED __builtin_amdgcn_sched_barrier(0)
; template <class Epi, class Sched, bool ALIGN_EPI = false, bool SP2 = false>
; __device__ __forceinline__ void gemm_phase(PG8_LAS unsigned char* lds, const Gemm g, const Sched& S, const Epi& E, int wave_s) {
;     ...
;         for (int t = 0; t < nt; t += 2) {
;             const bool last = (t == nt - 2);
;             const char* a1 = cA + (size_t)(t + 1) * kstep;
;             const char* a2 = last ? nA : cA + (size_t)(t + 2) * kstep; const char* b2 = last ? nB : cB + (size_t)(t + 2) * kstep;
;             const char* a3 = a2 + kstep; const char* b3 = b2 + kstep;
;             if (last && has_next) S.a_ready(nxt);
;     ...
;             PG8_WAIT_V(8); PG8_WAIT_L(0); PG8_BAR; PG8_MMA(0, 0, At, B0); PG8_MMA(0, 1, At, B1); PG8_BAR; PG8_SCHED;
;             PG8_LDA(At, 1, 1); PG8_STAGE(PG8_SB(1, 0), b3, voffB); PG8_STAGE(PG8_SB(1, 1), b3 + hstep, voffB); PG8_STAGE(PG8_SA(1, 0), a3, voffA);
;             PG8_WAIT_V(8); PG8_WAIT_L(0); PG8_BAR; PG8_MMA(1, 0, At, B0); PG8_MMA(1, 1, At, B1); PG8_BAR; PG8_SCHED;
	s_setprio 1
	s_waitcnt lgkmcnt(0)
	v_mfma_f32_16x16x32_bf16 v[124:127], v[144:147], v[184:187], v[124:127]
	v_mfma_f32_16x16x32_bf16 v[120:123], v[160:163], v[184:187], v[120:123]
	v_mfma_f32_16x16x32_bf16 v[108:111], v[144:147], v[206:209], v[108:111]
	v_mfma_f32_16x16x32_bf16 v[104:107], v[160:163], v[206:209], v[104:107]
	v_mfma_f32_16x16x32_bf16 v[92:95], v[144:147], v[214:217], v[92:95]
	v_mfma_f32_16x16x32_bf16 v[88:91], v[160:163], v[214:217], v[88:91]
	v_mfma_f32_16x16x32_bf16 v[76:79], v[144:147], v[222:225], v[76:79]
	v_mfma_f32_16x16x32_bf16 v[72:75], v[160:163], v[222:225], v[72:75]
	v_mfma_f32_16x16x32_bf16 v[124:127], v[156:159], v[188:191], v[124:127]
	v_mfma_f32_16x16x32_bf16 v[120:123], v[164:167], v[188:191], v[120:123]
	v_mfma_f32_16x16x32_bf16 v[108:111], v[156:159], v[210:213], v[108:111]
	v_mfma_f32_16x16x32_bf16 v[104:107], v[164:167], v[210:213], v[104:107]
	v_mfma_f32_16x16x32_bf16 v[92:95], v[156:159], v[218:221], v[92:95]
	v_mfma_f32_16x16x32_bf16 v[88:91], v[164:167], v[218:221], v[88:91]
	v_mfma_f32_16x16x32_bf16 v[76:79], v[156:159], v[226:229], v[76:79]
	v_mfma_f32_16x16x32_bf16 v[72:75], v[164:167], v[226:229], v[72:75]
	s_setprio 0
	s_setprio 1
	v_mfma_f32_16x16x32_bf16 v[116:119], v[168:171], v[184:187], v[116:119]
	v_mfma_f32_16x16x32_bf16 v[112:115], v[176:179], v[184:187], v[112:115]
	v_mfma_f32_16x16x32_bf16 v[100:103], v[168:171], v[206:209], v[100:103]
	v_mfma_f32_16x16x32_bf16 v[96:99], v[176:179], v[206:209], v[96:99]
	v_mfma_f32_16x16x32_bf16 v[84:87], v[168:171], v[214:217], v[84:87]
	v_mfma_f32_16x16x32_bf16 v[80:83], v[176:179], v[214:217], v[80:83]
	v_mfma_f32_16x16x32_bf16 v[68:71], v[168:171], v[222:225], v[68:71]
	v_mfma_f32_16x16x32_bf16 v[64:67], v[176:179], v[222:225], v[64:67]
	v_mfma_f32_16x16x32_bf16 v[116:119], v[172:175], v[188:191], v[116:119]
	v_mfma_f32_16x16x32_bf16 v[112:115], v[180:183], v[188:191], v[112:115]
	v_mfma_f32_16x16x32_bf16 v[100:103], v[172:175], v[210:213], v[100:103]
	v_mfma_f32_16x16x32_bf16 v[96:99], v[180:183], v[210:213], v[96:99]
	v_mfma_f32_16x16x32_bf16 v[84:87], v[172:175], v[218:221], v[84:87]
	v_mfma_f32_16x16x32_bf16 v[80:83], v[180:183], v[218:221], v[80:83]
	v_mfma_f32_16x16x32_bf16 v[68:71], v[172:175], v[226:229], v[68:71]
	v_mfma_f32_16x16x32_bf16 v[64:67], v[180:183], v[226:229], v[64:67]
	s_setprio 0
	s_barrier
	s_add_i32 s36, s36, s18
	v_lshl_add_u64 v[138:139], v[138:139], 0, s[34:35]
	s_mov_b32 m0, s36
	ds_read_b128 v[184:187], v143 offset:49152
	ds_read_b128 v[188:191], v143 offset:50176
	ds_read_b128 v[206:209], v143 offset:51200
	ds_read_b128 v[210:213], v143 offset:52224
	ds_read_b128 v[214:217], v143 offset:53248
	ds_read_b128 v[218:221], v143 offset:54272
	ds_read_b128 v[222:225], v143 offset:55296
	ds_read_b128 v[226:229], v143 offset:56320
	global_load_lds_dwordx4 v[138:139], off
	s_add_i32 m0, s36, 0x2000
	s_add_u32 s60, s60, 0x80080
	v_lshl_add_u64 v[138:139], v[150:151], 0, s[34:35]
	s_addc_u32 s61, s61, 0
	s_add_i32 s36, s37, s18
	global_load_lds_dwordx4 v[138:139], off
	v_lshl_add_u64 v[138:139], s[60:61], 0, v[148:149]
	s_mov_b32 m0, s36
	s_nop 0
	global_load_lds_dwordx4 v[138:139], off
	v_lshl_add_u64 v[138:139], s[60:61], 0, v[128:129]
	s_add_i32 m0, s36, 0x2000
	s_nop 0
	global_load_lds_dwordx4 v[138:139], off
	v_lshl_add_u64 v[138:139], v[152:153], 0, s[34:35]
	s_mov_b32 m0, s38
	s_nop 0
	global_load_lds_dwordx4 v[138:139], off
	v_lshl_add_u64 v[138:139], v[230:231], 0, s[34:35]
	s_mov_b32 m0, s39
	s_nop 0
	global_load_lds_dwordx4 v[138:139], off
	s_waitcnt vmcnt(8)
	s_waitcnt lgkmcnt(0)
	s_barrier
	s_setprio 1
	s_waitcnt lgkmcnt(0)
	v_mfma_f32_16x16x32_bf16 v[60:63], v[144:147], v[184:187], v[60:63]
	s_add_i32 s49, s49, 2
	v_mfma_f32_16x16x32_bf16 v[56:59], v[160:163], v[184:187], v[56:59]
	s_add_u32 s58, s58, 0x100
	v_mfma_f32_16x16x32_bf16 v[44:47], v[144:147], v[206:209], v[44:47]
	s_addc_u32 s59, s59, 0
	v_mfma_f32_16x16x32_bf16 v[40:43], v[160:163], v[206:209], v[40:43]
	s_add_u32 s29, s29, 0x100
	v_mfma_f32_16x16x32_bf16 v[28:31], v[144:147], v[214:217], v[28:31]
	s_addc_u32 s47, s47, 0
	v_mfma_f32_16x16x32_bf16 v[24:27], v[160:163], v[214:217], v[24:27]
	s_add_u32 s36, s58, 0xfff80080
	v_mfma_f32_16x16x32_bf16 v[12:15], v[144:147], v[222:225], v[12:15]
	s_addc_u32 s37, s59, -1
	v_mfma_f32_16x16x32_bf16 v[8:11], v[160:163], v[222:225], v[8:11]
	s_add_i32 s66, 0, 0x10000
	v_mfma_f32_16x16x32_bf16 v[60:63], v[156:159], v[188:191], v[60:63]
	s_cmp_eq_u32 s49, 28
	v_mfma_f32_16x16x32_bf16 v[56:59], v[164:167], v[188:191], v[56:59]
	s_cselect_b32 s63, s22, s37
	v_mfma_f32_16x16x32_bf16 v[44:47], v[156:159], v[210:213], v[44:47]
	s_cselect_b32 s62, s23, s36
	v_mfma_f32_16x16x32_bf16 v[40:43], v[164:167], v[210:213], v[40:43]
	s_cselect_b32 s61, s5, s47
	v_mfma_f32_16x16x32_bf16 v[28:31], v[156:159], v[218:221], v[28:31]
	s_cselect_b32 s60, s28, s29
	v_mfma_f32_16x16x32_bf16 v[24:27], v[164:167], v[218:221], v[24:27]
	s_add_i32 s36, 0, 0x14000
	v_mfma_f32_16x16x32_bf16 v[12:15], v[156:159], v[226:229], v[12:15]
	v_mfma_f32_16x16x32_bf16 v[8:11], v[164:167], v[226:229], v[8:11]
	s_setprio 0
	s_setprio 1
	v_mfma_f32_16x16x32_bf16 v[52:55], v[168:171], v[184:187], v[52:55]
	v_mfma_f32_16x16x32_bf16 v[48:51], v[176:179], v[184:187], v[48:51]
	v_mfma_f32_16x16x32_bf16 v[36:39], v[168:171], v[206:209], v[36:39]
	v_mfma_f32_16x16x32_bf16 v[32:35], v[176:179], v[206:209], v[32:35]
	v_mfma_f32_16x16x32_bf16 v[20:23], v[168:171], v[214:217], v[20:23]
	v_mfma_f32_16x16x32_bf16 v[16:19], v[176:179], v[214:217], v[16:19]
	v_mfma_f32_16x16x32_bf16 v[4:7], v[168:171], v[222:225], v[4:7]
	v_mfma_f32_16x16x32_bf16 v[0:3], v[176:179], v[222:225], v[0:3]
	v_mfma_f32_16x16x32_bf16 v[52:55], v[172:175], v[188:191], v[52:55]
	v_mfma_f32_16x16x32_bf16 v[48:51], v[180:183], v[188:191], v[48:51]
	v_mfma_f32_16x16x32_bf16 v[36:39], v[172:175], v[210:213], v[36:39]
	v_mfma_f32_16x16x32_bf16 v[32:35], v[180:183], v[210:213], v[32:35]
	v_mfma_f32_16x16x32_bf16 v[20:23], v[172:175], v[218:221], v[20:23]
	v_mfma_f32_16x16x32_bf16 v[16:19], v[180:183], v[218:221], v[16:19]
	v_mfma_f32_16x16x32_bf16 v[4:7], v[172:175], v[226:229], v[4:7]
	v_mfma_f32_16x16x32_bf16 v[0:3], v[180:183], v[226:229], v[0:3]
	s_setprio 0
	s_barrier
	s_cmp_gt_u32 s49, 29
	s_cbranch_scc0 .LBB0_453
	s_and_b64 vcc, exec, s[44:45]
	s_cbranch_vccz .LBB0_456
	s_barrier

; #define PG8_STAGE(bufoff, gbase, voff) do { _Pragma("unroll") for (int _i = 0; _i < 2; ++_i) \
;         __builtin_amdgcn_global_load_lds((const unsigned*)((const char*)(gbase) + (voff)[_i]), (PG8_LAS unsigned*)(lds + (bufoff) + ldsw + _i * 8192), 16, 0, 0); } while (0)
; #define PG8_LDA(dst, b, h) do { _Pragma("unroll") for (int m = 0; m < 4; ++m) _Pragma("unroll") for (int k = 0; k < 2; ++k) dst[m][k] = *(const PG8_LAS bf16x8*)(lds + PG8_SA(b, h) + aoff + m * 2048 + k * 1024); } while (0)
; #define PG8_LDB(dst, b, h) do { _Pragma("unroll") for (int n = 0; n < 2; ++n) _Pragma("unroll") for (int k = 0; k < 2; ++k) dst[n][k] = *(const PG8_LAS bf16x8*)(lds + PG8_SB(b, h) + boff + n * 2048 + k * 1024); } while (0)
; #define PG8_WAIT_V(n) asm volatile("s_waitcnt vmcnt(" #n ")" ::: "memory")
; #define PG8_WAIT_L(n) asm volatile("s_waitcnt lgkmcnt(" #n ")" ::: "memory")
; template <class Epi, class Sched, bool ALIGN_EPI = false, bool SP2 = false>
; __device__ __forceinline__ void gemm_phase(PG8_LAS unsigned char* lds, const Gemm g, const Sched& S, const Epi& E, int wave_s) {
;     ...
;         const bool has_next = S.next(ui + 1, nxt);
;         const char* nA = has_next ? (const char*)g.A + (size_t)nxt.pm * tstep : cA; const char* nB = has_next ? (const char*)g.Bt + (size_t)nxt.pn * tstep : cB;
;         for (int t = 0; t < nt; t += 2) {
;             const bool last = (t == nt - 2);
;             const char* a1 = cA + (size_t)(t + 1) * kstep;
;             const char* a2 = last ? nA : cA + (size_t)(t + 2) * kstep; const char* b2 = last ? nB : cB + (size_t)(t + 2) * kstep;
;             const char* a3 = a2 + kstep; const char* b3 = b2 + kstep;
;             if (last && has_next) S.a_ready(nxt);
;             if constexpr (SP2) {
;             PG8_LDB(B0, 0, 0); PG8_LDB(B1, 0, 1); PG8_SCHED; PG8_LDA(At, 0, 0); PG8_STAGE(PG8_SA(1, 1), a1 + hstep, voffA);
;             PG8_WAIT_V(8); PG8_WAIT_L(0); PG8_BAR; PG8_MMA(0, 0, At, B0); PG8_MMA(0, 1, At, B1); PG8_BAR; PG8_SCHED;
;     ...
;         { float zf_ = 0.f; asm volatile("" : "+v"(zf_)); const f32x4 zero4_ = {zf_, zf_, zf_, zf_};
; #pragma unroll
;         for (int a = 0; a < 2; ++a)
; #pragma unroll
;             for (int b = 0; b < 2; ++b)
; #pragma unroll
;                 for (int m = 0; m < 4; ++m)
; #pragma unroll
;                     for (int n = 0; n < 2; ++n) acc[a][b][m][n] = zero4_; }
.LBB0_468:
	s_ashr_i32 s53, s52, 31
	s_lshl_b64 s[22:23], s[52:53], 20
	s_add_u32 s54, s19, s22
	s_addc_u32 s55, s24, s23
	s_and_b64 s[22:23], s[40:41], exec
	s_cselect_b32 s22, s55, s61
	s_cselect_b32 s23, s54, s60
	s_ashr_i32 s49, s48, 31
	s_lshl_b64 s[56:57], s[48:49], 20
	s_add_u32 s56, s9, s56
	s_addc_u32 s57, s11, s57
	s_and_b64 s[64:65], s[40:41], exec
	s_cselect_b32 s5, s57, s63
	s_cselect_b32 s29, s56, s62
	s_add_u32 s60, s60, 0x80080
	s_addc_u32 s61, s61, 0
	s_add_u32 s49, s62, 0x100
	v_mov_b64_e32 v[6:7], v[2:3]
	v_mov_b64_e32 v[18:19], v[2:3]
	v_mov_b64_e32 v[22:23], v[2:3]
	v_mov_b64_e32 v[34:35], v[2:3]
	v_mov_b64_e32 v[38:39], v[2:3]
	v_mov_b64_e32 v[50:51], v[2:3]
	v_mov_b64_e32 v[54:55], v[2:3]
	v_mov_b64_e32 v[10:11], v[2:3]
	v_mov_b64_e32 v[14:15], v[2:3]
	v_mov_b64_e32 v[26:27], v[2:3]
	v_mov_b64_e32 v[30:31], v[2:3]
	v_mov_b64_e32 v[42:43], v[2:3]
	v_mov_b64_e32 v[46:47], v[2:3]
	v_mov_b64_e32 v[58:59], v[2:3]
	v_mov_b64_e32 v[62:63], v[2:3]
	v_mov_b64_e32 v[66:67], v[2:3]
	v_mov_b64_e32 v[70:71], v[2:3]
	v_mov_b64_e32 v[82:83], v[2:3]
	v_mov_b64_e32 v[86:87], v[2:3]
	v_mov_b64_e32 v[98:99], v[2:3]
	v_mov_b64_e32 v[102:103], v[2:3]
	v_mov_b64_e32 v[114:115], v[2:3]
	v_mov_b64_e32 v[118:119], v[2:3]
	v_mov_b64_e32 v[74:75], v[2:3]
	v_mov_b64_e32 v[78:79], v[2:3]
	v_mov_b64_e32 v[90:91], v[2:3]
	v_mov_b64_e32 v[94:95], v[2:3]
	v_mov_b64_e32 v[106:107], v[2:3]
	v_mov_b64_e32 v[110:111], v[2:3]
	v_mov_b64_e32 v[122:123], v[2:3]
	v_mov_b64_e32 v[126:127], v[2:3]
	s_addc_u32 s53, s63, 0
	s_mov_b32 s78, -2
	v_mov_b64_e32 v[4:5], v[0:1]
	v_mov_b64_e32 v[16:17], v[0:1]
	v_mov_b64_e32 v[20:21], v[0:1]
	v_mov_b64_e32 v[32:33], v[0:1]
	v_mov_b64_e32 v[36:37], v[0:1]
	v_mov_b64_e32 v[48:49], v[0:1]
	v_mov_b64_e32 v[52:53], v[0:1]
	v_mov_b64_e32 v[8:9], v[0:1]
	v_mov_b64_e32 v[12:13], v[0:1]
	v_mov_b64_e32 v[24:25], v[0:1]
	v_mov_b64_e32 v[28:29], v[0:1]
	v_mov_b64_e32 v[40:41], v[0:1]
	v_mov_b64_e32 v[44:45], v[0:1]
	v_mov_b64_e32 v[56:57], v[0:1]
	v_mov_b64_e32 v[60:61], v[0:1]
	v_mov_b64_e32 v[64:65], v[0:1]
	v_mov_b64_e32 v[68:69], v[0:1]
	v_mov_b64_e32 v[80:81], v[0:1]
	v_mov_b64_e32 v[84:85], v[0:1]
	v_mov_b64_e32 v[96:97], v[0:1]
	v_mov_b64_e32 v[100:101], v[0:1]
	v_mov_b64_e32 v[112:113], v[0:1]
	v_mov_b64_e32 v[116:117], v[0:1]
	v_mov_b64_e32 v[72:73], v[0:1]
	v_mov_b64_e32 v[76:77], v[0:1]
	v_mov_b64_e32 v[88:89], v[0:1]
	v_mov_b64_e32 v[92:93], v[0:1]
	v_mov_b64_e32 v[104:105], v[0:1]
	v_mov_b64_e32 v[108:109], v[0:1]
	v_mov_b64_e32 v[120:121], v[0:1]
	v_mov_b64_e32 v[124:125], v[0:1]
	s_add_u32 s36, s60, 0xfff80080
	s_addc_u32 s37, s61, -1
	s_add_i32 s79, 0, 0x10000
	s_cmp_eq_u32 s78, 28
	s_cselect_b32 s65, s22, s37
	s_cselect_b32 s64, s23, s36
	s_cselect_b32 s63, s5, s53
	s_cselect_b32 s62, s29, s49
	s_add_i32 s36, 0, 0x14000
.LBB0_469:
	v_add_u32_e32 v138, s79, v141
	ds_read_b128 v[144:147], v138
	ds_read_b128 v[156:159], v138 offset:1024
	ds_read_b128 v[160:163], v138 offset:2048
	ds_read_b128 v[164:167], v138 offset:3072
	v_add_u32_e32 v138, s36, v141
	ds_read_b128 v[168:171], v138
	ds_read_b128 v[172:175], v138 offset:1024
	ds_read_b128 v[176:179], v138 offset:2048
	ds_read_b128 v[180:183], v138 offset:3072
	v_lshl_add_u64 v[138:139], s[60:61], 0, v[134:135]
	s_add_i32 m0, s38, 0xc000
	ds_read_b128 v[184:187], v143
	ds_read_b128 v[188:191], v143 offset:1024
	ds_read_b128 v[206:209], v143 offset:2048
	ds_read_b128 v[210:213], v143 offset:3072
	ds_read_b128 v[214:217], v143 offset:4096
	ds_read_b128 v[218:221], v143 offset:5120
	ds_read_b128 v[222:225], v143 offset:6144
	ds_read_b128 v[226:229], v143 offset:7168
	global_load_lds_dwordx4 v[138:139], off
	v_lshl_add_u64 v[138:139], s[60:61], 0, v[136:137]
	s_add_i32 m0, s38, 0xe000
	s_nop 0
	global_load_lds_dwordx4 v[138:139], off
	s_waitcnt vmcnt(8)
	s_waitcnt lgkmcnt(0)
	s_barrier
	s_setprio 1
	s_waitcnt lgkmcnt(0)
	v_mfma_f32_16x16x32_bf16 v[124:127], v[144:147], v[184:187], v[124:127]
	v_mfma_f32_16x16x32_bf16 v[120:123], v[160:163], v[184:187], v[120:123]
	v_mfma_f32_16x16x32_bf16 v[108:111], v[144:147], v[206:209], v[108:111]
	v_mfma_f32_16x16x32_bf16 v[104:107], v[160:163], v[206:209], v[104:107]
	v_mfma_f32_16x16x32_bf16 v[92:95], v[144:147], v[214:217], v[92:95]
	v_mfma_f32_16x16x32_bf16 v[88:91], v[160:163], v[214:217], v[88:91]
	v_mfma_f32_16x16x32_bf16 v[76:79], v[144:147], v[222:225], v[76:79]
	v_mfma_f32_16x16x32_bf16 v[72:75], v[160:163], v[222:225], v[72:75]
	v_mfma_f32_16x16x32_bf16 v[124:127], v[156:159], v[188:191], v[124:127]
	v_mfma_f32_16x16x32_bf16 v[120:123], v[164:167], v[188:191], v[120:123]
	v_mfma_f32_16x16x32_bf16 v[108:111], v[156:159], v[210:213], v[108:111]
	v_mfma_f32_16x16x32_bf16 v[104:107], v[164:167], v[210:213], v[104:107]
	v_mfma_f32_16x16x32_bf16 v[92:95], v[156:159], v[218:221], v[92:95]
	v_mfma_f32_16x16x32_bf16 v[88:91], v[164:167], v[218:221], v[88:91]
	v_mfma_f32_16x16x32_bf16 v[76:79], v[156:159], v[226:229], v[76:79]
	v_mfma_f32_16x16x32_bf16 v[72:75], v[164:167], v[226:229], v[72:75]
	s_setprio 0
	s_setprio 1
	v_mfma_f32_16x16x32_bf16 v[116:119], v[168:171], v[184:187], v[116:119]
	v_mfma_f32_16x16x32_bf16 v[112:115], v[176:179], v[184:187], v[112:115]
	v_mfma_f32_16x16x32_bf16 v[100:103], v[168:171], v[206:209], v[100:103]
	v_mfma_f32_16x16x32_bf16 v[96:99], v[176:179], v[206:209], v[96:99]
	v_mfma_f32_16x16x32_bf16 v[84:87], v[168:171], v[214:217], v[84:87]
	v_mfma_f32_16x16x32_bf16 v[80:83], v[176:179], v[214:217], v[80:83]
	v_mfma_f32_16x16x32_bf16 v[68:71], v[168:171], v[222:225], v[68:71]
	v_mfma_f32_16x16x32_bf16 v[64:67], v[176:179], v[222:225], v[64:67]
	v_mfma_f32_16x16x32_bf16 v[116:119], v[172:175], v[188:191], v[116:119]
	v_mfma_f32_16x16x32_bf16 v[112:115], v[180:183], v[188:191], v[112:115]
	v_mfma_f32_16x16x32_bf16 v[100:103], v[172:175], v[210:213], v[100:103]
	v_mfma_f32_16x16x32_bf16 v[96:99], v[180:183], v[210:213], v[96:99]
	v_mfma_f32_16x16x32_bf16 v[84:87], v[172:175], v[218:221], v[84:87]
	v_mfma_f32_16x16x32_bf16 v[80:83], v[180:183], v[218:221], v[80:83]
	v_mfma_f32_16x16x32_bf16 v[68:71], v[172:175], v[226:229], v[68:71]
	v_mfma_f32_16x16x32_bf16 v[64:67], v[180:183], v[226:229], v[64:67]
	s_setprio 0
	s_barrier
; #define PG8_STAGE(bufoff, gbase, voff) do { _Pragma("unroll") for (int _i = 0; _i < 2; ++_i) \
;         __builtin_amdgcn_global_load_lds((const unsigned*)((const char*)(gbase) + (voff)[_i]), (PG8_LAS unsigned*)(lds + (bufoff) + ldsw + _i * 8192), 16, 0, 0); } while (0)
; #define PG8_LDA(dst, b, h) do { _Pragma("unroll") for (int m = 0; m < 4; ++m) _Pragma("unroll") for (int k = 0; k < 2; ++k) dst[m][k] = *(const PG8_LAS bf16x8*)(lds + PG8_SA(b, h) + aoff + m * 2048 + k * 1024); } while (0)
; #define PG8_LDB(dst, b, h) do { _Pragma("unroll") for (int n = 0; n < 2; ++n) _Pragma("unroll") for (int k = 0; k < 2; ++k) dst[n][k] = *(const PG8_LAS bf16x8*)(lds + PG8_SB(b, h) + boff + n * 2048 + k * 1024); } while (0)
; #define PG8_MMA(ai, bj, At, Bt) do { __builtin_amdgcn_s_setprio(1); _Pragma("unroll") for (int m = 0; m < 4; ++m) _Pragma("unroll") for (int n = 0; n < 2; ++n) _Pragma("unroll") for (int k = 0; k < 2; ++k) \
;         acc[ai][bj][m][n] = __builtin_amdgcn_mfma_f32_16x16x32_bf16(Bt[n][k], At[m][k], acc[ai][bj][m][n], 0, 0, 0); __builtin_amdgcn_s_setprio(0); } while (0)
; #define PG8_WAIT_V(n) asm volatile("s_waitcnt vmcnt(" #n ")" ::: "memory")
; #define PG8_WAIT_L(n) asm volatile("s_waitcnt lgkmcnt(" #n ")" ::: "memory")
; #define PG8_BAR __builtin_amdgcn_s_barrier()
; #define PG8_SCHED __builtin_amdgcn_sched_barrier(0)
; template <class Epi, class Sched, bool ALIGN_EPI = false, bool SP2 = false>
; __device__ __forceinline__ void gemm_phase(PG8_LAS unsigned char* lds, const Gemm g, const Sched& S, const Epi& E, int wave_s) {
;     ...
;             PG8_LDA(At, 0, 1); PG8_STAGE(PG8_SB(0, 0), b2, voffB); PG8_STAGE(PG8_SB(0, 1), b2 + hstep, voffB); PG8_STAGE(PG8_SA(0, 0), a2, voffA);
;             PG8_WAIT_V(8); PG8_WAIT_L(0); PG8_BAR; PG8_MMA(1, 0, At, B0); PG8_MMA(1, 1, At, B1); PG8_BAR; PG8_SCHED;
;             PG8_LDB(B0, 1, 0); PG8_LDB(B1, 1, 1); PG8_SCHED; PG8_LDA(At, 1, 0); PG8_STAGE(PG8_SA(0, 1), a2 + hstep, voffA);
;             PG8_WAIT_V(8); PG8_WAIT_L(0); PG8_BAR; PG8_MMA(0, 0, At, B0); PG8_MMA(0, 1, At, B1); PG8_BAR; PG8_SCHED;
	s_add_i32 s37, s79, s25
	v_lshl_add_u64 v[138:139], s[62:63], 0, v[148:149]
	s_mov_b32 m0, s37
	ds_read_b128 v[184:187], v143 offset:16384
	ds_read_b128 v[188:191], v143 offset:17408
	ds_read_b128 v[206:209], v143 offset:18432
	ds_read_b128 v[210:213], v143 offset:19456
	ds_read_b128 v[214:217], v143 offset:20480
	ds_read_b128 v[218:221], v143 offset:21504
	ds_read_b128 v[222:225], v143 offset:22528
	ds_read_b128 v[226:229], v143 offset:23552
	global_load_lds_dwordx4 v[138:139], off
	s_add_i32 m0, s37, 0x2000
	s_add_u32 s84, s62, 0x80000
	v_lshl_add_u64 v[150:151], s[62:63], 0, v[128:129]
	s_addc_u32 s85, s63, 0
	s_add_i32 s36, s36, s25
	global_load_lds_dwordx4 v[150:151], off
	v_lshl_add_u64 v[152:153], s[84:85], 0, v[148:149]
	s_mov_b32 m0, s36
	v_lshl_add_u64 v[230:231], s[64:65], 0, v[130:131]
	global_load_lds_dwordx4 v[152:153], off
	v_lshl_add_u64 v[152:153], s[84:85], 0, v[128:129]
	s_add_i32 m0, s36, 0x2000
	s_nop 0
	global_load_lds_dwordx4 v[152:153], off
	v_lshl_add_u64 v[152:153], s[64:65], 0, v[132:133]
	s_mov_b32 m0, s38
	s_nop 0
	global_load_lds_dwordx4 v[152:153], off
	s_mov_b32 m0, s39
	s_nop 0
	global_load_lds_dwordx4 v[230:231], off
	s_waitcnt vmcnt(8)
	s_waitcnt lgkmcnt(0)
	s_barrier
	s_setprio 1
	s_waitcnt lgkmcnt(0)
	v_mfma_f32_16x16x32_bf16 v[60:63], v[144:147], v[184:187], v[60:63]
	v_mfma_f32_16x16x32_bf16 v[56:59], v[160:163], v[184:187], v[56:59]
	v_mfma_f32_16x16x32_bf16 v[44:47], v[144:147], v[206:209], v[44:47]
	v_mfma_f32_16x16x32_bf16 v[40:43], v[160:163], v[206:209], v[40:43]
	v_mfma_f32_16x16x32_bf16 v[28:31], v[144:147], v[214:217], v[28:31]
	v_mfma_f32_16x16x32_bf16 v[24:27], v[160:163], v[214:217], v[24:27]
	v_mfma_f32_16x16x32_bf16 v[12:15], v[144:147], v[222:225], v[12:15]
	v_mfma_f32_16x16x32_bf16 v[8:11], v[160:163], v[222:225], v[8:11]
	v_mfma_f32_16x16x32_bf16 v[60:63], v[156:159], v[188:191], v[60:63]
	v_mfma_f32_16x16x32_bf16 v[56:59], v[164:167], v[188:191], v[56:59]
	v_mfma_f32_16x16x32_bf16 v[44:47], v[156:159], v[210:213], v[44:47]
	v_mfma_f32_16x16x32_bf16 v[40:43], v[164:167], v[210:213], v[40:43]
	v_mfma_f32_16x16x32_bf16 v[28:31], v[156:159], v[218:221], v[28:31]
	v_mfma_f32_16x16x32_bf16 v[24:27], v[164:167], v[218:221], v[24:27]
	v_mfma_f32_16x16x32_bf16 v[12:15], v[156:159], v[226:229], v[12:15]
	v_mfma_f32_16x16x32_bf16 v[8:11], v[164:167], v[226:229], v[8:11]
	s_setprio 0
	s_setprio 1
	v_mfma_f32_16x16x32_bf16 v[52:55], v[168:171], v[184:187], v[52:55]
	v_mfma_f32_16x16x32_bf16 v[48:51], v[176:179], v[184:187], v[48:51]
	v_mfma_f32_16x16x32_bf16 v[36:39], v[168:171], v[206:209], v[36:39]
	v_mfma_f32_16x16x32_bf16 v[32:35], v[176:179], v[206:209], v[32:35]
	v_mfma_f32_16x16x32_bf16 v[20:23], v[168:171], v[214:217], v[20:23]
	v_mfma_f32_16x16x32_bf16 v[16:19], v[176:179], v[214:217], v[16:19]
	v_mfma_f32_16x16x32_bf16 v[4:7], v[168:171], v[222:225], v[4:7]
	v_mfma_f32_16x16x32_bf16 v[0:3], v[176:179], v[222:225], v[0:3]
	v_mfma_f32_16x16x32_bf16 v[52:55], v[172:175], v[188:191], v[52:55]
	v_mfma_f32_16x16x32_bf16 v[48:51], v[180:183], v[188:191], v[48:51]
	v_mfma_f32_16x16x32_bf16 v[36:39], v[172:175], v[210:213], v[36:39]
	v_mfma_f32_16x16x32_bf16 v[32:35], v[180:183], v[210:213], v[32:35]
	v_mfma_f32_16x16x32_bf16 v[20:23], v[172:175], v[218:221], v[20:23]
	v_mfma_f32_16x16x32_bf16 v[16:19], v[180:183], v[218:221], v[16:19]
	v_mfma_f32_16x16x32_bf16 v[4:7], v[172:175], v[226:229], v[4:7]
	v_mfma_f32_16x16x32_bf16 v[0:3], v[180:183], v[226:229], v[0:3]
	s_setprio 0
	s_barrier
	s_add_i32 s36, 0, 0x18000
	s_add_i32 s37, 0, 0x1c000
	v_add_u32_e32 v164, s36, v141
	v_add_u32_e32 v180, s37, v141
	ds_read_b128 v[144:147], v164
	ds_read_b128 v[156:159], v164 offset:1024
	ds_read_b128 v[160:163], v164 offset:2048
	ds_read_b128 v[164:167], v164 offset:3072
	ds_read_b128 v[168:171], v180
	ds_read_b128 v[172:175], v180 offset:1024
	ds_read_b128 v[176:179], v180 offset:2048
	ds_read_b128 v[180:183], v180 offset:3072
	s_add_u32 s64, s64, 0x80000
	s_addc_u32 s65, s65, 0
	s_mov_b32 m0, s59
	v_lshl_add_u64 v[232:233], s[64:65], 0, v[132:133]
	ds_read_b128 v[184:187], v143 offset:32768
	ds_read_b128 v[188:191], v143 offset:33792
	ds_read_b128 v[206:209], v143 offset:34816
	ds_read_b128 v[210:213], v143 offset:35840
	ds_read_b128 v[214:217], v143 offset:36864
	ds_read_b128 v[218:221], v143 offset:37888
	ds_read_b128 v[222:225], v143 offset:38912
	ds_read_b128 v[226:229], v143 offset:39936
	global_load_lds_dwordx4 v[232:233], off
	v_lshl_add_u64 v[232:233], s[64:65], 0, v[130:131]
	s_mov_b32 m0, s67
	s_nop 0
	global_load_lds_dwordx4 v[232:233], off
	s_waitcnt vmcnt(8)
	s_waitcnt lgkmcnt(0)
	s_barrier
; #define PG8_STAGE(bufoff, gbase, voff) do { _Pragma("unroll") for (int _i = 0; _i < 2; ++_i) \
;         __builtin_amdgcn_global_load_lds((const unsigned*)((const char*)(gbase) + (voff)[_i]), (PG8_LAS unsigned*)(lds + (bufoff) + ldsw + _i * 8192), 16, 0, 0); } while (0)
; #define PG8_LDA(dst, b, h) do { _Pragma("unroll") for (int m = 0; m < 4; ++m) _Pragma("unroll") for (int k = 0; k < 2; ++k) dst[m][k] = *(const PG8_LAS bf16x8*)(lds + PG8_SA(b, h) + aoff + m * 2048 + k * 1024); } while (0)
; #define PG8_MMA(ai, bj, At, Bt) do { __builtin_amdgcn_s_setprio(1); _Pragma("unroll") for (int m = 0; m < 4; ++m) _Pragma("unroll") for (int n = 0; n < 2; ++n) _Pragma("unroll") for (int k = 0; k < 2; ++k) \
;         acc[ai][bj][m][n] = __builtin_amdgcn_mfma_f32_16x16x32_bf16(Bt[n][k], At[m][k], acc[ai][bj][m][n], 0, 0, 0); __builtin_amdgcn_s_setprio(0); } while (0)
; #define PG8_WAIT_V(n) asm volatile("s_waitcnt vmcnt(" #n ")" ::: "memory")
; #define PG8_WAIT_L(n) asm volatile("s_waitcnt lgkmcnt(" #n ")" ::: "memory")
; #define PG8_BAR __builtin_amdgcn_s_barrier()
; #define PG8_SCHED __builtin_amdgcn_sched_barrier(0)
; template <class Epi, class Sched, bool ALIGN_EPI = false, bool SP2 = false>
; __device__ __forceinline__ void gemm_phase(PG8_LAS unsigned char* lds, const Gemm g, const Sched& S, const Epi& E, int wave_s) {
;     ...
;         for (int t = 0; t < nt; t += 2) {
;             const bool last = (t == nt - 2);
;             const char* a1 = cA + (size_t)(t + 1) * kstep;
;             const char* a2 = last ? nA : cA + (size_t)(t + 2) * kstep; const char* b2 = last ? nB : cB + (size_t)(t + 2) * kstep;
;             const char* a3 = a2 + kstep; const char* b3 = b2 + kstep;
;             if (last && has_next) S.a_ready(nxt);
;     ...
;             PG8_WAIT_V(8); PG8_WAIT_L(0); PG8_BAR; PG8_MMA(0, 0, At, B0); PG8_MMA(0, 1, At, B1); PG8_BAR; PG8_SCHED;
;             PG8_LDA(At, 1, 1); PG8_STAGE(PG8_SB(1, 0), b3, voffB); PG8_STAGE(PG8_SB(1, 1), b3 + hstep, voffB); PG8_STAGE(PG8_SA(1, 0), a3, voffA);
;             PG8_WAIT_V(8); PG8_WAIT_L(0); PG8_BAR; PG8_MMA(1, 0, At, B0); PG8_MMA(1, 1, At, B1); PG8_BAR; PG8_SCHED;
	s_setprio 1
	s_waitcnt lgkmcnt(0)
	v_mfma_f32_16x16x32_bf16 v[124:127], v[144:147], v[184:187], v[124:127]
	v_mfma_f32_16x16x32_bf16 v[120:123], v[160:163], v[184:187], v[120:123]
	v_mfma_f32_16x16x32_bf16 v[108:111], v[144:147], v[206:209], v[108:111]
	v_mfma_f32_16x16x32_bf16 v[104:107], v[160:163], v[206:209], v[104:107]
	v_mfma_f32_16x16x32_bf16 v[92:95], v[144:147], v[214:217], v[92:95]
	v_mfma_f32_16x16x32_bf16 v[88:91], v[160:163], v[214:217], v[88:91]
	v_mfma_f32_16x16x32_bf16 v[76:79], v[144:147], v[222:225], v[76:79]
	v_mfma_f32_16x16x32_bf16 v[72:75], v[160:163], v[222:225], v[72:75]
	v_mfma_f32_16x16x32_bf16 v[124:127], v[156:159], v[188:191], v[124:127]
	v_mfma_f32_16x16x32_bf16 v[120:123], v[164:167], v[188:191], v[120:123]
	v_mfma_f32_16x16x32_bf16 v[108:111], v[156:159], v[210:213], v[108:111]
	v_mfma_f32_16x16x32_bf16 v[104:107], v[164:167], v[210:213], v[104:107]
	v_mfma_f32_16x16x32_bf16 v[92:95], v[156:159], v[218:221], v[92:95]
	v_mfma_f32_16x16x32_bf16 v[88:91], v[164:167], v[218:221], v[88:91]
	v_mfma_f32_16x16x32_bf16 v[76:79], v[156:159], v[226:229], v[76:79]
	v_mfma_f32_16x16x32_bf16 v[72:75], v[164:167], v[226:229], v[72:75]
	s_setprio 0
	s_setprio 1
	v_mfma_f32_16x16x32_bf16 v[116:119], v[168:171], v[184:187], v[116:119]
	v_mfma_f32_16x16x32_bf16 v[112:115], v[176:179], v[184:187], v[112:115]
	v_mfma_f32_16x16x32_bf16 v[100:103], v[168:171], v[206:209], v[100:103]
	v_mfma_f32_16x16x32_bf16 v[96:99], v[176:179], v[206:209], v[96:99]
	v_mfma_f32_16x16x32_bf16 v[84:87], v[168:171], v[214:217], v[84:87]
	v_mfma_f32_16x16x32_bf16 v[80:83], v[176:179], v[214:217], v[80:83]
	v_mfma_f32_16x16x32_bf16 v[68:71], v[168:171], v[222:225], v[68:71]
	v_mfma_f32_16x16x32_bf16 v[64:67], v[176:179], v[222:225], v[64:67]
	v_mfma_f32_16x16x32_bf16 v[116:119], v[172:175], v[188:191], v[116:119]
	v_mfma_f32_16x16x32_bf16 v[112:115], v[180:183], v[188:191], v[112:115]
	v_mfma_f32_16x16x32_bf16 v[100:103], v[172:175], v[210:213], v[100:103]
	v_mfma_f32_16x16x32_bf16 v[96:99], v[180:183], v[210:213], v[96:99]
	v_mfma_f32_16x16x32_bf16 v[84:87], v[172:175], v[218:221], v[84:87]
	v_mfma_f32_16x16x32_bf16 v[80:83], v[180:183], v[218:221], v[80:83]
	v_mfma_f32_16x16x32_bf16 v[68:71], v[172:175], v[226:229], v[68:71]
	v_mfma_f32_16x16x32_bf16 v[64:67], v[180:183], v[226:229], v[64:67]
	s_setprio 0
	s_barrier
	s_add_i32 s36, s36, s25
	v_lshl_add_u64 v[138:139], v[138:139], 0, s[34:35]
	s_mov_b32 m0, s36
	ds_read_b128 v[184:187], v143 offset:49152
	ds_read_b128 v[188:191], v143 offset:50176
	ds_read_b128 v[206:209], v143 offset:51200
	ds_read_b128 v[210:213], v143 offset:52224
	ds_read_b128 v[214:217], v143 offset:53248
	ds_read_b128 v[218:221], v143 offset:54272
	ds_read_b128 v[222:225], v143 offset:55296
	ds_read_b128 v[226:229], v143 offset:56320
	global_load_lds_dwordx4 v[138:139], off
	s_add_i32 m0, s36, 0x2000
	s_add_u32 s62, s62, 0x80080
	v_lshl_add_u64 v[138:139], v[150:151], 0, s[34:35]
	s_addc_u32 s63, s63, 0
	s_add_i32 s36, s37, s25
	global_load_lds_dwordx4 v[138:139], off
	v_lshl_add_u64 v[138:139], s[62:63], 0, v[148:149]
	s_mov_b32 m0, s36
	s_nop 0
	global_load_lds_dwordx4 v[138:139], off
	v_lshl_add_u64 v[138:139], s[62:63], 0, v[128:129]
	s_add_i32 m0, s36, 0x2000
	s_nop 0
	global_load_lds_dwordx4 v[138:139], off
	v_lshl_add_u64 v[138:139], v[152:153], 0, s[34:35]
	s_mov_b32 m0, s75
	s_nop 0
	global_load_lds_dwordx4 v[138:139], off
	v_lshl_add_u64 v[138:139], v[230:231], 0, s[34:35]
	s_mov_b32 m0, s76
	s_nop 0
	global_load_lds_dwordx4 v[138:139], off
	s_waitcnt vmcnt(8)
	s_waitcnt lgkmcnt(0)
	s_barrier
	s_setprio 1
	s_waitcnt lgkmcnt(0)
	v_mfma_f32_16x16x32_bf16 v[60:63], v[144:147], v[184:187], v[60:63]
	s_add_i32 s78, s78, 2
	v_mfma_f32_16x16x32_bf16 v[56:59], v[160:163], v[184:187], v[56:59]
	s_add_u32 s60, s60, 0x100
	v_mfma_f32_16x16x32_bf16 v[44:47], v[144:147], v[206:209], v[44:47]
	s_addc_u32 s61, s61, 0
	v_mfma_f32_16x16x32_bf16 v[40:43], v[160:163], v[206:209], v[40:43]
	s_add_u32 s49, s49, 0x100
	v_mfma_f32_16x16x32_bf16 v[28:31], v[144:147], v[214:217], v[28:31]
	s_addc_u32 s53, s53, 0
	v_mfma_f32_16x16x32_bf16 v[24:27], v[160:163], v[214:217], v[24:27]
	s_add_u32 s36, s60, 0xfff80080
	v_mfma_f32_16x16x32_bf16 v[12:15], v[144:147], v[222:225], v[12:15]
	s_addc_u32 s37, s61, -1
	v_mfma_f32_16x16x32_bf16 v[8:11], v[160:163], v[222:225], v[8:11]
	s_add_i32 s79, 0, 0x10000
	v_mfma_f32_16x16x32_bf16 v[60:63], v[156:159], v[188:191], v[60:63]
	s_cmp_eq_u32 s78, 28
	v_mfma_f32_16x16x32_bf16 v[56:59], v[164:167], v[188:191], v[56:59]
	s_cselect_b32 s65, s22, s37
	v_mfma_f32_16x16x32_bf16 v[44:47], v[156:159], v[210:213], v[44:47]
	s_cselect_b32 s64, s23, s36
	v_mfma_f32_16x16x32_bf16 v[40:43], v[164:167], v[210:213], v[40:43]
	s_cselect_b32 s63, s5, s53
	v_mfma_f32_16x16x32_bf16 v[28:31], v[156:159], v[218:221], v[28:31]
	s_cselect_b32 s62, s29, s49
	v_mfma_f32_16x16x32_bf16 v[24:27], v[164:167], v[218:221], v[24:27]
	s_add_i32 s36, 0, 0x14000
	v_mfma_f32_16x16x32_bf16 v[12:15], v[156:159], v[226:229], v[12:15]
	v_mfma_f32_16x16x32_bf16 v[8:11], v[164:167], v[226:229], v[8:11]
	s_setprio 0
	s_setprio 1
	v_mfma_f32_16x16x32_bf16 v[52:55], v[168:171], v[184:187], v[52:55]
	v_mfma_f32_16x16x32_bf16 v[48:51], v[176:179], v[184:187], v[48:51]
	v_mfma_f32_16x16x32_bf16 v[36:39], v[168:171], v[206:209], v[36:39]
	v_mfma_f32_16x16x32_bf16 v[32:35], v[176:179], v[206:209], v[32:35]
	v_mfma_f32_16x16x32_bf16 v[20:23], v[168:171], v[214:217], v[20:23]
	v_mfma_f32_16x16x32_bf16 v[16:19], v[176:179], v[214:217], v[16:19]
	v_mfma_f32_16x16x32_bf16 v[4:7], v[168:171], v[222:225], v[4:7]
	v_mfma_f32_16x16x32_bf16 v[0:3], v[176:179], v[222:225], v[0:3]
	v_mfma_f32_16x16x32_bf16 v[52:55], v[172:175], v[188:191], v[52:55]
	v_mfma_f32_16x16x32_bf16 v[48:51], v[180:183], v[188:191], v[48:51]
	v_mfma_f32_16x16x32_bf16 v[36:39], v[172:175], v[210:213], v[36:39]
	v_mfma_f32_16x16x32_bf16 v[32:35], v[180:183], v[210:213], v[32:35]
	v_mfma_f32_16x16x32_bf16 v[20:23], v[172:175], v[218:221], v[20:23]
	v_mfma_f32_16x16x32_bf16 v[16:19], v[180:183], v[218:221], v[16:19]
	v_mfma_f32_16x16x32_bf16 v[4:7], v[172:175], v[226:229], v[4:7]
	v_mfma_f32_16x16x32_bf16 v[0:3], v[180:183], v[226:229], v[0:3]
	s_setprio 0
	s_barrier
	s_cmp_gt_u32 s78, 29
	s_cbranch_scc0 .LBB0_469
	s_and_b64 vcc, exec, s[46:47]
	s_cbranch_vccz .LBB0_472
	s_barrier
